# RWKV scan: producer staging trimmed (rsq, row_bcast sums, loads one chunk ahead) and consumer re-laid out to 2 rows x 4 columns per lane (half the LDS reads)
# speedup vs baseline: 1.1587x; 1.0046x over previous
.LBB0_1746:
	s_and_b64 vcc, exec, s[6:7]
	s_cbranch_vccz .LBB0_1797
	v_readlane_b32 s4, v254, 37
	v_readlane_b32 s7, v254, 40
	s_cmp_lt_u32 s7, 2
	v_readlane_b32 s5, v254, 38
	v_readlane_b32 s6, v254, 39
	s_cbranch_scc0 .LBB0_1797
	s_ashr_i32 s18, s28, 5
	s_movk_i32 s0, 0x100
	s_waitcnt vmcnt(0)
	v_and_b32_e32 v4, 63, v34
	v_lshrrev_b32_e32 v23, 6, v34
	s_and_b32 s27, s28, 1
	s_bfe_u32 s26, s28, 0x40001
	s_ashr_i32 s19, s18, 31
	v_cmp_gt_u32_e32 vcc, s0, v34
	s_and_saveexec_b64 s[0:1], vcc
	s_xor_b64 s[20:21], exec, s[0:1]
	s_cbranch_execz .LBB0_1752
	v_lshrrev_b32_e32 v1, 4, v4
	v_lshlrev_b32_e32 v1, 1, v1
	v_lshl_or_b32 v1, v23, 3, v1
	v_and_b32_e32 v2, 3, v4
	v_bfe_u32 v3, v4, 3, 1
	v_lshl_or_b32 v2, v3, 2, v2
	v_bfe_u32 v3, v4, 2, 1
	v_and_b32_e32 v10, 15, v4
	s_waitcnt lgkmcnt(0)
	s_barrier
	v_add_u32_e32 v3, v1, v3
	v_lshlrev_b32_e32 v3, 2, v3
	v_lshlrev_b32_e32 v12, 7, v2
	s_add_i32 s0, 0, 0x18000
	v_lshlrev_b32_e32 v10, 4, v10
	v_cmp_eq_u32_e32 vcc, 7, v2
	v_add3_u32 v11, s0, v12, v3
	v_cmp_eq_u32_e64 s[0:1], 0, v2
	v_cmp_eq_u32_e64 s[6:7], 1, v2
	v_cmp_eq_u32_e64 s[8:9], 2, v2
	v_cmp_eq_u32_e64 s[10:11], 3, v2
	v_cmp_eq_u32_e64 s[12:13], 4, v2
	v_cmp_eq_u32_e64 s[14:15], 5, v2
	v_cmp_eq_u32_e64 s[16:17], 6, v2
	v_mov_b32_e32 v2, 0
	s_lshl_b32 s5, s27, 7
	s_mov_b32 s22, 0
	v_mov_b32_e32 v3, v2
	v_mov_b32_e32 v4, v2
	v_mov_b32_e32 v5, v2
	v_mov_b32_e32 v6, v2
	v_mov_b32_e32 v7, v2
	v_mov_b32_e32 v8, v2
	v_mov_b32_e32 v9, v2
.LBB0_1750:
	s_and_b32 s23, s22, 1
	s_mul_i32 s2, s23, 0xc000
	s_add_i32 s2, s2, 0
	v_add_u32_e32 v20, s2, v10
	s_add_i32 s2, s2, s5
	v_lshl_add_u32 v21, v1, 2, s2
	ds_read_b128 v[36:39], v20 offset:0
	ds_read_b128 v[40:43], v20 offset:8192
	ds_read_b64 v[56:57], v21 offset:40960
	ds_read_b128 v[48:51], v20 offset:24576
	ds_read_b128 v[44:47], v20 offset:16384
	ds_read_b128 v[52:55], v20 offset:32768
	s_waitcnt lgkmcnt(0)
	v_pk_mul_f32 v[22:23], v[2:3], v[36:37] op_sel:[0,0] op_sel_hi:[1,0]
	ds_read_b128 v[60:63], v20 offset:256
	v_pk_fma_f32 v[22:23], v[4:5], v[36:37], v[22:23] op_sel:[0,1,0] op_sel_hi:[1,1,1]
	ds_read_b128 v[64:67], v20 offset:8448
	v_pk_fma_f32 v[22:23], v[6:7], v[38:39], v[22:23] op_sel:[0,0,0] op_sel_hi:[1,0,1]
	ds_read_b64 v[80:81], v21 offset:41216
	v_pk_fma_f32 v[22:23], v[8:9], v[38:39], v[22:23] op_sel:[0,1,0] op_sel_hi:[1,1,1]
	ds_read_b128 v[72:75], v20 offset:24832
	ds_read_b128 v[68:71], v20 offset:16640
	ds_read_b128 v[76:79], v20 offset:33024
	v_add_f32_dpp v22, v22, v22 quad_perm:[1,0,3,2] row_mask:0xf bank_mask:0xf
	v_add_f32_dpp v23, v23, v23 quad_perm:[1,0,3,2] row_mask:0xf bank_mask:0xf
	v_pk_mul_f32 v[84:85], v[2:3], v[40:41] op_sel:[0,0] op_sel_hi:[1,0]
	v_pk_mul_f32 v[86:87], v[4:5], v[40:41] op_sel:[0,1] op_sel_hi:[1,1]
	v_add_f32_dpp v22, v22, v22 quad_perm:[2,3,0,1] row_mask:0xf bank_mask:0xf
	v_add_f32_dpp v23, v23, v23 quad_perm:[2,3,0,1] row_mask:0xf bank_mask:0xf
	v_pk_mul_f32 v[88:89], v[6:7], v[42:43] op_sel:[0,0] op_sel_hi:[1,0]
	v_pk_mul_f32 v[90:91], v[8:9], v[42:43] op_sel:[0,1] op_sel_hi:[1,1]
	v_add_f32_dpp v22, v22, v22 row_half_mirror row_mask:0xf bank_mask:0xf
	v_add_f32_dpp v23, v23, v23 row_half_mirror row_mask:0xf bank_mask:0xf
	v_pk_fma_f32 v[84:85], v[48:49], v[56:57], v[84:85] op_sel:[0,0,0] op_sel_hi:[0,1,1]
	v_pk_fma_f32 v[86:87], v[48:49], v[56:57], v[86:87] op_sel:[1,0,0] op_sel_hi:[1,1,1]
	v_add_f32_dpp v22, v22, v22 row_mirror row_mask:0xf bank_mask:0xf
	v_add_f32_dpp v23, v23, v23 row_mirror row_mask:0xf bank_mask:0xf
	v_pk_fma_f32 v[88:89], v[50:51], v[56:57], v[88:89] op_sel:[0,0,0] op_sel_hi:[0,1,1]
	v_pk_fma_f32 v[90:91], v[50:51], v[56:57], v[90:91] op_sel:[1,0,0] op_sel_hi:[1,1,1]
	v_pk_fma_f32 v[2:3], v[44:45], v[22:23], v[84:85] op_sel:[0,0,0] op_sel_hi:[0,1,1] neg_lo:[1,0,0] neg_hi:[1,0,0]
	v_pk_fma_f32 v[4:5], v[44:45], v[22:23], v[86:87] op_sel:[1,0,0] op_sel_hi:[1,1,1] neg_lo:[1,0,0] neg_hi:[1,0,0]
	v_pk_fma_f32 v[6:7], v[46:47], v[22:23], v[88:89] op_sel:[0,0,0] op_sel_hi:[0,1,1] neg_lo:[1,0,0] neg_hi:[1,0,0]
	v_pk_fma_f32 v[8:9], v[46:47], v[22:23], v[90:91] op_sel:[1,0,0] op_sel_hi:[1,1,1] neg_lo:[1,0,0] neg_hi:[1,0,0]
	v_pk_mul_f32 v[24:25], v[2:3], v[52:53] op_sel:[0,0] op_sel_hi:[1,0]
	v_pk_mul_f32 v[84:85], v[4:5], v[52:53] op_sel:[0,1] op_sel_hi:[1,1]
	v_pk_fma_f32 v[24:25], v[6:7], v[54:55], v[24:25] op_sel:[0,0,0] op_sel_hi:[1,0,1]
	v_pk_fma_f32 v[84:85], v[8:9], v[54:55], v[84:85] op_sel:[0,1,0] op_sel_hi:[1,1,1]
	v_pk_add_f32 v[24:25], v[24:25], v[84:85]
	s_waitcnt lgkmcnt(0)
	v_pk_mul_f32 v[22:23], v[2:3], v[60:61] op_sel:[0,0] op_sel_hi:[1,0]
	ds_read_b128 v[36:39], v20 offset:512
	v_pk_fma_f32 v[22:23], v[4:5], v[60:61], v[22:23] op_sel:[0,1,0] op_sel_hi:[1,1,1]
	ds_read_b128 v[40:43], v20 offset:8704
	v_pk_fma_f32 v[22:23], v[6:7], v[62:63], v[22:23] op_sel:[0,0,0] op_sel_hi:[1,0,1]
	ds_read_b64 v[56:57], v21 offset:41472
	v_pk_fma_f32 v[22:23], v[8:9], v[62:63], v[22:23] op_sel:[0,1,0] op_sel_hi:[1,1,1]
	ds_read_b128 v[48:51], v20 offset:25088
	v_add_f32_dpp v24, v24, v24 row_ror:12 row_mask:0xf bank_mask:0x5
	ds_read_b128 v[44:47], v20 offset:16896
	v_add_f32_dpp v25, v25, v25 row_ror:4 row_mask:0xf bank_mask:0xa
	ds_read_b128 v[52:55], v20 offset:33280
	v_add_f32_dpp v22, v22, v22 quad_perm:[1,0,3,2] row_mask:0xf bank_mask:0xf
	v_add_f32_dpp v23, v23, v23 quad_perm:[1,0,3,2] row_mask:0xf bank_mask:0xf
	v_pk_mul_f32 v[84:85], v[2:3], v[64:65] op_sel:[0,0] op_sel_hi:[1,0]
	v_pk_mul_f32 v[86:87], v[4:5], v[64:65] op_sel:[0,1] op_sel_hi:[1,1]
	v_mov_b32_dpp v24, v25 quad_perm:[0,1,2,3] row_mask:0xf bank_mask:0xa
	v_add_f32_dpp v22, v22, v22 quad_perm:[2,3,0,1] row_mask:0xf bank_mask:0xf
	v_add_f32_dpp v23, v23, v23 quad_perm:[2,3,0,1] row_mask:0xf bank_mask:0xf
	v_pk_mul_f32 v[88:89], v[6:7], v[66:67] op_sel:[0,0] op_sel_hi:[1,0]
	v_pk_mul_f32 v[90:91], v[8:9], v[66:67] op_sel:[0,1] op_sel_hi:[1,1]
	v_add_f32_dpp v24, v24, v24 row_ror:8 row_mask:0xf bank_mask:0xf
	v_add_f32_dpp v22, v22, v22 row_half_mirror row_mask:0xf bank_mask:0xf
	v_add_f32_dpp v23, v23, v23 row_half_mirror row_mask:0xf bank_mask:0xf
	v_pk_fma_f32 v[84:85], v[72:73], v[80:81], v[84:85] op_sel:[0,0,0] op_sel_hi:[0,1,1]
	v_pk_fma_f32 v[86:87], v[72:73], v[80:81], v[86:87] op_sel:[1,0,0] op_sel_hi:[1,1,1]
	v_add_f32_dpp v24, v24, v24 quad_perm:[1,0,3,2] row_mask:0xf bank_mask:0xf
	v_add_f32_dpp v22, v22, v22 row_mirror row_mask:0xf bank_mask:0xf
	v_add_f32_dpp v23, v23, v23 row_mirror row_mask:0xf bank_mask:0xf
	v_pk_fma_f32 v[88:89], v[74:75], v[80:81], v[88:89] op_sel:[0,0,0] op_sel_hi:[0,1,1]
	v_pk_fma_f32 v[90:91], v[74:75], v[80:81], v[90:91] op_sel:[1,0,0] op_sel_hi:[1,1,1]
	v_add_f32_dpp v24, v24, v24 quad_perm:[2,3,0,1] row_mask:0xf bank_mask:0xf
	v_cndmask_b32_e64 v30, 0, v24, s[0:1]
	v_pk_fma_f32 v[2:3], v[68:69], v[22:23], v[84:85] op_sel:[0,0,0] op_sel_hi:[0,1,1] neg_lo:[1,0,0] neg_hi:[1,0,0]
	v_pk_fma_f32 v[4:5], v[68:69], v[22:23], v[86:87] op_sel:[1,0,0] op_sel_hi:[1,1,1] neg_lo:[1,0,0] neg_hi:[1,0,0]
	v_pk_fma_f32 v[6:7], v[70:71], v[22:23], v[88:89] op_sel:[0,0,0] op_sel_hi:[0,1,1] neg_lo:[1,0,0] neg_hi:[1,0,0]
	v_pk_fma_f32 v[8:9], v[70:71], v[22:23], v[90:91] op_sel:[1,0,0] op_sel_hi:[1,1,1] neg_lo:[1,0,0] neg_hi:[1,0,0]
	v_pk_mul_f32 v[26:27], v[2:3], v[76:77] op_sel:[0,0] op_sel_hi:[1,0]
	v_pk_mul_f32 v[84:85], v[4:5], v[76:77] op_sel:[0,1] op_sel_hi:[1,1]
	v_pk_fma_f32 v[26:27], v[6:7], v[78:79], v[26:27] op_sel:[0,0,0] op_sel_hi:[1,0,1]
	v_pk_fma_f32 v[84:85], v[8:9], v[78:79], v[84:85] op_sel:[0,1,0] op_sel_hi:[1,1,1]
	v_pk_add_f32 v[26:27], v[26:27], v[84:85]
	s_waitcnt lgkmcnt(0)
	v_pk_mul_f32 v[22:23], v[2:3], v[36:37] op_sel:[0,0] op_sel_hi:[1,0]
	ds_read_b128 v[60:63], v20 offset:768
	v_pk_fma_f32 v[22:23], v[4:5], v[36:37], v[22:23] op_sel:[0,1,0] op_sel_hi:[1,1,1]
	ds_read_b128 v[64:67], v20 offset:8960
	v_pk_fma_f32 v[22:23], v[6:7], v[38:39], v[22:23] op_sel:[0,0,0] op_sel_hi:[1,0,1]
	ds_read_b64 v[80:81], v21 offset:41728
	v_pk_fma_f32 v[22:23], v[8:9], v[38:39], v[22:23] op_sel:[0,1,0] op_sel_hi:[1,1,1]
	ds_read_b128 v[72:75], v20 offset:25344
	v_add_f32_dpp v26, v26, v26 row_ror:12 row_mask:0xf bank_mask:0x5
	ds_read_b128 v[68:71], v20 offset:17152
	v_add_f32_dpp v27, v27, v27 row_ror:4 row_mask:0xf bank_mask:0xa
	ds_read_b128 v[76:79], v20 offset:33536
	v_add_f32_dpp v22, v22, v22 quad_perm:[1,0,3,2] row_mask:0xf bank_mask:0xf
	v_add_f32_dpp v23, v23, v23 quad_perm:[1,0,3,2] row_mask:0xf bank_mask:0xf
	v_pk_mul_f32 v[84:85], v[2:3], v[40:41] op_sel:[0,0] op_sel_hi:[1,0]
	v_pk_mul_f32 v[86:87], v[4:5], v[40:41] op_sel:[0,1] op_sel_hi:[1,1]
	v_mov_b32_dpp v26, v27 quad_perm:[0,1,2,3] row_mask:0xf bank_mask:0xa
	v_add_f32_dpp v22, v22, v22 quad_perm:[2,3,0,1] row_mask:0xf bank_mask:0xf
	v_add_f32_dpp v23, v23, v23 quad_perm:[2,3,0,1] row_mask:0xf bank_mask:0xf
	v_pk_mul_f32 v[88:89], v[6:7], v[42:43] op_sel:[0,0] op_sel_hi:[1,0]
	v_pk_mul_f32 v[90:91], v[8:9], v[42:43] op_sel:[0,1] op_sel_hi:[1,1]
	v_add_f32_dpp v26, v26, v26 row_ror:8 row_mask:0xf bank_mask:0xf
	v_add_f32_dpp v22, v22, v22 row_half_mirror row_mask:0xf bank_mask:0xf
	v_add_f32_dpp v23, v23, v23 row_half_mirror row_mask:0xf bank_mask:0xf
	v_pk_fma_f32 v[84:85], v[48:49], v[56:57], v[84:85] op_sel:[0,0,0] op_sel_hi:[0,1,1]
	v_pk_fma_f32 v[86:87], v[48:49], v[56:57], v[86:87] op_sel:[1,0,0] op_sel_hi:[1,1,1]
	v_add_f32_dpp v26, v26, v26 quad_perm:[1,0,3,2] row_mask:0xf bank_mask:0xf
	v_add_f32_dpp v22, v22, v22 row_mirror row_mask:0xf bank_mask:0xf
	v_add_f32_dpp v23, v23, v23 row_mirror row_mask:0xf bank_mask:0xf
	v_pk_fma_f32 v[88:89], v[50:51], v[56:57], v[88:89] op_sel:[0,0,0] op_sel_hi:[0,1,1]
	v_pk_fma_f32 v[90:91], v[50:51], v[56:57], v[90:91] op_sel:[1,0,0] op_sel_hi:[1,1,1]
	v_add_f32_dpp v26, v26, v26 quad_perm:[2,3,0,1] row_mask:0xf bank_mask:0xf
	v_cndmask_b32_e64 v30, v30, v26, s[6:7]
	v_pk_fma_f32 v[2:3], v[44:45], v[22:23], v[84:85] op_sel:[0,0,0] op_sel_hi:[0,1,1] neg_lo:[1,0,0] neg_hi:[1,0,0]
	v_pk_fma_f32 v[4:5], v[44:45], v[22:23], v[86:87] op_sel:[1,0,0] op_sel_hi:[1,1,1] neg_lo:[1,0,0] neg_hi:[1,0,0]
	v_pk_fma_f32 v[6:7], v[46:47], v[22:23], v[88:89] op_sel:[0,0,0] op_sel_hi:[0,1,1] neg_lo:[1,0,0] neg_hi:[1,0,0]
	v_pk_fma_f32 v[8:9], v[46:47], v[22:23], v[90:91] op_sel:[1,0,0] op_sel_hi:[1,1,1] neg_lo:[1,0,0] neg_hi:[1,0,0]
	v_pk_mul_f32 v[24:25], v[2:3], v[52:53] op_sel:[0,0] op_sel_hi:[1,0]
	v_pk_mul_f32 v[84:85], v[4:5], v[52:53] op_sel:[0,1] op_sel_hi:[1,1]
	v_pk_fma_f32 v[24:25], v[6:7], v[54:55], v[24:25] op_sel:[0,0,0] op_sel_hi:[1,0,1]
	v_pk_fma_f32 v[84:85], v[8:9], v[54:55], v[84:85] op_sel:[0,1,0] op_sel_hi:[1,1,1]
	v_pk_add_f32 v[24:25], v[24:25], v[84:85]
	s_waitcnt lgkmcnt(0)
	v_pk_mul_f32 v[22:23], v[2:3], v[60:61] op_sel:[0,0] op_sel_hi:[1,0]
	ds_read_b128 v[36:39], v20 offset:1024
	v_pk_fma_f32 v[22:23], v[4:5], v[60:61], v[22:23] op_sel:[0,1,0] op_sel_hi:[1,1,1]
	ds_read_b128 v[40:43], v20 offset:9216
	v_pk_fma_f32 v[22:23], v[6:7], v[62:63], v[22:23] op_sel:[0,0,0] op_sel_hi:[1,0,1]
	ds_read_b64 v[56:57], v21 offset:41984
	v_pk_fma_f32 v[22:23], v[8:9], v[62:63], v[22:23] op_sel:[0,1,0] op_sel_hi:[1,1,1]
	ds_read_b128 v[48:51], v20 offset:25600
	v_add_f32_dpp v24, v24, v24 row_ror:12 row_mask:0xf bank_mask:0x5
	ds_read_b128 v[44:47], v20 offset:17408
	v_add_f32_dpp v25, v25, v25 row_ror:4 row_mask:0xf bank_mask:0xa
	ds_read_b128 v[52:55], v20 offset:33792
	v_add_f32_dpp v22, v22, v22 quad_perm:[1,0,3,2] row_mask:0xf bank_mask:0xf
	v_add_f32_dpp v23, v23, v23 quad_perm:[1,0,3,2] row_mask:0xf bank_mask:0xf
	v_pk_mul_f32 v[84:85], v[2:3], v[64:65] op_sel:[0,0] op_sel_hi:[1,0]
	v_pk_mul_f32 v[86:87], v[4:5], v[64:65] op_sel:[0,1] op_sel_hi:[1,1]
	v_mov_b32_dpp v24, v25 quad_perm:[0,1,2,3] row_mask:0xf bank_mask:0xa
	v_add_f32_dpp v22, v22, v22 quad_perm:[2,3,0,1] row_mask:0xf bank_mask:0xf
	v_add_f32_dpp v23, v23, v23 quad_perm:[2,3,0,1] row_mask:0xf bank_mask:0xf
	v_pk_mul_f32 v[88:89], v[6:7], v[66:67] op_sel:[0,0] op_sel_hi:[1,0]
	v_pk_mul_f32 v[90:91], v[8:9], v[66:67] op_sel:[0,1] op_sel_hi:[1,1]
	v_add_f32_dpp v24, v24, v24 row_ror:8 row_mask:0xf bank_mask:0xf
	v_add_f32_dpp v22, v22, v22 row_half_mirror row_mask:0xf bank_mask:0xf
	v_add_f32_dpp v23, v23, v23 row_half_mirror row_mask:0xf bank_mask:0xf
	v_pk_fma_f32 v[84:85], v[72:73], v[80:81], v[84:85] op_sel:[0,0,0] op_sel_hi:[0,1,1]
	v_pk_fma_f32 v[86:87], v[72:73], v[80:81], v[86:87] op_sel:[1,0,0] op_sel_hi:[1,1,1]
	v_add_f32_dpp v24, v24, v24 quad_perm:[1,0,3,2] row_mask:0xf bank_mask:0xf
	v_add_f32_dpp v22, v22, v22 row_mirror row_mask:0xf bank_mask:0xf
	v_add_f32_dpp v23, v23, v23 row_mirror row_mask:0xf bank_mask:0xf
	v_pk_fma_f32 v[88:89], v[74:75], v[80:81], v[88:89] op_sel:[0,0,0] op_sel_hi:[0,1,1]
	v_pk_fma_f32 v[90:91], v[74:75], v[80:81], v[90:91] op_sel:[1,0,0] op_sel_hi:[1,1,1]
	v_add_f32_dpp v24, v24, v24 quad_perm:[2,3,0,1] row_mask:0xf bank_mask:0xf
	v_cndmask_b32_e64 v30, v30, v24, s[8:9]
	v_pk_fma_f32 v[2:3], v[68:69], v[22:23], v[84:85] op_sel:[0,0,0] op_sel_hi:[0,1,1] neg_lo:[1,0,0] neg_hi:[1,0,0]
	v_pk_fma_f32 v[4:5], v[68:69], v[22:23], v[86:87] op_sel:[1,0,0] op_sel_hi:[1,1,1] neg_lo:[1,0,0] neg_hi:[1,0,0]
	v_pk_fma_f32 v[6:7], v[70:71], v[22:23], v[88:89] op_sel:[0,0,0] op_sel_hi:[0,1,1] neg_lo:[1,0,0] neg_hi:[1,0,0]
	v_pk_fma_f32 v[8:9], v[70:71], v[22:23], v[90:91] op_sel:[1,0,0] op_sel_hi:[1,1,1] neg_lo:[1,0,0] neg_hi:[1,0,0]
	v_pk_mul_f32 v[26:27], v[2:3], v[76:77] op_sel:[0,0] op_sel_hi:[1,0]
	v_pk_mul_f32 v[84:85], v[4:5], v[76:77] op_sel:[0,1] op_sel_hi:[1,1]
	v_pk_fma_f32 v[26:27], v[6:7], v[78:79], v[26:27] op_sel:[0,0,0] op_sel_hi:[1,0,1]
	v_pk_fma_f32 v[84:85], v[8:9], v[78:79], v[84:85] op_sel:[0,1,0] op_sel_hi:[1,1,1]
	v_pk_add_f32 v[26:27], v[26:27], v[84:85]
	s_waitcnt lgkmcnt(0)
	v_pk_mul_f32 v[22:23], v[2:3], v[36:37] op_sel:[0,0] op_sel_hi:[1,0]
	ds_read_b128 v[60:63], v20 offset:1280
	v_pk_fma_f32 v[22:23], v[4:5], v[36:37], v[22:23] op_sel:[0,1,0] op_sel_hi:[1,1,1]
	ds_read_b128 v[64:67], v20 offset:9472
	v_pk_fma_f32 v[22:23], v[6:7], v[38:39], v[22:23] op_sel:[0,0,0] op_sel_hi:[1,0,1]
	ds_read_b64 v[80:81], v21 offset:42240
	v_pk_fma_f32 v[22:23], v[8:9], v[38:39], v[22:23] op_sel:[0,1,0] op_sel_hi:[1,1,1]
	ds_read_b128 v[72:75], v20 offset:25856
	v_add_f32_dpp v26, v26, v26 row_ror:12 row_mask:0xf bank_mask:0x5
	ds_read_b128 v[68:71], v20 offset:17664
	v_add_f32_dpp v27, v27, v27 row_ror:4 row_mask:0xf bank_mask:0xa
	ds_read_b128 v[76:79], v20 offset:34048
	v_add_f32_dpp v22, v22, v22 quad_perm:[1,0,3,2] row_mask:0xf bank_mask:0xf
	v_add_f32_dpp v23, v23, v23 quad_perm:[1,0,3,2] row_mask:0xf bank_mask:0xf
	v_pk_mul_f32 v[84:85], v[2:3], v[40:41] op_sel:[0,0] op_sel_hi:[1,0]
	v_pk_mul_f32 v[86:87], v[4:5], v[40:41] op_sel:[0,1] op_sel_hi:[1,1]
	v_mov_b32_dpp v26, v27 quad_perm:[0,1,2,3] row_mask:0xf bank_mask:0xa
	v_add_f32_dpp v22, v22, v22 quad_perm:[2,3,0,1] row_mask:0xf bank_mask:0xf
	v_add_f32_dpp v23, v23, v23 quad_perm:[2,3,0,1] row_mask:0xf bank_mask:0xf
	v_pk_mul_f32 v[88:89], v[6:7], v[42:43] op_sel:[0,0] op_sel_hi:[1,0]
	v_pk_mul_f32 v[90:91], v[8:9], v[42:43] op_sel:[0,1] op_sel_hi:[1,1]
	v_add_f32_dpp v26, v26, v26 row_ror:8 row_mask:0xf bank_mask:0xf
	v_add_f32_dpp v22, v22, v22 row_half_mirror row_mask:0xf bank_mask:0xf
	v_add_f32_dpp v23, v23, v23 row_half_mirror row_mask:0xf bank_mask:0xf
	v_pk_fma_f32 v[84:85], v[48:49], v[56:57], v[84:85] op_sel:[0,0,0] op_sel_hi:[0,1,1]
	v_pk_fma_f32 v[86:87], v[48:49], v[56:57], v[86:87] op_sel:[1,0,0] op_sel_hi:[1,1,1]
	v_add_f32_dpp v26, v26, v26 quad_perm:[1,0,3,2] row_mask:0xf bank_mask:0xf
	v_add_f32_dpp v22, v22, v22 row_mirror row_mask:0xf bank_mask:0xf
	v_add_f32_dpp v23, v23, v23 row_mirror row_mask:0xf bank_mask:0xf
	v_pk_fma_f32 v[88:89], v[50:51], v[56:57], v[88:89] op_sel:[0,0,0] op_sel_hi:[0,1,1]
	v_pk_fma_f32 v[90:91], v[50:51], v[56:57], v[90:91] op_sel:[1,0,0] op_sel_hi:[1,1,1]
	v_add_f32_dpp v26, v26, v26 quad_perm:[2,3,0,1] row_mask:0xf bank_mask:0xf
	v_cndmask_b32_e64 v30, v30, v26, s[10:11]
	v_pk_fma_f32 v[2:3], v[44:45], v[22:23], v[84:85] op_sel:[0,0,0] op_sel_hi:[0,1,1] neg_lo:[1,0,0] neg_hi:[1,0,0]
	v_pk_fma_f32 v[4:5], v[44:45], v[22:23], v[86:87] op_sel:[1,0,0] op_sel_hi:[1,1,1] neg_lo:[1,0,0] neg_hi:[1,0,0]
	v_pk_fma_f32 v[6:7], v[46:47], v[22:23], v[88:89] op_sel:[0,0,0] op_sel_hi:[0,1,1] neg_lo:[1,0,0] neg_hi:[1,0,0]
	v_pk_fma_f32 v[8:9], v[46:47], v[22:23], v[90:91] op_sel:[1,0,0] op_sel_hi:[1,1,1] neg_lo:[1,0,0] neg_hi:[1,0,0]
	v_pk_mul_f32 v[24:25], v[2:3], v[52:53] op_sel:[0,0] op_sel_hi:[1,0]
	v_pk_mul_f32 v[84:85], v[4:5], v[52:53] op_sel:[0,1] op_sel_hi:[1,1]
	v_pk_fma_f32 v[24:25], v[6:7], v[54:55], v[24:25] op_sel:[0,0,0] op_sel_hi:[1,0,1]
	v_pk_fma_f32 v[84:85], v[8:9], v[54:55], v[84:85] op_sel:[0,1,0] op_sel_hi:[1,1,1]
	v_pk_add_f32 v[24:25], v[24:25], v[84:85]
	s_waitcnt lgkmcnt(0)
	v_pk_mul_f32 v[22:23], v[2:3], v[60:61] op_sel:[0,0] op_sel_hi:[1,0]
	ds_read_b128 v[36:39], v20 offset:1536
	v_pk_fma_f32 v[22:23], v[4:5], v[60:61], v[22:23] op_sel:[0,1,0] op_sel_hi:[1,1,1]
	ds_read_b128 v[40:43], v20 offset:9728
	v_pk_fma_f32 v[22:23], v[6:7], v[62:63], v[22:23] op_sel:[0,0,0] op_sel_hi:[1,0,1]
	ds_read_b64 v[56:57], v21 offset:42496
	v_pk_fma_f32 v[22:23], v[8:9], v[62:63], v[22:23] op_sel:[0,1,0] op_sel_hi:[1,1,1]
	ds_read_b128 v[48:51], v20 offset:26112
	v_add_f32_dpp v24, v24, v24 row_ror:12 row_mask:0xf bank_mask:0x5
	ds_read_b128 v[44:47], v20 offset:17920
	v_add_f32_dpp v25, v25, v25 row_ror:4 row_mask:0xf bank_mask:0xa
	ds_read_b128 v[52:55], v20 offset:34304
	v_add_f32_dpp v22, v22, v22 quad_perm:[1,0,3,2] row_mask:0xf bank_mask:0xf
	v_add_f32_dpp v23, v23, v23 quad_perm:[1,0,3,2] row_mask:0xf bank_mask:0xf
	v_pk_mul_f32 v[84:85], v[2:3], v[64:65] op_sel:[0,0] op_sel_hi:[1,0]
	v_pk_mul_f32 v[86:87], v[4:5], v[64:65] op_sel:[0,1] op_sel_hi:[1,1]
	v_mov_b32_dpp v24, v25 quad_perm:[0,1,2,3] row_mask:0xf bank_mask:0xa
	v_add_f32_dpp v22, v22, v22 quad_perm:[2,3,0,1] row_mask:0xf bank_mask:0xf
	v_add_f32_dpp v23, v23, v23 quad_perm:[2,3,0,1] row_mask:0xf bank_mask:0xf
	v_pk_mul_f32 v[88:89], v[6:7], v[66:67] op_sel:[0,0] op_sel_hi:[1,0]
	v_pk_mul_f32 v[90:91], v[8:9], v[66:67] op_sel:[0,1] op_sel_hi:[1,1]
	v_add_f32_dpp v24, v24, v24 row_ror:8 row_mask:0xf bank_mask:0xf
	v_add_f32_dpp v22, v22, v22 row_half_mirror row_mask:0xf bank_mask:0xf
	v_add_f32_dpp v23, v23, v23 row_half_mirror row_mask:0xf bank_mask:0xf
	v_pk_fma_f32 v[84:85], v[72:73], v[80:81], v[84:85] op_sel:[0,0,0] op_sel_hi:[0,1,1]
	v_pk_fma_f32 v[86:87], v[72:73], v[80:81], v[86:87] op_sel:[1,0,0] op_sel_hi:[1,1,1]
	v_add_f32_dpp v24, v24, v24 quad_perm:[1,0,3,2] row_mask:0xf bank_mask:0xf
	v_add_f32_dpp v22, v22, v22 row_mirror row_mask:0xf bank_mask:0xf
	v_add_f32_dpp v23, v23, v23 row_mirror row_mask:0xf bank_mask:0xf
	v_pk_fma_f32 v[88:89], v[74:75], v[80:81], v[88:89] op_sel:[0,0,0] op_sel_hi:[0,1,1]
	v_pk_fma_f32 v[90:91], v[74:75], v[80:81], v[90:91] op_sel:[1,0,0] op_sel_hi:[1,1,1]
	v_add_f32_dpp v24, v24, v24 quad_perm:[2,3,0,1] row_mask:0xf bank_mask:0xf
	v_cndmask_b32_e64 v30, v30, v24, s[12:13]
	v_pk_fma_f32 v[2:3], v[68:69], v[22:23], v[84:85] op_sel:[0,0,0] op_sel_hi:[0,1,1] neg_lo:[1,0,0] neg_hi:[1,0,0]
	v_pk_fma_f32 v[4:5], v[68:69], v[22:23], v[86:87] op_sel:[1,0,0] op_sel_hi:[1,1,1] neg_lo:[1,0,0] neg_hi:[1,0,0]
	v_pk_fma_f32 v[6:7], v[70:71], v[22:23], v[88:89] op_sel:[0,0,0] op_sel_hi:[0,1,1] neg_lo:[1,0,0] neg_hi:[1,0,0]
	v_pk_fma_f32 v[8:9], v[70:71], v[22:23], v[90:91] op_sel:[1,0,0] op_sel_hi:[1,1,1] neg_lo:[1,0,0] neg_hi:[1,0,0]
	v_pk_mul_f32 v[26:27], v[2:3], v[76:77] op_sel:[0,0] op_sel_hi:[1,0]
	v_pk_mul_f32 v[84:85], v[4:5], v[76:77] op_sel:[0,1] op_sel_hi:[1,1]
	v_pk_fma_f32 v[26:27], v[6:7], v[78:79], v[26:27] op_sel:[0,0,0] op_sel_hi:[1,0,1]
	v_pk_fma_f32 v[84:85], v[8:9], v[78:79], v[84:85] op_sel:[0,1,0] op_sel_hi:[1,1,1]
	v_pk_add_f32 v[26:27], v[26:27], v[84:85]
	s_waitcnt lgkmcnt(0)
	v_pk_mul_f32 v[22:23], v[2:3], v[36:37] op_sel:[0,0] op_sel_hi:[1,0]
	ds_read_b128 v[60:63], v20 offset:1792
	v_pk_fma_f32 v[22:23], v[4:5], v[36:37], v[22:23] op_sel:[0,1,0] op_sel_hi:[1,1,1]
	ds_read_b128 v[64:67], v20 offset:9984
	v_pk_fma_f32 v[22:23], v[6:7], v[38:39], v[22:23] op_sel:[0,0,0] op_sel_hi:[1,0,1]
	ds_read_b64 v[80:81], v21 offset:42752
	v_pk_fma_f32 v[22:23], v[8:9], v[38:39], v[22:23] op_sel:[0,1,0] op_sel_hi:[1,1,1]
	ds_read_b128 v[72:75], v20 offset:26368
	v_add_f32_dpp v26, v26, v26 row_ror:12 row_mask:0xf bank_mask:0x5
	ds_read_b128 v[68:71], v20 offset:18176
	v_add_f32_dpp v27, v27, v27 row_ror:4 row_mask:0xf bank_mask:0xa
	ds_read_b128 v[76:79], v20 offset:34560
	v_add_f32_dpp v22, v22, v22 quad_perm:[1,0,3,2] row_mask:0xf bank_mask:0xf
	v_add_f32_dpp v23, v23, v23 quad_perm:[1,0,3,2] row_mask:0xf bank_mask:0xf
	v_pk_mul_f32 v[84:85], v[2:3], v[40:41] op_sel:[0,0] op_sel_hi:[1,0]
	v_pk_mul_f32 v[86:87], v[4:5], v[40:41] op_sel:[0,1] op_sel_hi:[1,1]
	v_mov_b32_dpp v26, v27 quad_perm:[0,1,2,3] row_mask:0xf bank_mask:0xa
	v_add_f32_dpp v22, v22, v22 quad_perm:[2,3,0,1] row_mask:0xf bank_mask:0xf
	v_add_f32_dpp v23, v23, v23 quad_perm:[2,3,0,1] row_mask:0xf bank_mask:0xf
	v_pk_mul_f32 v[88:89], v[6:7], v[42:43] op_sel:[0,0] op_sel_hi:[1,0]
	v_pk_mul_f32 v[90:91], v[8:9], v[42:43] op_sel:[0,1] op_sel_hi:[1,1]
	v_add_f32_dpp v26, v26, v26 row_ror:8 row_mask:0xf bank_mask:0xf
	v_add_f32_dpp v22, v22, v22 row_half_mirror row_mask:0xf bank_mask:0xf
	v_add_f32_dpp v23, v23, v23 row_half_mirror row_mask:0xf bank_mask:0xf
	v_pk_fma_f32 v[84:85], v[48:49], v[56:57], v[84:85] op_sel:[0,0,0] op_sel_hi:[0,1,1]
	v_pk_fma_f32 v[86:87], v[48:49], v[56:57], v[86:87] op_sel:[1,0,0] op_sel_hi:[1,1,1]
	v_add_f32_dpp v26, v26, v26 quad_perm:[1,0,3,2] row_mask:0xf bank_mask:0xf
	v_add_f32_dpp v22, v22, v22 row_mirror row_mask:0xf bank_mask:0xf
	v_add_f32_dpp v23, v23, v23 row_mirror row_mask:0xf bank_mask:0xf
	v_pk_fma_f32 v[88:89], v[50:51], v[56:57], v[88:89] op_sel:[0,0,0] op_sel_hi:[0,1,1]
	v_pk_fma_f32 v[90:91], v[50:51], v[56:57], v[90:91] op_sel:[1,0,0] op_sel_hi:[1,1,1]
	v_add_f32_dpp v26, v26, v26 quad_perm:[2,3,0,1] row_mask:0xf bank_mask:0xf
	v_cndmask_b32_e64 v30, v30, v26, s[14:15]
	v_pk_fma_f32 v[2:3], v[44:45], v[22:23], v[84:85] op_sel:[0,0,0] op_sel_hi:[0,1,1] neg_lo:[1,0,0] neg_hi:[1,0,0]
	v_pk_fma_f32 v[4:5], v[44:45], v[22:23], v[86:87] op_sel:[1,0,0] op_sel_hi:[1,1,1] neg_lo:[1,0,0] neg_hi:[1,0,0]
	v_pk_fma_f32 v[6:7], v[46:47], v[22:23], v[88:89] op_sel:[0,0,0] op_sel_hi:[0,1,1] neg_lo:[1,0,0] neg_hi:[1,0,0]
	v_pk_fma_f32 v[8:9], v[46:47], v[22:23], v[90:91] op_sel:[1,0,0] op_sel_hi:[1,1,1] neg_lo:[1,0,0] neg_hi:[1,0,0]
	v_pk_mul_f32 v[24:25], v[2:3], v[52:53] op_sel:[0,0] op_sel_hi:[1,0]
	v_pk_mul_f32 v[84:85], v[4:5], v[52:53] op_sel:[0,1] op_sel_hi:[1,1]
	v_pk_fma_f32 v[24:25], v[6:7], v[54:55], v[24:25] op_sel:[0,0,0] op_sel_hi:[1,0,1]
	v_pk_fma_f32 v[84:85], v[8:9], v[54:55], v[84:85] op_sel:[0,1,0] op_sel_hi:[1,1,1]
	v_pk_add_f32 v[24:25], v[24:25], v[84:85]
	s_waitcnt lgkmcnt(0)
	v_pk_mul_f32 v[22:23], v[2:3], v[60:61] op_sel:[0,0] op_sel_hi:[1,0]
	ds_read_b128 v[36:39], v20 offset:2048
	v_pk_fma_f32 v[22:23], v[4:5], v[60:61], v[22:23] op_sel:[0,1,0] op_sel_hi:[1,1,1]
	ds_read_b128 v[40:43], v20 offset:10240
	v_pk_fma_f32 v[22:23], v[6:7], v[62:63], v[22:23] op_sel:[0,0,0] op_sel_hi:[1,0,1]
	ds_read_b64 v[56:57], v21 offset:43008
	v_pk_fma_f32 v[22:23], v[8:9], v[62:63], v[22:23] op_sel:[0,1,0] op_sel_hi:[1,1,1]
	ds_read_b128 v[48:51], v20 offset:26624
	v_add_f32_dpp v24, v24, v24 row_ror:12 row_mask:0xf bank_mask:0x5
	ds_read_b128 v[44:47], v20 offset:18432
	v_add_f32_dpp v25, v25, v25 row_ror:4 row_mask:0xf bank_mask:0xa
	ds_read_b128 v[52:55], v20 offset:34816
	v_add_f32_dpp v22, v22, v22 quad_perm:[1,0,3,2] row_mask:0xf bank_mask:0xf
	v_add_f32_dpp v23, v23, v23 quad_perm:[1,0,3,2] row_mask:0xf bank_mask:0xf
	v_pk_mul_f32 v[84:85], v[2:3], v[64:65] op_sel:[0,0] op_sel_hi:[1,0]
	v_pk_mul_f32 v[86:87], v[4:5], v[64:65] op_sel:[0,1] op_sel_hi:[1,1]
	v_mov_b32_dpp v24, v25 quad_perm:[0,1,2,3] row_mask:0xf bank_mask:0xa
	v_add_f32_dpp v22, v22, v22 quad_perm:[2,3,0,1] row_mask:0xf bank_mask:0xf
	v_add_f32_dpp v23, v23, v23 quad_perm:[2,3,0,1] row_mask:0xf bank_mask:0xf
	v_pk_mul_f32 v[88:89], v[6:7], v[66:67] op_sel:[0,0] op_sel_hi:[1,0]
	v_pk_mul_f32 v[90:91], v[8:9], v[66:67] op_sel:[0,1] op_sel_hi:[1,1]
	v_add_f32_dpp v24, v24, v24 row_ror:8 row_mask:0xf bank_mask:0xf
	v_add_f32_dpp v22, v22, v22 row_half_mirror row_mask:0xf bank_mask:0xf
	v_add_f32_dpp v23, v23, v23 row_half_mirror row_mask:0xf bank_mask:0xf
	v_pk_fma_f32 v[84:85], v[72:73], v[80:81], v[84:85] op_sel:[0,0,0] op_sel_hi:[0,1,1]
	v_pk_fma_f32 v[86:87], v[72:73], v[80:81], v[86:87] op_sel:[1,0,0] op_sel_hi:[1,1,1]
	v_add_f32_dpp v24, v24, v24 quad_perm:[1,0,3,2] row_mask:0xf bank_mask:0xf
	v_add_f32_dpp v22, v22, v22 row_mirror row_mask:0xf bank_mask:0xf
	v_add_f32_dpp v23, v23, v23 row_mirror row_mask:0xf bank_mask:0xf
	v_pk_fma_f32 v[88:89], v[74:75], v[80:81], v[88:89] op_sel:[0,0,0] op_sel_hi:[0,1,1]
	v_pk_fma_f32 v[90:91], v[74:75], v[80:81], v[90:91] op_sel:[1,0,0] op_sel_hi:[1,1,1]
	v_add_f32_dpp v24, v24, v24 quad_perm:[2,3,0,1] row_mask:0xf bank_mask:0xf
	v_cndmask_b32_e64 v30, v30, v24, s[16:17]
	v_pk_fma_f32 v[2:3], v[68:69], v[22:23], v[84:85] op_sel:[0,0,0] op_sel_hi:[0,1,1] neg_lo:[1,0,0] neg_hi:[1,0,0]
	v_pk_fma_f32 v[4:5], v[68:69], v[22:23], v[86:87] op_sel:[1,0,0] op_sel_hi:[1,1,1] neg_lo:[1,0,0] neg_hi:[1,0,0]
	v_pk_fma_f32 v[6:7], v[70:71], v[22:23], v[88:89] op_sel:[0,0,0] op_sel_hi:[0,1,1] neg_lo:[1,0,0] neg_hi:[1,0,0]
	v_pk_fma_f32 v[8:9], v[70:71], v[22:23], v[90:91] op_sel:[1,0,0] op_sel_hi:[1,1,1] neg_lo:[1,0,0] neg_hi:[1,0,0]
	v_pk_mul_f32 v[26:27], v[2:3], v[76:77] op_sel:[0,0] op_sel_hi:[1,0]
	v_pk_mul_f32 v[84:85], v[4:5], v[76:77] op_sel:[0,1] op_sel_hi:[1,1]
	v_pk_fma_f32 v[26:27], v[6:7], v[78:79], v[26:27] op_sel:[0,0,0] op_sel_hi:[1,0,1]
	v_pk_fma_f32 v[84:85], v[8:9], v[78:79], v[84:85] op_sel:[0,1,0] op_sel_hi:[1,1,1]
	v_pk_add_f32 v[26:27], v[26:27], v[84:85]
	s_waitcnt lgkmcnt(0)
	v_pk_mul_f32 v[22:23], v[2:3], v[36:37] op_sel:[0,0] op_sel_hi:[1,0]
	ds_read_b128 v[60:63], v20 offset:2304
	v_pk_fma_f32 v[22:23], v[4:5], v[36:37], v[22:23] op_sel:[0,1,0] op_sel_hi:[1,1,1]
	ds_read_b128 v[64:67], v20 offset:10496
	v_pk_fma_f32 v[22:23], v[6:7], v[38:39], v[22:23] op_sel:[0,0,0] op_sel_hi:[1,0,1]
	ds_read_b64 v[80:81], v21 offset:43264
	v_pk_fma_f32 v[22:23], v[8:9], v[38:39], v[22:23] op_sel:[0,1,0] op_sel_hi:[1,1,1]
	ds_read_b128 v[72:75], v20 offset:26880
	v_add_f32_dpp v26, v26, v26 row_ror:12 row_mask:0xf bank_mask:0x5
	ds_read_b128 v[68:71], v20 offset:18688
	v_add_f32_dpp v27, v27, v27 row_ror:4 row_mask:0xf bank_mask:0xa
	ds_read_b128 v[76:79], v20 offset:35072
	v_add_f32_dpp v22, v22, v22 quad_perm:[1,0,3,2] row_mask:0xf bank_mask:0xf
	v_add_f32_dpp v23, v23, v23 quad_perm:[1,0,3,2] row_mask:0xf bank_mask:0xf
	v_pk_mul_f32 v[84:85], v[2:3], v[40:41] op_sel:[0,0] op_sel_hi:[1,0]
	v_pk_mul_f32 v[86:87], v[4:5], v[40:41] op_sel:[0,1] op_sel_hi:[1,1]
	v_mov_b32_dpp v26, v27 quad_perm:[0,1,2,3] row_mask:0xf bank_mask:0xa
	v_add_f32_dpp v22, v22, v22 quad_perm:[2,3,0,1] row_mask:0xf bank_mask:0xf
	v_add_f32_dpp v23, v23, v23 quad_perm:[2,3,0,1] row_mask:0xf bank_mask:0xf
	v_pk_mul_f32 v[88:89], v[6:7], v[42:43] op_sel:[0,0] op_sel_hi:[1,0]
	v_pk_mul_f32 v[90:91], v[8:9], v[42:43] op_sel:[0,1] op_sel_hi:[1,1]
	v_add_f32_dpp v26, v26, v26 row_ror:8 row_mask:0xf bank_mask:0xf
	v_add_f32_dpp v22, v22, v22 row_half_mirror row_mask:0xf bank_mask:0xf
	v_add_f32_dpp v23, v23, v23 row_half_mirror row_mask:0xf bank_mask:0xf
	v_pk_fma_f32 v[84:85], v[48:49], v[56:57], v[84:85] op_sel:[0,0,0] op_sel_hi:[0,1,1]
	v_pk_fma_f32 v[86:87], v[48:49], v[56:57], v[86:87] op_sel:[1,0,0] op_sel_hi:[1,1,1]
	v_add_f32_dpp v26, v26, v26 quad_perm:[1,0,3,2] row_mask:0xf bank_mask:0xf
	v_add_f32_dpp v22, v22, v22 row_mirror row_mask:0xf bank_mask:0xf
	v_add_f32_dpp v23, v23, v23 row_mirror row_mask:0xf bank_mask:0xf
	v_pk_fma_f32 v[88:89], v[50:51], v[56:57], v[88:89] op_sel:[0,0,0] op_sel_hi:[0,1,1]
	v_pk_fma_f32 v[90:91], v[50:51], v[56:57], v[90:91] op_sel:[1,0,0] op_sel_hi:[1,1,1]
	v_add_f32_dpp v26, v26, v26 quad_perm:[2,3,0,1] row_mask:0xf bank_mask:0xf
	v_cndmask_b32_e32 v30, v30, v26, vcc
	v_pk_fma_f32 v[2:3], v[44:45], v[22:23], v[84:85] op_sel:[0,0,0] op_sel_hi:[0,1,1] neg_lo:[1,0,0] neg_hi:[1,0,0]
	v_pk_fma_f32 v[4:5], v[44:45], v[22:23], v[86:87] op_sel:[1,0,0] op_sel_hi:[1,1,1] neg_lo:[1,0,0] neg_hi:[1,0,0]
	v_pk_fma_f32 v[6:7], v[46:47], v[22:23], v[88:89] op_sel:[0,0,0] op_sel_hi:[0,1,1] neg_lo:[1,0,0] neg_hi:[1,0,0]
	v_pk_fma_f32 v[8:9], v[46:47], v[22:23], v[90:91] op_sel:[1,0,0] op_sel_hi:[1,1,1] neg_lo:[1,0,0] neg_hi:[1,0,0]
	v_pk_mul_f32 v[24:25], v[2:3], v[52:53] op_sel:[0,0] op_sel_hi:[1,0]
	v_pk_mul_f32 v[84:85], v[4:5], v[52:53] op_sel:[0,1] op_sel_hi:[1,1]
	v_pk_fma_f32 v[24:25], v[6:7], v[54:55], v[24:25] op_sel:[0,0,0] op_sel_hi:[1,0,1]
	v_pk_fma_f32 v[84:85], v[8:9], v[54:55], v[84:85] op_sel:[0,1,0] op_sel_hi:[1,1,1]
	v_pk_add_f32 v[24:25], v[24:25], v[84:85]
	s_waitcnt lgkmcnt(0)
	v_pk_mul_f32 v[22:23], v[2:3], v[60:61] op_sel:[0,0] op_sel_hi:[1,0]
	ds_read_b128 v[36:39], v20 offset:2560
	v_pk_fma_f32 v[22:23], v[4:5], v[60:61], v[22:23] op_sel:[0,1,0] op_sel_hi:[1,1,1]
	ds_read_b128 v[40:43], v20 offset:10752
	v_pk_fma_f32 v[22:23], v[6:7], v[62:63], v[22:23] op_sel:[0,0,0] op_sel_hi:[1,0,1]
	ds_read_b64 v[56:57], v21 offset:43520
	v_pk_fma_f32 v[22:23], v[8:9], v[62:63], v[22:23] op_sel:[0,1,0] op_sel_hi:[1,1,1]
	ds_read_b128 v[48:51], v20 offset:27136
	v_add_f32_dpp v24, v24, v24 row_ror:12 row_mask:0xf bank_mask:0x5
	ds_read_b128 v[44:47], v20 offset:18944
	v_add_f32_dpp v25, v25, v25 row_ror:4 row_mask:0xf bank_mask:0xa
	ds_read_b128 v[52:55], v20 offset:35328
	v_add_f32_dpp v22, v22, v22 quad_perm:[1,0,3,2] row_mask:0xf bank_mask:0xf
	v_add_f32_dpp v23, v23, v23 quad_perm:[1,0,3,2] row_mask:0xf bank_mask:0xf
	v_pk_mul_f32 v[84:85], v[2:3], v[64:65] op_sel:[0,0] op_sel_hi:[1,0]
	v_pk_mul_f32 v[86:87], v[4:5], v[64:65] op_sel:[0,1] op_sel_hi:[1,1]
	v_mov_b32_dpp v24, v25 quad_perm:[0,1,2,3] row_mask:0xf bank_mask:0xa
	v_add_f32_dpp v22, v22, v22 quad_perm:[2,3,0,1] row_mask:0xf bank_mask:0xf
	v_add_f32_dpp v23, v23, v23 quad_perm:[2,3,0,1] row_mask:0xf bank_mask:0xf
	v_pk_mul_f32 v[88:89], v[6:7], v[66:67] op_sel:[0,0] op_sel_hi:[1,0]
	v_pk_mul_f32 v[90:91], v[8:9], v[66:67] op_sel:[0,1] op_sel_hi:[1,1]
	v_add_f32_dpp v24, v24, v24 row_ror:8 row_mask:0xf bank_mask:0xf
	v_add_f32_dpp v22, v22, v22 row_half_mirror row_mask:0xf bank_mask:0xf
	v_add_f32_dpp v23, v23, v23 row_half_mirror row_mask:0xf bank_mask:0xf
	v_pk_fma_f32 v[84:85], v[72:73], v[80:81], v[84:85] op_sel:[0,0,0] op_sel_hi:[0,1,1]
	v_pk_fma_f32 v[86:87], v[72:73], v[80:81], v[86:87] op_sel:[1,0,0] op_sel_hi:[1,1,1]
	v_add_f32_dpp v24, v24, v24 quad_perm:[1,0,3,2] row_mask:0xf bank_mask:0xf
	v_add_f32_dpp v22, v22, v22 row_mirror row_mask:0xf bank_mask:0xf
	v_add_f32_dpp v23, v23, v23 row_mirror row_mask:0xf bank_mask:0xf
	v_pk_fma_f32 v[88:89], v[74:75], v[80:81], v[88:89] op_sel:[0,0,0] op_sel_hi:[0,1,1]
	v_pk_fma_f32 v[90:91], v[74:75], v[80:81], v[90:91] op_sel:[1,0,0] op_sel_hi:[1,1,1]
	v_add_f32_dpp v24, v24, v24 quad_perm:[2,3,0,1] row_mask:0xf bank_mask:0xf
	v_cndmask_b32_e64 v31, 0, v24, s[0:1]
	v_pk_fma_f32 v[2:3], v[68:69], v[22:23], v[84:85] op_sel:[0,0,0] op_sel_hi:[0,1,1] neg_lo:[1,0,0] neg_hi:[1,0,0]
	v_pk_fma_f32 v[4:5], v[68:69], v[22:23], v[86:87] op_sel:[1,0,0] op_sel_hi:[1,1,1] neg_lo:[1,0,0] neg_hi:[1,0,0]
	v_pk_fma_f32 v[6:7], v[70:71], v[22:23], v[88:89] op_sel:[0,0,0] op_sel_hi:[0,1,1] neg_lo:[1,0,0] neg_hi:[1,0,0]
	v_pk_fma_f32 v[8:9], v[70:71], v[22:23], v[90:91] op_sel:[1,0,0] op_sel_hi:[1,1,1] neg_lo:[1,0,0] neg_hi:[1,0,0]
	v_pk_mul_f32 v[26:27], v[2:3], v[76:77] op_sel:[0,0] op_sel_hi:[1,0]
	v_pk_mul_f32 v[84:85], v[4:5], v[76:77] op_sel:[0,1] op_sel_hi:[1,1]
	v_pk_fma_f32 v[26:27], v[6:7], v[78:79], v[26:27] op_sel:[0,0,0] op_sel_hi:[1,0,1]
	v_pk_fma_f32 v[84:85], v[8:9], v[78:79], v[84:85] op_sel:[0,1,0] op_sel_hi:[1,1,1]
	v_pk_add_f32 v[26:27], v[26:27], v[84:85]
	s_waitcnt lgkmcnt(0)
	v_pk_mul_f32 v[22:23], v[2:3], v[36:37] op_sel:[0,0] op_sel_hi:[1,0]
	ds_read_b128 v[60:63], v20 offset:2816
	v_pk_fma_f32 v[22:23], v[4:5], v[36:37], v[22:23] op_sel:[0,1,0] op_sel_hi:[1,1,1]
	ds_read_b128 v[64:67], v20 offset:11008
	v_pk_fma_f32 v[22:23], v[6:7], v[38:39], v[22:23] op_sel:[0,0,0] op_sel_hi:[1,0,1]
	ds_read_b64 v[80:81], v21 offset:43776
	v_pk_fma_f32 v[22:23], v[8:9], v[38:39], v[22:23] op_sel:[0,1,0] op_sel_hi:[1,1,1]
	ds_read_b128 v[72:75], v20 offset:27392
	v_add_f32_dpp v26, v26, v26 row_ror:12 row_mask:0xf bank_mask:0x5
	ds_read_b128 v[68:71], v20 offset:19200
	v_add_f32_dpp v27, v27, v27 row_ror:4 row_mask:0xf bank_mask:0xa
	ds_read_b128 v[76:79], v20 offset:35584
	v_add_f32_dpp v22, v22, v22 quad_perm:[1,0,3,2] row_mask:0xf bank_mask:0xf
	v_add_f32_dpp v23, v23, v23 quad_perm:[1,0,3,2] row_mask:0xf bank_mask:0xf
	v_pk_mul_f32 v[84:85], v[2:3], v[40:41] op_sel:[0,0] op_sel_hi:[1,0]
	v_pk_mul_f32 v[86:87], v[4:5], v[40:41] op_sel:[0,1] op_sel_hi:[1,1]
	v_mov_b32_dpp v26, v27 quad_perm:[0,1,2,3] row_mask:0xf bank_mask:0xa
	v_add_f32_dpp v22, v22, v22 quad_perm:[2,3,0,1] row_mask:0xf bank_mask:0xf
	v_add_f32_dpp v23, v23, v23 quad_perm:[2,3,0,1] row_mask:0xf bank_mask:0xf
	v_pk_mul_f32 v[88:89], v[6:7], v[42:43] op_sel:[0,0] op_sel_hi:[1,0]
	v_pk_mul_f32 v[90:91], v[8:9], v[42:43] op_sel:[0,1] op_sel_hi:[1,1]
	v_add_f32_dpp v26, v26, v26 row_ror:8 row_mask:0xf bank_mask:0xf
	v_add_f32_dpp v22, v22, v22 row_half_mirror row_mask:0xf bank_mask:0xf
	v_add_f32_dpp v23, v23, v23 row_half_mirror row_mask:0xf bank_mask:0xf
	v_pk_fma_f32 v[84:85], v[48:49], v[56:57], v[84:85] op_sel:[0,0,0] op_sel_hi:[0,1,1]
	v_pk_fma_f32 v[86:87], v[48:49], v[56:57], v[86:87] op_sel:[1,0,0] op_sel_hi:[1,1,1]
	v_add_f32_dpp v26, v26, v26 quad_perm:[1,0,3,2] row_mask:0xf bank_mask:0xf
	v_add_f32_dpp v22, v22, v22 row_mirror row_mask:0xf bank_mask:0xf
	v_add_f32_dpp v23, v23, v23 row_mirror row_mask:0xf bank_mask:0xf
	v_pk_fma_f32 v[88:89], v[50:51], v[56:57], v[88:89] op_sel:[0,0,0] op_sel_hi:[0,1,1]
	v_pk_fma_f32 v[90:91], v[50:51], v[56:57], v[90:91] op_sel:[1,0,0] op_sel_hi:[1,1,1]
	v_add_f32_dpp v26, v26, v26 quad_perm:[2,3,0,1] row_mask:0xf bank_mask:0xf
	v_cndmask_b32_e64 v31, v31, v26, s[6:7]
	v_pk_fma_f32 v[2:3], v[44:45], v[22:23], v[84:85] op_sel:[0,0,0] op_sel_hi:[0,1,1] neg_lo:[1,0,0] neg_hi:[1,0,0]
	v_pk_fma_f32 v[4:5], v[44:45], v[22:23], v[86:87] op_sel:[1,0,0] op_sel_hi:[1,1,1] neg_lo:[1,0,0] neg_hi:[1,0,0]
	v_pk_fma_f32 v[6:7], v[46:47], v[22:23], v[88:89] op_sel:[0,0,0] op_sel_hi:[0,1,1] neg_lo:[1,0,0] neg_hi:[1,0,0]
	v_pk_fma_f32 v[8:9], v[46:47], v[22:23], v[90:91] op_sel:[1,0,0] op_sel_hi:[1,1,1] neg_lo:[1,0,0] neg_hi:[1,0,0]
	v_pk_mul_f32 v[24:25], v[2:3], v[52:53] op_sel:[0,0] op_sel_hi:[1,0]
	v_pk_mul_f32 v[84:85], v[4:5], v[52:53] op_sel:[0,1] op_sel_hi:[1,1]
	v_pk_fma_f32 v[24:25], v[6:7], v[54:55], v[24:25] op_sel:[0,0,0] op_sel_hi:[1,0,1]
	v_pk_fma_f32 v[84:85], v[8:9], v[54:55], v[84:85] op_sel:[0,1,0] op_sel_hi:[1,1,1]
	v_pk_add_f32 v[24:25], v[24:25], v[84:85]
	s_waitcnt lgkmcnt(0)
	v_pk_mul_f32 v[22:23], v[2:3], v[60:61] op_sel:[0,0] op_sel_hi:[1,0]
	ds_read_b128 v[36:39], v20 offset:3072
	v_pk_fma_f32 v[22:23], v[4:5], v[60:61], v[22:23] op_sel:[0,1,0] op_sel_hi:[1,1,1]
	ds_read_b128 v[40:43], v20 offset:11264
	v_pk_fma_f32 v[22:23], v[6:7], v[62:63], v[22:23] op_sel:[0,0,0] op_sel_hi:[1,0,1]
	ds_read_b64 v[56:57], v21 offset:44032
	v_pk_fma_f32 v[22:23], v[8:9], v[62:63], v[22:23] op_sel:[0,1,0] op_sel_hi:[1,1,1]
	ds_read_b128 v[48:51], v20 offset:27648
	v_add_f32_dpp v24, v24, v24 row_ror:12 row_mask:0xf bank_mask:0x5
	ds_read_b128 v[44:47], v20 offset:19456
	v_add_f32_dpp v25, v25, v25 row_ror:4 row_mask:0xf bank_mask:0xa
	ds_read_b128 v[52:55], v20 offset:35840
	v_add_f32_dpp v22, v22, v22 quad_perm:[1,0,3,2] row_mask:0xf bank_mask:0xf
	v_add_f32_dpp v23, v23, v23 quad_perm:[1,0,3,2] row_mask:0xf bank_mask:0xf
	v_pk_mul_f32 v[84:85], v[2:3], v[64:65] op_sel:[0,0] op_sel_hi:[1,0]
	v_pk_mul_f32 v[86:87], v[4:5], v[64:65] op_sel:[0,1] op_sel_hi:[1,1]
	v_mov_b32_dpp v24, v25 quad_perm:[0,1,2,3] row_mask:0xf bank_mask:0xa
	v_add_f32_dpp v22, v22, v22 quad_perm:[2,3,0,1] row_mask:0xf bank_mask:0xf
	v_add_f32_dpp v23, v23, v23 quad_perm:[2,3,0,1] row_mask:0xf bank_mask:0xf
	v_pk_mul_f32 v[88:89], v[6:7], v[66:67] op_sel:[0,0] op_sel_hi:[1,0]
	v_pk_mul_f32 v[90:91], v[8:9], v[66:67] op_sel:[0,1] op_sel_hi:[1,1]
	v_add_f32_dpp v24, v24, v24 row_ror:8 row_mask:0xf bank_mask:0xf
	v_add_f32_dpp v22, v22, v22 row_half_mirror row_mask:0xf bank_mask:0xf
	v_add_f32_dpp v23, v23, v23 row_half_mirror row_mask:0xf bank_mask:0xf
	v_pk_fma_f32 v[84:85], v[72:73], v[80:81], v[84:85] op_sel:[0,0,0] op_sel_hi:[0,1,1]
	v_pk_fma_f32 v[86:87], v[72:73], v[80:81], v[86:87] op_sel:[1,0,0] op_sel_hi:[1,1,1]
	v_add_f32_dpp v24, v24, v24 quad_perm:[1,0,3,2] row_mask:0xf bank_mask:0xf
	v_add_f32_dpp v22, v22, v22 row_mirror row_mask:0xf bank_mask:0xf
	v_add_f32_dpp v23, v23, v23 row_mirror row_mask:0xf bank_mask:0xf
	v_pk_fma_f32 v[88:89], v[74:75], v[80:81], v[88:89] op_sel:[0,0,0] op_sel_hi:[0,1,1]
	v_pk_fma_f32 v[90:91], v[74:75], v[80:81], v[90:91] op_sel:[1,0,0] op_sel_hi:[1,1,1]
	v_add_f32_dpp v24, v24, v24 quad_perm:[2,3,0,1] row_mask:0xf bank_mask:0xf
	v_cndmask_b32_e64 v31, v31, v24, s[8:9]
	v_pk_fma_f32 v[2:3], v[68:69], v[22:23], v[84:85] op_sel:[0,0,0] op_sel_hi:[0,1,1] neg_lo:[1,0,0] neg_hi:[1,0,0]
	v_pk_fma_f32 v[4:5], v[68:69], v[22:23], v[86:87] op_sel:[1,0,0] op_sel_hi:[1,1,1] neg_lo:[1,0,0] neg_hi:[1,0,0]
	v_pk_fma_f32 v[6:7], v[70:71], v[22:23], v[88:89] op_sel:[0,0,0] op_sel_hi:[0,1,1] neg_lo:[1,0,0] neg_hi:[1,0,0]
	v_pk_fma_f32 v[8:9], v[70:71], v[22:23], v[90:91] op_sel:[1,0,0] op_sel_hi:[1,1,1] neg_lo:[1,0,0] neg_hi:[1,0,0]
	v_pk_mul_f32 v[26:27], v[2:3], v[76:77] op_sel:[0,0] op_sel_hi:[1,0]
	v_pk_mul_f32 v[84:85], v[4:5], v[76:77] op_sel:[0,1] op_sel_hi:[1,1]
	v_pk_fma_f32 v[26:27], v[6:7], v[78:79], v[26:27] op_sel:[0,0,0] op_sel_hi:[1,0,1]
	v_pk_fma_f32 v[84:85], v[8:9], v[78:79], v[84:85] op_sel:[0,1,0] op_sel_hi:[1,1,1]
	v_pk_add_f32 v[26:27], v[26:27], v[84:85]
	s_waitcnt lgkmcnt(0)
	v_pk_mul_f32 v[22:23], v[2:3], v[36:37] op_sel:[0,0] op_sel_hi:[1,0]
	ds_read_b128 v[60:63], v20 offset:3328
	v_pk_fma_f32 v[22:23], v[4:5], v[36:37], v[22:23] op_sel:[0,1,0] op_sel_hi:[1,1,1]
	ds_read_b128 v[64:67], v20 offset:11520
	v_pk_fma_f32 v[22:23], v[6:7], v[38:39], v[22:23] op_sel:[0,0,0] op_sel_hi:[1,0,1]
	ds_read_b64 v[80:81], v21 offset:44288
	v_pk_fma_f32 v[22:23], v[8:9], v[38:39], v[22:23] op_sel:[0,1,0] op_sel_hi:[1,1,1]
	ds_read_b128 v[72:75], v20 offset:27904
	v_add_f32_dpp v26, v26, v26 row_ror:12 row_mask:0xf bank_mask:0x5
	ds_read_b128 v[68:71], v20 offset:19712
	v_add_f32_dpp v27, v27, v27 row_ror:4 row_mask:0xf bank_mask:0xa
	ds_read_b128 v[76:79], v20 offset:36096
	v_add_f32_dpp v22, v22, v22 quad_perm:[1,0,3,2] row_mask:0xf bank_mask:0xf
	v_add_f32_dpp v23, v23, v23 quad_perm:[1,0,3,2] row_mask:0xf bank_mask:0xf
	v_pk_mul_f32 v[84:85], v[2:3], v[40:41] op_sel:[0,0] op_sel_hi:[1,0]
	v_pk_mul_f32 v[86:87], v[4:5], v[40:41] op_sel:[0,1] op_sel_hi:[1,1]
	v_mov_b32_dpp v26, v27 quad_perm:[0,1,2,3] row_mask:0xf bank_mask:0xa
	v_add_f32_dpp v22, v22, v22 quad_perm:[2,3,0,1] row_mask:0xf bank_mask:0xf
	v_add_f32_dpp v23, v23, v23 quad_perm:[2,3,0,1] row_mask:0xf bank_mask:0xf
	v_pk_mul_f32 v[88:89], v[6:7], v[42:43] op_sel:[0,0] op_sel_hi:[1,0]
	v_pk_mul_f32 v[90:91], v[8:9], v[42:43] op_sel:[0,1] op_sel_hi:[1,1]
	v_add_f32_dpp v26, v26, v26 row_ror:8 row_mask:0xf bank_mask:0xf
	v_add_f32_dpp v22, v22, v22 row_half_mirror row_mask:0xf bank_mask:0xf
	v_add_f32_dpp v23, v23, v23 row_half_mirror row_mask:0xf bank_mask:0xf
	v_pk_fma_f32 v[84:85], v[48:49], v[56:57], v[84:85] op_sel:[0,0,0] op_sel_hi:[0,1,1]
	v_pk_fma_f32 v[86:87], v[48:49], v[56:57], v[86:87] op_sel:[1,0,0] op_sel_hi:[1,1,1]
	v_add_f32_dpp v26, v26, v26 quad_perm:[1,0,3,2] row_mask:0xf bank_mask:0xf
	v_add_f32_dpp v22, v22, v22 row_mirror row_mask:0xf bank_mask:0xf
	v_add_f32_dpp v23, v23, v23 row_mirror row_mask:0xf bank_mask:0xf
	v_pk_fma_f32 v[88:89], v[50:51], v[56:57], v[88:89] op_sel:[0,0,0] op_sel_hi:[0,1,1]
	v_pk_fma_f32 v[90:91], v[50:51], v[56:57], v[90:91] op_sel:[1,0,0] op_sel_hi:[1,1,1]
	v_add_f32_dpp v26, v26, v26 quad_perm:[2,3,0,1] row_mask:0xf bank_mask:0xf
	v_cndmask_b32_e64 v31, v31, v26, s[10:11]
	v_pk_fma_f32 v[2:3], v[44:45], v[22:23], v[84:85] op_sel:[0,0,0] op_sel_hi:[0,1,1] neg_lo:[1,0,0] neg_hi:[1,0,0]
	v_pk_fma_f32 v[4:5], v[44:45], v[22:23], v[86:87] op_sel:[1,0,0] op_sel_hi:[1,1,1] neg_lo:[1,0,0] neg_hi:[1,0,0]
	v_pk_fma_f32 v[6:7], v[46:47], v[22:23], v[88:89] op_sel:[0,0,0] op_sel_hi:[0,1,1] neg_lo:[1,0,0] neg_hi:[1,0,0]
	v_pk_fma_f32 v[8:9], v[46:47], v[22:23], v[90:91] op_sel:[1,0,0] op_sel_hi:[1,1,1] neg_lo:[1,0,0] neg_hi:[1,0,0]
	v_pk_mul_f32 v[24:25], v[2:3], v[52:53] op_sel:[0,0] op_sel_hi:[1,0]
	v_pk_mul_f32 v[84:85], v[4:5], v[52:53] op_sel:[0,1] op_sel_hi:[1,1]
	v_pk_fma_f32 v[24:25], v[6:7], v[54:55], v[24:25] op_sel:[0,0,0] op_sel_hi:[1,0,1]
	v_pk_fma_f32 v[84:85], v[8:9], v[54:55], v[84:85] op_sel:[0,1,0] op_sel_hi:[1,1,1]
	v_pk_add_f32 v[24:25], v[24:25], v[84:85]
	s_waitcnt lgkmcnt(0)
	v_pk_mul_f32 v[22:23], v[2:3], v[60:61] op_sel:[0,0] op_sel_hi:[1,0]
	ds_read_b128 v[36:39], v20 offset:3584
	v_pk_fma_f32 v[22:23], v[4:5], v[60:61], v[22:23] op_sel:[0,1,0] op_sel_hi:[1,1,1]
	ds_read_b128 v[40:43], v20 offset:11776
	v_pk_fma_f32 v[22:23], v[6:7], v[62:63], v[22:23] op_sel:[0,0,0] op_sel_hi:[1,0,1]
	ds_read_b64 v[56:57], v21 offset:44544
	v_pk_fma_f32 v[22:23], v[8:9], v[62:63], v[22:23] op_sel:[0,1,0] op_sel_hi:[1,1,1]
	ds_read_b128 v[48:51], v20 offset:28160
	v_add_f32_dpp v24, v24, v24 row_ror:12 row_mask:0xf bank_mask:0x5
	ds_read_b128 v[44:47], v20 offset:19968
	v_add_f32_dpp v25, v25, v25 row_ror:4 row_mask:0xf bank_mask:0xa
	ds_read_b128 v[52:55], v20 offset:36352
	v_add_f32_dpp v22, v22, v22 quad_perm:[1,0,3,2] row_mask:0xf bank_mask:0xf
	v_add_f32_dpp v23, v23, v23 quad_perm:[1,0,3,2] row_mask:0xf bank_mask:0xf
	v_pk_mul_f32 v[84:85], v[2:3], v[64:65] op_sel:[0,0] op_sel_hi:[1,0]
	v_pk_mul_f32 v[86:87], v[4:5], v[64:65] op_sel:[0,1] op_sel_hi:[1,1]
	v_mov_b32_dpp v24, v25 quad_perm:[0,1,2,3] row_mask:0xf bank_mask:0xa
	v_add_f32_dpp v22, v22, v22 quad_perm:[2,3,0,1] row_mask:0xf bank_mask:0xf
	v_add_f32_dpp v23, v23, v23 quad_perm:[2,3,0,1] row_mask:0xf bank_mask:0xf
	v_pk_mul_f32 v[88:89], v[6:7], v[66:67] op_sel:[0,0] op_sel_hi:[1,0]
	v_pk_mul_f32 v[90:91], v[8:9], v[66:67] op_sel:[0,1] op_sel_hi:[1,1]
	v_add_f32_dpp v24, v24, v24 row_ror:8 row_mask:0xf bank_mask:0xf
	v_add_f32_dpp v22, v22, v22 row_half_mirror row_mask:0xf bank_mask:0xf
	v_add_f32_dpp v23, v23, v23 row_half_mirror row_mask:0xf bank_mask:0xf
	v_pk_fma_f32 v[84:85], v[72:73], v[80:81], v[84:85] op_sel:[0,0,0] op_sel_hi:[0,1,1]
	v_pk_fma_f32 v[86:87], v[72:73], v[80:81], v[86:87] op_sel:[1,0,0] op_sel_hi:[1,1,1]
	v_add_f32_dpp v24, v24, v24 quad_perm:[1,0,3,2] row_mask:0xf bank_mask:0xf
	v_add_f32_dpp v22, v22, v22 row_mirror row_mask:0xf bank_mask:0xf
	v_add_f32_dpp v23, v23, v23 row_mirror row_mask:0xf bank_mask:0xf
	v_pk_fma_f32 v[88:89], v[74:75], v[80:81], v[88:89] op_sel:[0,0,0] op_sel_hi:[0,1,1]
	v_pk_fma_f32 v[90:91], v[74:75], v[80:81], v[90:91] op_sel:[1,0,0] op_sel_hi:[1,1,1]
	v_add_f32_dpp v24, v24, v24 quad_perm:[2,3,0,1] row_mask:0xf bank_mask:0xf
	v_cndmask_b32_e64 v31, v31, v24, s[12:13]
	v_pk_fma_f32 v[2:3], v[68:69], v[22:23], v[84:85] op_sel:[0,0,0] op_sel_hi:[0,1,1] neg_lo:[1,0,0] neg_hi:[1,0,0]
	v_pk_fma_f32 v[4:5], v[68:69], v[22:23], v[86:87] op_sel:[1,0,0] op_sel_hi:[1,1,1] neg_lo:[1,0,0] neg_hi:[1,0,0]
	v_pk_fma_f32 v[6:7], v[70:71], v[22:23], v[88:89] op_sel:[0,0,0] op_sel_hi:[0,1,1] neg_lo:[1,0,0] neg_hi:[1,0,0]
	v_pk_fma_f32 v[8:9], v[70:71], v[22:23], v[90:91] op_sel:[1,0,0] op_sel_hi:[1,1,1] neg_lo:[1,0,0] neg_hi:[1,0,0]
	v_pk_mul_f32 v[26:27], v[2:3], v[76:77] op_sel:[0,0] op_sel_hi:[1,0]
	v_pk_mul_f32 v[84:85], v[4:5], v[76:77] op_sel:[0,1] op_sel_hi:[1,1]
	v_pk_fma_f32 v[26:27], v[6:7], v[78:79], v[26:27] op_sel:[0,0,0] op_sel_hi:[1,0,1]
	v_pk_fma_f32 v[84:85], v[8:9], v[78:79], v[84:85] op_sel:[0,1,0] op_sel_hi:[1,1,1]
	v_pk_add_f32 v[26:27], v[26:27], v[84:85]
	s_waitcnt lgkmcnt(0)
	v_pk_mul_f32 v[22:23], v[2:3], v[36:37] op_sel:[0,0] op_sel_hi:[1,0]
	ds_read_b128 v[60:63], v20 offset:3840
	v_pk_fma_f32 v[22:23], v[4:5], v[36:37], v[22:23] op_sel:[0,1,0] op_sel_hi:[1,1,1]
	ds_read_b128 v[64:67], v20 offset:12032
	v_pk_fma_f32 v[22:23], v[6:7], v[38:39], v[22:23] op_sel:[0,0,0] op_sel_hi:[1,0,1]
	ds_read_b64 v[80:81], v21 offset:44800
	v_pk_fma_f32 v[22:23], v[8:9], v[38:39], v[22:23] op_sel:[0,1,0] op_sel_hi:[1,1,1]
	ds_read_b128 v[72:75], v20 offset:28416
	v_add_f32_dpp v26, v26, v26 row_ror:12 row_mask:0xf bank_mask:0x5
	ds_read_b128 v[68:71], v20 offset:20224
	v_add_f32_dpp v27, v27, v27 row_ror:4 row_mask:0xf bank_mask:0xa
	ds_read_b128 v[76:79], v20 offset:36608
	v_add_f32_dpp v22, v22, v22 quad_perm:[1,0,3,2] row_mask:0xf bank_mask:0xf
	v_add_f32_dpp v23, v23, v23 quad_perm:[1,0,3,2] row_mask:0xf bank_mask:0xf
	v_pk_mul_f32 v[84:85], v[2:3], v[40:41] op_sel:[0,0] op_sel_hi:[1,0]
	v_pk_mul_f32 v[86:87], v[4:5], v[40:41] op_sel:[0,1] op_sel_hi:[1,1]
	v_mov_b32_dpp v26, v27 quad_perm:[0,1,2,3] row_mask:0xf bank_mask:0xa
	v_add_f32_dpp v22, v22, v22 quad_perm:[2,3,0,1] row_mask:0xf bank_mask:0xf
	v_add_f32_dpp v23, v23, v23 quad_perm:[2,3,0,1] row_mask:0xf bank_mask:0xf
	v_pk_mul_f32 v[88:89], v[6:7], v[42:43] op_sel:[0,0] op_sel_hi:[1,0]
	v_pk_mul_f32 v[90:91], v[8:9], v[42:43] op_sel:[0,1] op_sel_hi:[1,1]
	v_add_f32_dpp v26, v26, v26 row_ror:8 row_mask:0xf bank_mask:0xf
	v_add_f32_dpp v22, v22, v22 row_half_mirror row_mask:0xf bank_mask:0xf
	v_add_f32_dpp v23, v23, v23 row_half_mirror row_mask:0xf bank_mask:0xf
	v_pk_fma_f32 v[84:85], v[48:49], v[56:57], v[84:85] op_sel:[0,0,0] op_sel_hi:[0,1,1]
	v_pk_fma_f32 v[86:87], v[48:49], v[56:57], v[86:87] op_sel:[1,0,0] op_sel_hi:[1,1,1]
	v_add_f32_dpp v26, v26, v26 quad_perm:[1,0,3,2] row_mask:0xf bank_mask:0xf
	v_add_f32_dpp v22, v22, v22 row_mirror row_mask:0xf bank_mask:0xf
	v_add_f32_dpp v23, v23, v23 row_mirror row_mask:0xf bank_mask:0xf
	v_pk_fma_f32 v[88:89], v[50:51], v[56:57], v[88:89] op_sel:[0,0,0] op_sel_hi:[0,1,1]
	v_pk_fma_f32 v[90:91], v[50:51], v[56:57], v[90:91] op_sel:[1,0,0] op_sel_hi:[1,1,1]
	v_add_f32_dpp v26, v26, v26 quad_perm:[2,3,0,1] row_mask:0xf bank_mask:0xf
	v_cndmask_b32_e64 v31, v31, v26, s[14:15]
	v_pk_fma_f32 v[2:3], v[44:45], v[22:23], v[84:85] op_sel:[0,0,0] op_sel_hi:[0,1,1] neg_lo:[1,0,0] neg_hi:[1,0,0]
	v_pk_fma_f32 v[4:5], v[44:45], v[22:23], v[86:87] op_sel:[1,0,0] op_sel_hi:[1,1,1] neg_lo:[1,0,0] neg_hi:[1,0,0]
	v_pk_fma_f32 v[6:7], v[46:47], v[22:23], v[88:89] op_sel:[0,0,0] op_sel_hi:[0,1,1] neg_lo:[1,0,0] neg_hi:[1,0,0]
	v_pk_fma_f32 v[8:9], v[46:47], v[22:23], v[90:91] op_sel:[1,0,0] op_sel_hi:[1,1,1] neg_lo:[1,0,0] neg_hi:[1,0,0]
	v_pk_mul_f32 v[24:25], v[2:3], v[52:53] op_sel:[0,0] op_sel_hi:[1,0]
	v_pk_mul_f32 v[84:85], v[4:5], v[52:53] op_sel:[0,1] op_sel_hi:[1,1]
	v_pk_fma_f32 v[24:25], v[6:7], v[54:55], v[24:25] op_sel:[0,0,0] op_sel_hi:[1,0,1]
	v_pk_fma_f32 v[84:85], v[8:9], v[54:55], v[84:85] op_sel:[0,1,0] op_sel_hi:[1,1,1]
	v_pk_add_f32 v[24:25], v[24:25], v[84:85]
	s_waitcnt lgkmcnt(0)
	v_pk_mul_f32 v[22:23], v[2:3], v[60:61] op_sel:[0,0] op_sel_hi:[1,0]
	ds_read_b128 v[36:39], v20 offset:4096
	v_pk_fma_f32 v[22:23], v[4:5], v[60:61], v[22:23] op_sel:[0,1,0] op_sel_hi:[1,1,1]
	ds_read_b128 v[40:43], v20 offset:12288
	v_pk_fma_f32 v[22:23], v[6:7], v[62:63], v[22:23] op_sel:[0,0,0] op_sel_hi:[1,0,1]
	ds_read_b64 v[56:57], v21 offset:45056
	v_pk_fma_f32 v[22:23], v[8:9], v[62:63], v[22:23] op_sel:[0,1,0] op_sel_hi:[1,1,1]
	ds_read_b128 v[48:51], v20 offset:28672
	v_add_f32_dpp v24, v24, v24 row_ror:12 row_mask:0xf bank_mask:0x5
	ds_read_b128 v[44:47], v20 offset:20480
	v_add_f32_dpp v25, v25, v25 row_ror:4 row_mask:0xf bank_mask:0xa
	ds_read_b128 v[52:55], v20 offset:36864
	v_add_f32_dpp v22, v22, v22 quad_perm:[1,0,3,2] row_mask:0xf bank_mask:0xf
	v_add_f32_dpp v23, v23, v23 quad_perm:[1,0,3,2] row_mask:0xf bank_mask:0xf
	v_pk_mul_f32 v[84:85], v[2:3], v[64:65] op_sel:[0,0] op_sel_hi:[1,0]
	v_pk_mul_f32 v[86:87], v[4:5], v[64:65] op_sel:[0,1] op_sel_hi:[1,1]
	v_mov_b32_dpp v24, v25 quad_perm:[0,1,2,3] row_mask:0xf bank_mask:0xa
	v_add_f32_dpp v22, v22, v22 quad_perm:[2,3,0,1] row_mask:0xf bank_mask:0xf
	v_add_f32_dpp v23, v23, v23 quad_perm:[2,3,0,1] row_mask:0xf bank_mask:0xf
	v_pk_mul_f32 v[88:89], v[6:7], v[66:67] op_sel:[0,0] op_sel_hi:[1,0]
	v_pk_mul_f32 v[90:91], v[8:9], v[66:67] op_sel:[0,1] op_sel_hi:[1,1]
	v_add_f32_dpp v24, v24, v24 row_ror:8 row_mask:0xf bank_mask:0xf
	v_add_f32_dpp v22, v22, v22 row_half_mirror row_mask:0xf bank_mask:0xf
	v_add_f32_dpp v23, v23, v23 row_half_mirror row_mask:0xf bank_mask:0xf
	v_pk_fma_f32 v[84:85], v[72:73], v[80:81], v[84:85] op_sel:[0,0,0] op_sel_hi:[0,1,1]
	v_pk_fma_f32 v[86:87], v[72:73], v[80:81], v[86:87] op_sel:[1,0,0] op_sel_hi:[1,1,1]
	v_add_f32_dpp v24, v24, v24 quad_perm:[1,0,3,2] row_mask:0xf bank_mask:0xf
	v_add_f32_dpp v22, v22, v22 row_mirror row_mask:0xf bank_mask:0xf
	v_add_f32_dpp v23, v23, v23 row_mirror row_mask:0xf bank_mask:0xf
	v_pk_fma_f32 v[88:89], v[74:75], v[80:81], v[88:89] op_sel:[0,0,0] op_sel_hi:[0,1,1]
	v_pk_fma_f32 v[90:91], v[74:75], v[80:81], v[90:91] op_sel:[1,0,0] op_sel_hi:[1,1,1]
	v_add_f32_dpp v24, v24, v24 quad_perm:[2,3,0,1] row_mask:0xf bank_mask:0xf
	v_cndmask_b32_e64 v31, v31, v24, s[16:17]
	v_pk_fma_f32 v[2:3], v[68:69], v[22:23], v[84:85] op_sel:[0,0,0] op_sel_hi:[0,1,1] neg_lo:[1,0,0] neg_hi:[1,0,0]
	v_pk_fma_f32 v[4:5], v[68:69], v[22:23], v[86:87] op_sel:[1,0,0] op_sel_hi:[1,1,1] neg_lo:[1,0,0] neg_hi:[1,0,0]
	v_pk_fma_f32 v[6:7], v[70:71], v[22:23], v[88:89] op_sel:[0,0,0] op_sel_hi:[0,1,1] neg_lo:[1,0,0] neg_hi:[1,0,0]
	v_pk_fma_f32 v[8:9], v[70:71], v[22:23], v[90:91] op_sel:[1,0,0] op_sel_hi:[1,1,1] neg_lo:[1,0,0] neg_hi:[1,0,0]
	v_pk_mul_f32 v[26:27], v[2:3], v[76:77] op_sel:[0,0] op_sel_hi:[1,0]
	v_pk_mul_f32 v[84:85], v[4:5], v[76:77] op_sel:[0,1] op_sel_hi:[1,1]
	v_pk_fma_f32 v[26:27], v[6:7], v[78:79], v[26:27] op_sel:[0,0,0] op_sel_hi:[1,0,1]
	v_pk_fma_f32 v[84:85], v[8:9], v[78:79], v[84:85] op_sel:[0,1,0] op_sel_hi:[1,1,1]
	v_pk_add_f32 v[26:27], v[26:27], v[84:85]
	s_waitcnt lgkmcnt(0)
	v_pk_mul_f32 v[22:23], v[2:3], v[36:37] op_sel:[0,0] op_sel_hi:[1,0]
	ds_read_b128 v[60:63], v20 offset:4352
	v_pk_fma_f32 v[22:23], v[4:5], v[36:37], v[22:23] op_sel:[0,1,0] op_sel_hi:[1,1,1]
	ds_read_b128 v[64:67], v20 offset:12544
	v_pk_fma_f32 v[22:23], v[6:7], v[38:39], v[22:23] op_sel:[0,0,0] op_sel_hi:[1,0,1]
	ds_read_b64 v[80:81], v21 offset:45312
	v_pk_fma_f32 v[22:23], v[8:9], v[38:39], v[22:23] op_sel:[0,1,0] op_sel_hi:[1,1,1]
	ds_read_b128 v[72:75], v20 offset:28928
	v_add_f32_dpp v26, v26, v26 row_ror:12 row_mask:0xf bank_mask:0x5
	ds_read_b128 v[68:71], v20 offset:20736
	v_add_f32_dpp v27, v27, v27 row_ror:4 row_mask:0xf bank_mask:0xa
	ds_read_b128 v[76:79], v20 offset:37120
	v_add_f32_dpp v22, v22, v22 quad_perm:[1,0,3,2] row_mask:0xf bank_mask:0xf
	v_add_f32_dpp v23, v23, v23 quad_perm:[1,0,3,2] row_mask:0xf bank_mask:0xf
	v_pk_mul_f32 v[84:85], v[2:3], v[40:41] op_sel:[0,0] op_sel_hi:[1,0]
	v_pk_mul_f32 v[86:87], v[4:5], v[40:41] op_sel:[0,1] op_sel_hi:[1,1]
	v_mov_b32_dpp v26, v27 quad_perm:[0,1,2,3] row_mask:0xf bank_mask:0xa
	v_add_f32_dpp v22, v22, v22 quad_perm:[2,3,0,1] row_mask:0xf bank_mask:0xf
	v_add_f32_dpp v23, v23, v23 quad_perm:[2,3,0,1] row_mask:0xf bank_mask:0xf
	v_pk_mul_f32 v[88:89], v[6:7], v[42:43] op_sel:[0,0] op_sel_hi:[1,0]
	v_pk_mul_f32 v[90:91], v[8:9], v[42:43] op_sel:[0,1] op_sel_hi:[1,1]
	v_add_f32_dpp v26, v26, v26 row_ror:8 row_mask:0xf bank_mask:0xf
	v_add_f32_dpp v22, v22, v22 row_half_mirror row_mask:0xf bank_mask:0xf
	v_add_f32_dpp v23, v23, v23 row_half_mirror row_mask:0xf bank_mask:0xf
	v_pk_fma_f32 v[84:85], v[48:49], v[56:57], v[84:85] op_sel:[0,0,0] op_sel_hi:[0,1,1]
	v_pk_fma_f32 v[86:87], v[48:49], v[56:57], v[86:87] op_sel:[1,0,0] op_sel_hi:[1,1,1]
	v_add_f32_dpp v26, v26, v26 quad_perm:[1,0,3,2] row_mask:0xf bank_mask:0xf
	v_add_f32_dpp v22, v22, v22 row_mirror row_mask:0xf bank_mask:0xf
	v_add_f32_dpp v23, v23, v23 row_mirror row_mask:0xf bank_mask:0xf
	v_pk_fma_f32 v[88:89], v[50:51], v[56:57], v[88:89] op_sel:[0,0,0] op_sel_hi:[0,1,1]
	v_pk_fma_f32 v[90:91], v[50:51], v[56:57], v[90:91] op_sel:[1,0,0] op_sel_hi:[1,1,1]
	v_add_f32_dpp v26, v26, v26 quad_perm:[2,3,0,1] row_mask:0xf bank_mask:0xf
	v_cndmask_b32_e32 v31, v31, v26, vcc
	v_pk_fma_f32 v[2:3], v[44:45], v[22:23], v[84:85] op_sel:[0,0,0] op_sel_hi:[0,1,1] neg_lo:[1,0,0] neg_hi:[1,0,0]
	v_pk_fma_f32 v[4:5], v[44:45], v[22:23], v[86:87] op_sel:[1,0,0] op_sel_hi:[1,1,1] neg_lo:[1,0,0] neg_hi:[1,0,0]
	v_pk_fma_f32 v[6:7], v[46:47], v[22:23], v[88:89] op_sel:[0,0,0] op_sel_hi:[0,1,1] neg_lo:[1,0,0] neg_hi:[1,0,0]
	v_pk_fma_f32 v[8:9], v[46:47], v[22:23], v[90:91] op_sel:[1,0,0] op_sel_hi:[1,1,1] neg_lo:[1,0,0] neg_hi:[1,0,0]
	v_pk_mul_f32 v[24:25], v[2:3], v[52:53] op_sel:[0,0] op_sel_hi:[1,0]
	v_pk_mul_f32 v[84:85], v[4:5], v[52:53] op_sel:[0,1] op_sel_hi:[1,1]
	v_pk_fma_f32 v[24:25], v[6:7], v[54:55], v[24:25] op_sel:[0,0,0] op_sel_hi:[1,0,1]
	v_pk_fma_f32 v[84:85], v[8:9], v[54:55], v[84:85] op_sel:[0,1,0] op_sel_hi:[1,1,1]
	v_pk_add_f32 v[24:25], v[24:25], v[84:85]
	s_waitcnt lgkmcnt(0)
	v_pk_mul_f32 v[22:23], v[2:3], v[60:61] op_sel:[0,0] op_sel_hi:[1,0]
	ds_read_b128 v[36:39], v20 offset:4608
	v_pk_fma_f32 v[22:23], v[4:5], v[60:61], v[22:23] op_sel:[0,1,0] op_sel_hi:[1,1,1]
	ds_read_b128 v[40:43], v20 offset:12800
	v_pk_fma_f32 v[22:23], v[6:7], v[62:63], v[22:23] op_sel:[0,0,0] op_sel_hi:[1,0,1]
	ds_read_b64 v[56:57], v21 offset:45568
	v_pk_fma_f32 v[22:23], v[8:9], v[62:63], v[22:23] op_sel:[0,1,0] op_sel_hi:[1,1,1]
	ds_read_b128 v[48:51], v20 offset:29184
	v_add_f32_dpp v24, v24, v24 row_ror:12 row_mask:0xf bank_mask:0x5
	ds_read_b128 v[44:47], v20 offset:20992
	v_add_f32_dpp v25, v25, v25 row_ror:4 row_mask:0xf bank_mask:0xa
	ds_read_b128 v[52:55], v20 offset:37376
	v_add_f32_dpp v22, v22, v22 quad_perm:[1,0,3,2] row_mask:0xf bank_mask:0xf
	v_add_f32_dpp v23, v23, v23 quad_perm:[1,0,3,2] row_mask:0xf bank_mask:0xf
	v_pk_mul_f32 v[84:85], v[2:3], v[64:65] op_sel:[0,0] op_sel_hi:[1,0]
	v_pk_mul_f32 v[86:87], v[4:5], v[64:65] op_sel:[0,1] op_sel_hi:[1,1]
	v_mov_b32_dpp v24, v25 quad_perm:[0,1,2,3] row_mask:0xf bank_mask:0xa
	v_add_f32_dpp v22, v22, v22 quad_perm:[2,3,0,1] row_mask:0xf bank_mask:0xf
	v_add_f32_dpp v23, v23, v23 quad_perm:[2,3,0,1] row_mask:0xf bank_mask:0xf
	v_pk_mul_f32 v[88:89], v[6:7], v[66:67] op_sel:[0,0] op_sel_hi:[1,0]
	v_pk_mul_f32 v[90:91], v[8:9], v[66:67] op_sel:[0,1] op_sel_hi:[1,1]
	v_add_f32_dpp v24, v24, v24 row_ror:8 row_mask:0xf bank_mask:0xf
	v_add_f32_dpp v22, v22, v22 row_half_mirror row_mask:0xf bank_mask:0xf
	v_add_f32_dpp v23, v23, v23 row_half_mirror row_mask:0xf bank_mask:0xf
	v_pk_fma_f32 v[84:85], v[72:73], v[80:81], v[84:85] op_sel:[0,0,0] op_sel_hi:[0,1,1]
	v_pk_fma_f32 v[86:87], v[72:73], v[80:81], v[86:87] op_sel:[1,0,0] op_sel_hi:[1,1,1]
	v_add_f32_dpp v24, v24, v24 quad_perm:[1,0,3,2] row_mask:0xf bank_mask:0xf
	v_add_f32_dpp v22, v22, v22 row_mirror row_mask:0xf bank_mask:0xf
	v_add_f32_dpp v23, v23, v23 row_mirror row_mask:0xf bank_mask:0xf
	v_pk_fma_f32 v[88:89], v[74:75], v[80:81], v[88:89] op_sel:[0,0,0] op_sel_hi:[0,1,1]
	v_pk_fma_f32 v[90:91], v[74:75], v[80:81], v[90:91] op_sel:[1,0,0] op_sel_hi:[1,1,1]
	v_add_f32_dpp v24, v24, v24 quad_perm:[2,3,0,1] row_mask:0xf bank_mask:0xf
	v_cndmask_b32_e64 v32, 0, v24, s[0:1]
	v_pk_fma_f32 v[2:3], v[68:69], v[22:23], v[84:85] op_sel:[0,0,0] op_sel_hi:[0,1,1] neg_lo:[1,0,0] neg_hi:[1,0,0]
	v_pk_fma_f32 v[4:5], v[68:69], v[22:23], v[86:87] op_sel:[1,0,0] op_sel_hi:[1,1,1] neg_lo:[1,0,0] neg_hi:[1,0,0]
	v_pk_fma_f32 v[6:7], v[70:71], v[22:23], v[88:89] op_sel:[0,0,0] op_sel_hi:[0,1,1] neg_lo:[1,0,0] neg_hi:[1,0,0]
	v_pk_fma_f32 v[8:9], v[70:71], v[22:23], v[90:91] op_sel:[1,0,0] op_sel_hi:[1,1,1] neg_lo:[1,0,0] neg_hi:[1,0,0]
	v_pk_mul_f32 v[26:27], v[2:3], v[76:77] op_sel:[0,0] op_sel_hi:[1,0]
	v_pk_mul_f32 v[84:85], v[4:5], v[76:77] op_sel:[0,1] op_sel_hi:[1,1]
	v_pk_fma_f32 v[26:27], v[6:7], v[78:79], v[26:27] op_sel:[0,0,0] op_sel_hi:[1,0,1]
	v_pk_fma_f32 v[84:85], v[8:9], v[78:79], v[84:85] op_sel:[0,1,0] op_sel_hi:[1,1,1]
	v_pk_add_f32 v[26:27], v[26:27], v[84:85]
	s_waitcnt lgkmcnt(0)
	v_pk_mul_f32 v[22:23], v[2:3], v[36:37] op_sel:[0,0] op_sel_hi:[1,0]
	ds_read_b128 v[60:63], v20 offset:4864
	v_pk_fma_f32 v[22:23], v[4:5], v[36:37], v[22:23] op_sel:[0,1,0] op_sel_hi:[1,1,1]
	ds_read_b128 v[64:67], v20 offset:13056
	v_pk_fma_f32 v[22:23], v[6:7], v[38:39], v[22:23] op_sel:[0,0,0] op_sel_hi:[1,0,1]
	ds_read_b64 v[80:81], v21 offset:45824
	v_pk_fma_f32 v[22:23], v[8:9], v[38:39], v[22:23] op_sel:[0,1,0] op_sel_hi:[1,1,1]
	ds_read_b128 v[72:75], v20 offset:29440
	v_add_f32_dpp v26, v26, v26 row_ror:12 row_mask:0xf bank_mask:0x5
	ds_read_b128 v[68:71], v20 offset:21248
	v_add_f32_dpp v27, v27, v27 row_ror:4 row_mask:0xf bank_mask:0xa
	ds_read_b128 v[76:79], v20 offset:37632
	v_add_f32_dpp v22, v22, v22 quad_perm:[1,0,3,2] row_mask:0xf bank_mask:0xf
	v_add_f32_dpp v23, v23, v23 quad_perm:[1,0,3,2] row_mask:0xf bank_mask:0xf
	v_pk_mul_f32 v[84:85], v[2:3], v[40:41] op_sel:[0,0] op_sel_hi:[1,0]
	v_pk_mul_f32 v[86:87], v[4:5], v[40:41] op_sel:[0,1] op_sel_hi:[1,1]
	v_mov_b32_dpp v26, v27 quad_perm:[0,1,2,3] row_mask:0xf bank_mask:0xa
	v_add_f32_dpp v22, v22, v22 quad_perm:[2,3,0,1] row_mask:0xf bank_mask:0xf
	v_add_f32_dpp v23, v23, v23 quad_perm:[2,3,0,1] row_mask:0xf bank_mask:0xf
	v_pk_mul_f32 v[88:89], v[6:7], v[42:43] op_sel:[0,0] op_sel_hi:[1,0]
	v_pk_mul_f32 v[90:91], v[8:9], v[42:43] op_sel:[0,1] op_sel_hi:[1,1]
	v_add_f32_dpp v26, v26, v26 row_ror:8 row_mask:0xf bank_mask:0xf
	v_add_f32_dpp v22, v22, v22 row_half_mirror row_mask:0xf bank_mask:0xf
	v_add_f32_dpp v23, v23, v23 row_half_mirror row_mask:0xf bank_mask:0xf
	v_pk_fma_f32 v[84:85], v[48:49], v[56:57], v[84:85] op_sel:[0,0,0] op_sel_hi:[0,1,1]
	v_pk_fma_f32 v[86:87], v[48:49], v[56:57], v[86:87] op_sel:[1,0,0] op_sel_hi:[1,1,1]
	v_add_f32_dpp v26, v26, v26 quad_perm:[1,0,3,2] row_mask:0xf bank_mask:0xf
	v_add_f32_dpp v22, v22, v22 row_mirror row_mask:0xf bank_mask:0xf
	v_add_f32_dpp v23, v23, v23 row_mirror row_mask:0xf bank_mask:0xf
	v_pk_fma_f32 v[88:89], v[50:51], v[56:57], v[88:89] op_sel:[0,0,0] op_sel_hi:[0,1,1]
	v_pk_fma_f32 v[90:91], v[50:51], v[56:57], v[90:91] op_sel:[1,0,0] op_sel_hi:[1,1,1]
	v_add_f32_dpp v26, v26, v26 quad_perm:[2,3,0,1] row_mask:0xf bank_mask:0xf
	v_cndmask_b32_e64 v32, v32, v26, s[6:7]
	v_pk_fma_f32 v[2:3], v[44:45], v[22:23], v[84:85] op_sel:[0,0,0] op_sel_hi:[0,1,1] neg_lo:[1,0,0] neg_hi:[1,0,0]
	v_pk_fma_f32 v[4:5], v[44:45], v[22:23], v[86:87] op_sel:[1,0,0] op_sel_hi:[1,1,1] neg_lo:[1,0,0] neg_hi:[1,0,0]
	v_pk_fma_f32 v[6:7], v[46:47], v[22:23], v[88:89] op_sel:[0,0,0] op_sel_hi:[0,1,1] neg_lo:[1,0,0] neg_hi:[1,0,0]
	v_pk_fma_f32 v[8:9], v[46:47], v[22:23], v[90:91] op_sel:[1,0,0] op_sel_hi:[1,1,1] neg_lo:[1,0,0] neg_hi:[1,0,0]
	v_pk_mul_f32 v[24:25], v[2:3], v[52:53] op_sel:[0,0] op_sel_hi:[1,0]
	v_pk_mul_f32 v[84:85], v[4:5], v[52:53] op_sel:[0,1] op_sel_hi:[1,1]
	v_pk_fma_f32 v[24:25], v[6:7], v[54:55], v[24:25] op_sel:[0,0,0] op_sel_hi:[1,0,1]
	v_pk_fma_f32 v[84:85], v[8:9], v[54:55], v[84:85] op_sel:[0,1,0] op_sel_hi:[1,1,1]
	v_pk_add_f32 v[24:25], v[24:25], v[84:85]
	s_waitcnt lgkmcnt(0)
	v_pk_mul_f32 v[22:23], v[2:3], v[60:61] op_sel:[0,0] op_sel_hi:[1,0]
	ds_read_b128 v[36:39], v20 offset:5120
	v_pk_fma_f32 v[22:23], v[4:5], v[60:61], v[22:23] op_sel:[0,1,0] op_sel_hi:[1,1,1]
	ds_read_b128 v[40:43], v20 offset:13312
	v_pk_fma_f32 v[22:23], v[6:7], v[62:63], v[22:23] op_sel:[0,0,0] op_sel_hi:[1,0,1]
	ds_read_b64 v[56:57], v21 offset:46080
	v_pk_fma_f32 v[22:23], v[8:9], v[62:63], v[22:23] op_sel:[0,1,0] op_sel_hi:[1,1,1]
	ds_read_b128 v[48:51], v20 offset:29696
	v_add_f32_dpp v24, v24, v24 row_ror:12 row_mask:0xf bank_mask:0x5
	ds_read_b128 v[44:47], v20 offset:21504
	v_add_f32_dpp v25, v25, v25 row_ror:4 row_mask:0xf bank_mask:0xa
	ds_read_b128 v[52:55], v20 offset:37888
	v_add_f32_dpp v22, v22, v22 quad_perm:[1,0,3,2] row_mask:0xf bank_mask:0xf
	v_add_f32_dpp v23, v23, v23 quad_perm:[1,0,3,2] row_mask:0xf bank_mask:0xf
	v_pk_mul_f32 v[84:85], v[2:3], v[64:65] op_sel:[0,0] op_sel_hi:[1,0]
	v_pk_mul_f32 v[86:87], v[4:5], v[64:65] op_sel:[0,1] op_sel_hi:[1,1]
	v_mov_b32_dpp v24, v25 quad_perm:[0,1,2,3] row_mask:0xf bank_mask:0xa
	v_add_f32_dpp v22, v22, v22 quad_perm:[2,3,0,1] row_mask:0xf bank_mask:0xf
	v_add_f32_dpp v23, v23, v23 quad_perm:[2,3,0,1] row_mask:0xf bank_mask:0xf
	v_pk_mul_f32 v[88:89], v[6:7], v[66:67] op_sel:[0,0] op_sel_hi:[1,0]
	v_pk_mul_f32 v[90:91], v[8:9], v[66:67] op_sel:[0,1] op_sel_hi:[1,1]
	v_add_f32_dpp v24, v24, v24 row_ror:8 row_mask:0xf bank_mask:0xf
	v_add_f32_dpp v22, v22, v22 row_half_mirror row_mask:0xf bank_mask:0xf
	v_add_f32_dpp v23, v23, v23 row_half_mirror row_mask:0xf bank_mask:0xf
	v_pk_fma_f32 v[84:85], v[72:73], v[80:81], v[84:85] op_sel:[0,0,0] op_sel_hi:[0,1,1]
	v_pk_fma_f32 v[86:87], v[72:73], v[80:81], v[86:87] op_sel:[1,0,0] op_sel_hi:[1,1,1]
	v_add_f32_dpp v24, v24, v24 quad_perm:[1,0,3,2] row_mask:0xf bank_mask:0xf
	v_add_f32_dpp v22, v22, v22 row_mirror row_mask:0xf bank_mask:0xf
	v_add_f32_dpp v23, v23, v23 row_mirror row_mask:0xf bank_mask:0xf
	v_pk_fma_f32 v[88:89], v[74:75], v[80:81], v[88:89] op_sel:[0,0,0] op_sel_hi:[0,1,1]
	v_pk_fma_f32 v[90:91], v[74:75], v[80:81], v[90:91] op_sel:[1,0,0] op_sel_hi:[1,1,1]
	v_add_f32_dpp v24, v24, v24 quad_perm:[2,3,0,1] row_mask:0xf bank_mask:0xf
	v_cndmask_b32_e64 v32, v32, v24, s[8:9]
	v_pk_fma_f32 v[2:3], v[68:69], v[22:23], v[84:85] op_sel:[0,0,0] op_sel_hi:[0,1,1] neg_lo:[1,0,0] neg_hi:[1,0,0]
	v_pk_fma_f32 v[4:5], v[68:69], v[22:23], v[86:87] op_sel:[1,0,0] op_sel_hi:[1,1,1] neg_lo:[1,0,0] neg_hi:[1,0,0]
	v_pk_fma_f32 v[6:7], v[70:71], v[22:23], v[88:89] op_sel:[0,0,0] op_sel_hi:[0,1,1] neg_lo:[1,0,0] neg_hi:[1,0,0]
	v_pk_fma_f32 v[8:9], v[70:71], v[22:23], v[90:91] op_sel:[1,0,0] op_sel_hi:[1,1,1] neg_lo:[1,0,0] neg_hi:[1,0,0]
	v_pk_mul_f32 v[26:27], v[2:3], v[76:77] op_sel:[0,0] op_sel_hi:[1,0]
	v_pk_mul_f32 v[84:85], v[4:5], v[76:77] op_sel:[0,1] op_sel_hi:[1,1]
	v_pk_fma_f32 v[26:27], v[6:7], v[78:79], v[26:27] op_sel:[0,0,0] op_sel_hi:[1,0,1]
	v_pk_fma_f32 v[84:85], v[8:9], v[78:79], v[84:85] op_sel:[0,1,0] op_sel_hi:[1,1,1]
	v_pk_add_f32 v[26:27], v[26:27], v[84:85]
	s_waitcnt lgkmcnt(0)
	v_pk_mul_f32 v[22:23], v[2:3], v[36:37] op_sel:[0,0] op_sel_hi:[1,0]
	ds_read_b128 v[60:63], v20 offset:5376
	v_pk_fma_f32 v[22:23], v[4:5], v[36:37], v[22:23] op_sel:[0,1,0] op_sel_hi:[1,1,1]
	ds_read_b128 v[64:67], v20 offset:13568
	v_pk_fma_f32 v[22:23], v[6:7], v[38:39], v[22:23] op_sel:[0,0,0] op_sel_hi:[1,0,1]
	ds_read_b64 v[80:81], v21 offset:46336
	v_pk_fma_f32 v[22:23], v[8:9], v[38:39], v[22:23] op_sel:[0,1,0] op_sel_hi:[1,1,1]
	ds_read_b128 v[72:75], v20 offset:29952
	v_add_f32_dpp v26, v26, v26 row_ror:12 row_mask:0xf bank_mask:0x5
	ds_read_b128 v[68:71], v20 offset:21760
	v_add_f32_dpp v27, v27, v27 row_ror:4 row_mask:0xf bank_mask:0xa
	ds_read_b128 v[76:79], v20 offset:38144
	v_add_f32_dpp v22, v22, v22 quad_perm:[1,0,3,2] row_mask:0xf bank_mask:0xf
	v_add_f32_dpp v23, v23, v23 quad_perm:[1,0,3,2] row_mask:0xf bank_mask:0xf
	v_pk_mul_f32 v[84:85], v[2:3], v[40:41] op_sel:[0,0] op_sel_hi:[1,0]
	v_pk_mul_f32 v[86:87], v[4:5], v[40:41] op_sel:[0,1] op_sel_hi:[1,1]
	v_mov_b32_dpp v26, v27 quad_perm:[0,1,2,3] row_mask:0xf bank_mask:0xa
	v_add_f32_dpp v22, v22, v22 quad_perm:[2,3,0,1] row_mask:0xf bank_mask:0xf
	v_add_f32_dpp v23, v23, v23 quad_perm:[2,3,0,1] row_mask:0xf bank_mask:0xf
	v_pk_mul_f32 v[88:89], v[6:7], v[42:43] op_sel:[0,0] op_sel_hi:[1,0]
	v_pk_mul_f32 v[90:91], v[8:9], v[42:43] op_sel:[0,1] op_sel_hi:[1,1]
	v_add_f32_dpp v26, v26, v26 row_ror:8 row_mask:0xf bank_mask:0xf
	v_add_f32_dpp v22, v22, v22 row_half_mirror row_mask:0xf bank_mask:0xf
	v_add_f32_dpp v23, v23, v23 row_half_mirror row_mask:0xf bank_mask:0xf
	v_pk_fma_f32 v[84:85], v[48:49], v[56:57], v[84:85] op_sel:[0,0,0] op_sel_hi:[0,1,1]
	v_pk_fma_f32 v[86:87], v[48:49], v[56:57], v[86:87] op_sel:[1,0,0] op_sel_hi:[1,1,1]
	v_add_f32_dpp v26, v26, v26 quad_perm:[1,0,3,2] row_mask:0xf bank_mask:0xf
	v_add_f32_dpp v22, v22, v22 row_mirror row_mask:0xf bank_mask:0xf
	v_add_f32_dpp v23, v23, v23 row_mirror row_mask:0xf bank_mask:0xf
	v_pk_fma_f32 v[88:89], v[50:51], v[56:57], v[88:89] op_sel:[0,0,0] op_sel_hi:[0,1,1]
	v_pk_fma_f32 v[90:91], v[50:51], v[56:57], v[90:91] op_sel:[1,0,0] op_sel_hi:[1,1,1]
	v_add_f32_dpp v26, v26, v26 quad_perm:[2,3,0,1] row_mask:0xf bank_mask:0xf
	v_cndmask_b32_e64 v32, v32, v26, s[10:11]
	v_pk_fma_f32 v[2:3], v[44:45], v[22:23], v[84:85] op_sel:[0,0,0] op_sel_hi:[0,1,1] neg_lo:[1,0,0] neg_hi:[1,0,0]
	v_pk_fma_f32 v[4:5], v[44:45], v[22:23], v[86:87] op_sel:[1,0,0] op_sel_hi:[1,1,1] neg_lo:[1,0,0] neg_hi:[1,0,0]
	v_pk_fma_f32 v[6:7], v[46:47], v[22:23], v[88:89] op_sel:[0,0,0] op_sel_hi:[0,1,1] neg_lo:[1,0,0] neg_hi:[1,0,0]
	v_pk_fma_f32 v[8:9], v[46:47], v[22:23], v[90:91] op_sel:[1,0,0] op_sel_hi:[1,1,1] neg_lo:[1,0,0] neg_hi:[1,0,0]
	v_pk_mul_f32 v[24:25], v[2:3], v[52:53] op_sel:[0,0] op_sel_hi:[1,0]
	v_pk_mul_f32 v[84:85], v[4:5], v[52:53] op_sel:[0,1] op_sel_hi:[1,1]
	v_pk_fma_f32 v[24:25], v[6:7], v[54:55], v[24:25] op_sel:[0,0,0] op_sel_hi:[1,0,1]
	v_pk_fma_f32 v[84:85], v[8:9], v[54:55], v[84:85] op_sel:[0,1,0] op_sel_hi:[1,1,1]
	v_pk_add_f32 v[24:25], v[24:25], v[84:85]
	s_waitcnt lgkmcnt(0)
	v_pk_mul_f32 v[22:23], v[2:3], v[60:61] op_sel:[0,0] op_sel_hi:[1,0]
	ds_read_b128 v[36:39], v20 offset:5632
	v_pk_fma_f32 v[22:23], v[4:5], v[60:61], v[22:23] op_sel:[0,1,0] op_sel_hi:[1,1,1]
	ds_read_b128 v[40:43], v20 offset:13824
	v_pk_fma_f32 v[22:23], v[6:7], v[62:63], v[22:23] op_sel:[0,0,0] op_sel_hi:[1,0,1]
	ds_read_b64 v[56:57], v21 offset:46592
	v_pk_fma_f32 v[22:23], v[8:9], v[62:63], v[22:23] op_sel:[0,1,0] op_sel_hi:[1,1,1]
	ds_read_b128 v[48:51], v20 offset:30208
	v_add_f32_dpp v24, v24, v24 row_ror:12 row_mask:0xf bank_mask:0x5
	ds_read_b128 v[44:47], v20 offset:22016
	v_add_f32_dpp v25, v25, v25 row_ror:4 row_mask:0xf bank_mask:0xa
	ds_read_b128 v[52:55], v20 offset:38400
	v_add_f32_dpp v22, v22, v22 quad_perm:[1,0,3,2] row_mask:0xf bank_mask:0xf
	v_add_f32_dpp v23, v23, v23 quad_perm:[1,0,3,2] row_mask:0xf bank_mask:0xf
	v_pk_mul_f32 v[84:85], v[2:3], v[64:65] op_sel:[0,0] op_sel_hi:[1,0]
	v_pk_mul_f32 v[86:87], v[4:5], v[64:65] op_sel:[0,1] op_sel_hi:[1,1]
	v_mov_b32_dpp v24, v25 quad_perm:[0,1,2,3] row_mask:0xf bank_mask:0xa
	v_add_f32_dpp v22, v22, v22 quad_perm:[2,3,0,1] row_mask:0xf bank_mask:0xf
	v_add_f32_dpp v23, v23, v23 quad_perm:[2,3,0,1] row_mask:0xf bank_mask:0xf
	v_pk_mul_f32 v[88:89], v[6:7], v[66:67] op_sel:[0,0] op_sel_hi:[1,0]
	v_pk_mul_f32 v[90:91], v[8:9], v[66:67] op_sel:[0,1] op_sel_hi:[1,1]
	v_add_f32_dpp v24, v24, v24 row_ror:8 row_mask:0xf bank_mask:0xf
	v_add_f32_dpp v22, v22, v22 row_half_mirror row_mask:0xf bank_mask:0xf
	v_add_f32_dpp v23, v23, v23 row_half_mirror row_mask:0xf bank_mask:0xf
	v_pk_fma_f32 v[84:85], v[72:73], v[80:81], v[84:85] op_sel:[0,0,0] op_sel_hi:[0,1,1]
	v_pk_fma_f32 v[86:87], v[72:73], v[80:81], v[86:87] op_sel:[1,0,0] op_sel_hi:[1,1,1]
	v_add_f32_dpp v24, v24, v24 quad_perm:[1,0,3,2] row_mask:0xf bank_mask:0xf
	v_add_f32_dpp v22, v22, v22 row_mirror row_mask:0xf bank_mask:0xf
	v_add_f32_dpp v23, v23, v23 row_mirror row_mask:0xf bank_mask:0xf
	v_pk_fma_f32 v[88:89], v[74:75], v[80:81], v[88:89] op_sel:[0,0,0] op_sel_hi:[0,1,1]
	v_pk_fma_f32 v[90:91], v[74:75], v[80:81], v[90:91] op_sel:[1,0,0] op_sel_hi:[1,1,1]
	v_add_f32_dpp v24, v24, v24 quad_perm:[2,3,0,1] row_mask:0xf bank_mask:0xf
	v_cndmask_b32_e64 v32, v32, v24, s[12:13]
	v_pk_fma_f32 v[2:3], v[68:69], v[22:23], v[84:85] op_sel:[0,0,0] op_sel_hi:[0,1,1] neg_lo:[1,0,0] neg_hi:[1,0,0]
	v_pk_fma_f32 v[4:5], v[68:69], v[22:23], v[86:87] op_sel:[1,0,0] op_sel_hi:[1,1,1] neg_lo:[1,0,0] neg_hi:[1,0,0]
	v_pk_fma_f32 v[6:7], v[70:71], v[22:23], v[88:89] op_sel:[0,0,0] op_sel_hi:[0,1,1] neg_lo:[1,0,0] neg_hi:[1,0,0]
	v_pk_fma_f32 v[8:9], v[70:71], v[22:23], v[90:91] op_sel:[1,0,0] op_sel_hi:[1,1,1] neg_lo:[1,0,0] neg_hi:[1,0,0]
	v_pk_mul_f32 v[26:27], v[2:3], v[76:77] op_sel:[0,0] op_sel_hi:[1,0]
	v_pk_mul_f32 v[84:85], v[4:5], v[76:77] op_sel:[0,1] op_sel_hi:[1,1]
	v_pk_fma_f32 v[26:27], v[6:7], v[78:79], v[26:27] op_sel:[0,0,0] op_sel_hi:[1,0,1]
	v_pk_fma_f32 v[84:85], v[8:9], v[78:79], v[84:85] op_sel:[0,1,0] op_sel_hi:[1,1,1]
	v_pk_add_f32 v[26:27], v[26:27], v[84:85]
	s_waitcnt lgkmcnt(0)
	v_pk_mul_f32 v[22:23], v[2:3], v[36:37] op_sel:[0,0] op_sel_hi:[1,0]
	ds_read_b128 v[60:63], v20 offset:5888
	v_pk_fma_f32 v[22:23], v[4:5], v[36:37], v[22:23] op_sel:[0,1,0] op_sel_hi:[1,1,1]
	ds_read_b128 v[64:67], v20 offset:14080
	v_pk_fma_f32 v[22:23], v[6:7], v[38:39], v[22:23] op_sel:[0,0,0] op_sel_hi:[1,0,1]
	ds_read_b64 v[80:81], v21 offset:46848
	v_pk_fma_f32 v[22:23], v[8:9], v[38:39], v[22:23] op_sel:[0,1,0] op_sel_hi:[1,1,1]
	ds_read_b128 v[72:75], v20 offset:30464
	v_add_f32_dpp v26, v26, v26 row_ror:12 row_mask:0xf bank_mask:0x5
	ds_read_b128 v[68:71], v20 offset:22272
	v_add_f32_dpp v27, v27, v27 row_ror:4 row_mask:0xf bank_mask:0xa
	ds_read_b128 v[76:79], v20 offset:38656
	v_add_f32_dpp v22, v22, v22 quad_perm:[1,0,3,2] row_mask:0xf bank_mask:0xf
	v_add_f32_dpp v23, v23, v23 quad_perm:[1,0,3,2] row_mask:0xf bank_mask:0xf
	v_pk_mul_f32 v[84:85], v[2:3], v[40:41] op_sel:[0,0] op_sel_hi:[1,0]
	v_pk_mul_f32 v[86:87], v[4:5], v[40:41] op_sel:[0,1] op_sel_hi:[1,1]
	v_mov_b32_dpp v26, v27 quad_perm:[0,1,2,3] row_mask:0xf bank_mask:0xa
	v_add_f32_dpp v22, v22, v22 quad_perm:[2,3,0,1] row_mask:0xf bank_mask:0xf
	v_add_f32_dpp v23, v23, v23 quad_perm:[2,3,0,1] row_mask:0xf bank_mask:0xf
	v_pk_mul_f32 v[88:89], v[6:7], v[42:43] op_sel:[0,0] op_sel_hi:[1,0]
	v_pk_mul_f32 v[90:91], v[8:9], v[42:43] op_sel:[0,1] op_sel_hi:[1,1]
	v_add_f32_dpp v26, v26, v26 row_ror:8 row_mask:0xf bank_mask:0xf
	v_add_f32_dpp v22, v22, v22 row_half_mirror row_mask:0xf bank_mask:0xf
	v_add_f32_dpp v23, v23, v23 row_half_mirror row_mask:0xf bank_mask:0xf
	v_pk_fma_f32 v[84:85], v[48:49], v[56:57], v[84:85] op_sel:[0,0,0] op_sel_hi:[0,1,1]
	v_pk_fma_f32 v[86:87], v[48:49], v[56:57], v[86:87] op_sel:[1,0,0] op_sel_hi:[1,1,1]
	v_add_f32_dpp v26, v26, v26 quad_perm:[1,0,3,2] row_mask:0xf bank_mask:0xf
	v_add_f32_dpp v22, v22, v22 row_mirror row_mask:0xf bank_mask:0xf
	v_add_f32_dpp v23, v23, v23 row_mirror row_mask:0xf bank_mask:0xf
	v_pk_fma_f32 v[88:89], v[50:51], v[56:57], v[88:89] op_sel:[0,0,0] op_sel_hi:[0,1,1]
	v_pk_fma_f32 v[90:91], v[50:51], v[56:57], v[90:91] op_sel:[1,0,0] op_sel_hi:[1,1,1]
	v_add_f32_dpp v26, v26, v26 quad_perm:[2,3,0,1] row_mask:0xf bank_mask:0xf
	v_cndmask_b32_e64 v32, v32, v26, s[14:15]
	v_pk_fma_f32 v[2:3], v[44:45], v[22:23], v[84:85] op_sel:[0,0,0] op_sel_hi:[0,1,1] neg_lo:[1,0,0] neg_hi:[1,0,0]
	v_pk_fma_f32 v[4:5], v[44:45], v[22:23], v[86:87] op_sel:[1,0,0] op_sel_hi:[1,1,1] neg_lo:[1,0,0] neg_hi:[1,0,0]
	v_pk_fma_f32 v[6:7], v[46:47], v[22:23], v[88:89] op_sel:[0,0,0] op_sel_hi:[0,1,1] neg_lo:[1,0,0] neg_hi:[1,0,0]
	v_pk_fma_f32 v[8:9], v[46:47], v[22:23], v[90:91] op_sel:[1,0,0] op_sel_hi:[1,1,1] neg_lo:[1,0,0] neg_hi:[1,0,0]
	v_pk_mul_f32 v[24:25], v[2:3], v[52:53] op_sel:[0,0] op_sel_hi:[1,0]
	v_pk_mul_f32 v[84:85], v[4:5], v[52:53] op_sel:[0,1] op_sel_hi:[1,1]
	v_pk_fma_f32 v[24:25], v[6:7], v[54:55], v[24:25] op_sel:[0,0,0] op_sel_hi:[1,0,1]
	v_pk_fma_f32 v[84:85], v[8:9], v[54:55], v[84:85] op_sel:[0,1,0] op_sel_hi:[1,1,1]
	v_pk_add_f32 v[24:25], v[24:25], v[84:85]
	s_waitcnt lgkmcnt(0)
	v_pk_mul_f32 v[22:23], v[2:3], v[60:61] op_sel:[0,0] op_sel_hi:[1,0]
	ds_read_b128 v[36:39], v20 offset:6144
	v_pk_fma_f32 v[22:23], v[4:5], v[60:61], v[22:23] op_sel:[0,1,0] op_sel_hi:[1,1,1]
	ds_read_b128 v[40:43], v20 offset:14336
	v_pk_fma_f32 v[22:23], v[6:7], v[62:63], v[22:23] op_sel:[0,0,0] op_sel_hi:[1,0,1]
	ds_read_b64 v[56:57], v21 offset:47104
	v_pk_fma_f32 v[22:23], v[8:9], v[62:63], v[22:23] op_sel:[0,1,0] op_sel_hi:[1,1,1]
	ds_read_b128 v[48:51], v20 offset:30720
	v_add_f32_dpp v24, v24, v24 row_ror:12 row_mask:0xf bank_mask:0x5
	ds_read_b128 v[44:47], v20 offset:22528
	v_add_f32_dpp v25, v25, v25 row_ror:4 row_mask:0xf bank_mask:0xa
	ds_read_b128 v[52:55], v20 offset:38912
	v_add_f32_dpp v22, v22, v22 quad_perm:[1,0,3,2] row_mask:0xf bank_mask:0xf
	v_add_f32_dpp v23, v23, v23 quad_perm:[1,0,3,2] row_mask:0xf bank_mask:0xf
	v_pk_mul_f32 v[84:85], v[2:3], v[64:65] op_sel:[0,0] op_sel_hi:[1,0]
	v_pk_mul_f32 v[86:87], v[4:5], v[64:65] op_sel:[0,1] op_sel_hi:[1,1]
	v_mov_b32_dpp v24, v25 quad_perm:[0,1,2,3] row_mask:0xf bank_mask:0xa
	v_add_f32_dpp v22, v22, v22 quad_perm:[2,3,0,1] row_mask:0xf bank_mask:0xf
	v_add_f32_dpp v23, v23, v23 quad_perm:[2,3,0,1] row_mask:0xf bank_mask:0xf
	v_pk_mul_f32 v[88:89], v[6:7], v[66:67] op_sel:[0,0] op_sel_hi:[1,0]
	v_pk_mul_f32 v[90:91], v[8:9], v[66:67] op_sel:[0,1] op_sel_hi:[1,1]
	v_add_f32_dpp v24, v24, v24 row_ror:8 row_mask:0xf bank_mask:0xf
	v_add_f32_dpp v22, v22, v22 row_half_mirror row_mask:0xf bank_mask:0xf
	v_add_f32_dpp v23, v23, v23 row_half_mirror row_mask:0xf bank_mask:0xf
	v_pk_fma_f32 v[84:85], v[72:73], v[80:81], v[84:85] op_sel:[0,0,0] op_sel_hi:[0,1,1]
	v_pk_fma_f32 v[86:87], v[72:73], v[80:81], v[86:87] op_sel:[1,0,0] op_sel_hi:[1,1,1]
	v_add_f32_dpp v24, v24, v24 quad_perm:[1,0,3,2] row_mask:0xf bank_mask:0xf
	v_add_f32_dpp v22, v22, v22 row_mirror row_mask:0xf bank_mask:0xf
	v_add_f32_dpp v23, v23, v23 row_mirror row_mask:0xf bank_mask:0xf
	v_pk_fma_f32 v[88:89], v[74:75], v[80:81], v[88:89] op_sel:[0,0,0] op_sel_hi:[0,1,1]
	v_pk_fma_f32 v[90:91], v[74:75], v[80:81], v[90:91] op_sel:[1,0,0] op_sel_hi:[1,1,1]
	v_add_f32_dpp v24, v24, v24 quad_perm:[2,3,0,1] row_mask:0xf bank_mask:0xf
	v_cndmask_b32_e64 v32, v32, v24, s[16:17]
	v_pk_fma_f32 v[2:3], v[68:69], v[22:23], v[84:85] op_sel:[0,0,0] op_sel_hi:[0,1,1] neg_lo:[1,0,0] neg_hi:[1,0,0]
	v_pk_fma_f32 v[4:5], v[68:69], v[22:23], v[86:87] op_sel:[1,0,0] op_sel_hi:[1,1,1] neg_lo:[1,0,0] neg_hi:[1,0,0]
	v_pk_fma_f32 v[6:7], v[70:71], v[22:23], v[88:89] op_sel:[0,0,0] op_sel_hi:[0,1,1] neg_lo:[1,0,0] neg_hi:[1,0,0]
	v_pk_fma_f32 v[8:9], v[70:71], v[22:23], v[90:91] op_sel:[1,0,0] op_sel_hi:[1,1,1] neg_lo:[1,0,0] neg_hi:[1,0,0]
	v_pk_mul_f32 v[26:27], v[2:3], v[76:77] op_sel:[0,0] op_sel_hi:[1,0]
	v_pk_mul_f32 v[84:85], v[4:5], v[76:77] op_sel:[0,1] op_sel_hi:[1,1]
	v_pk_fma_f32 v[26:27], v[6:7], v[78:79], v[26:27] op_sel:[0,0,0] op_sel_hi:[1,0,1]
	v_pk_fma_f32 v[84:85], v[8:9], v[78:79], v[84:85] op_sel:[0,1,0] op_sel_hi:[1,1,1]
	v_pk_add_f32 v[26:27], v[26:27], v[84:85]
	s_waitcnt lgkmcnt(0)
	v_pk_mul_f32 v[22:23], v[2:3], v[36:37] op_sel:[0,0] op_sel_hi:[1,0]
	ds_read_b128 v[60:63], v20 offset:6400
	v_pk_fma_f32 v[22:23], v[4:5], v[36:37], v[22:23] op_sel:[0,1,0] op_sel_hi:[1,1,1]
	ds_read_b128 v[64:67], v20 offset:14592
	v_pk_fma_f32 v[22:23], v[6:7], v[38:39], v[22:23] op_sel:[0,0,0] op_sel_hi:[1,0,1]
	ds_read_b64 v[80:81], v21 offset:47360
	v_pk_fma_f32 v[22:23], v[8:9], v[38:39], v[22:23] op_sel:[0,1,0] op_sel_hi:[1,1,1]
	ds_read_b128 v[72:75], v20 offset:30976
	v_add_f32_dpp v26, v26, v26 row_ror:12 row_mask:0xf bank_mask:0x5
	ds_read_b128 v[68:71], v20 offset:22784
	v_add_f32_dpp v27, v27, v27 row_ror:4 row_mask:0xf bank_mask:0xa
	ds_read_b128 v[76:79], v20 offset:39168
	v_add_f32_dpp v22, v22, v22 quad_perm:[1,0,3,2] row_mask:0xf bank_mask:0xf
	v_add_f32_dpp v23, v23, v23 quad_perm:[1,0,3,2] row_mask:0xf bank_mask:0xf
	v_pk_mul_f32 v[84:85], v[2:3], v[40:41] op_sel:[0,0] op_sel_hi:[1,0]
	v_pk_mul_f32 v[86:87], v[4:5], v[40:41] op_sel:[0,1] op_sel_hi:[1,1]
	v_mov_b32_dpp v26, v27 quad_perm:[0,1,2,3] row_mask:0xf bank_mask:0xa
	v_add_f32_dpp v22, v22, v22 quad_perm:[2,3,0,1] row_mask:0xf bank_mask:0xf
	v_add_f32_dpp v23, v23, v23 quad_perm:[2,3,0,1] row_mask:0xf bank_mask:0xf
	v_pk_mul_f32 v[88:89], v[6:7], v[42:43] op_sel:[0,0] op_sel_hi:[1,0]
	v_pk_mul_f32 v[90:91], v[8:9], v[42:43] op_sel:[0,1] op_sel_hi:[1,1]
	v_add_f32_dpp v26, v26, v26 row_ror:8 row_mask:0xf bank_mask:0xf
	v_add_f32_dpp v22, v22, v22 row_half_mirror row_mask:0xf bank_mask:0xf
	v_add_f32_dpp v23, v23, v23 row_half_mirror row_mask:0xf bank_mask:0xf
	v_pk_fma_f32 v[84:85], v[48:49], v[56:57], v[84:85] op_sel:[0,0,0] op_sel_hi:[0,1,1]
	v_pk_fma_f32 v[86:87], v[48:49], v[56:57], v[86:87] op_sel:[1,0,0] op_sel_hi:[1,1,1]
	v_add_f32_dpp v26, v26, v26 quad_perm:[1,0,3,2] row_mask:0xf bank_mask:0xf
	v_add_f32_dpp v22, v22, v22 row_mirror row_mask:0xf bank_mask:0xf
	v_add_f32_dpp v23, v23, v23 row_mirror row_mask:0xf bank_mask:0xf
	v_pk_fma_f32 v[88:89], v[50:51], v[56:57], v[88:89] op_sel:[0,0,0] op_sel_hi:[0,1,1]
	v_pk_fma_f32 v[90:91], v[50:51], v[56:57], v[90:91] op_sel:[1,0,0] op_sel_hi:[1,1,1]
	v_add_f32_dpp v26, v26, v26 quad_perm:[2,3,0,1] row_mask:0xf bank_mask:0xf
	v_cndmask_b32_e32 v32, v32, v26, vcc
	v_pk_fma_f32 v[2:3], v[44:45], v[22:23], v[84:85] op_sel:[0,0,0] op_sel_hi:[0,1,1] neg_lo:[1,0,0] neg_hi:[1,0,0]
	v_pk_fma_f32 v[4:5], v[44:45], v[22:23], v[86:87] op_sel:[1,0,0] op_sel_hi:[1,1,1] neg_lo:[1,0,0] neg_hi:[1,0,0]
	v_pk_fma_f32 v[6:7], v[46:47], v[22:23], v[88:89] op_sel:[0,0,0] op_sel_hi:[0,1,1] neg_lo:[1,0,0] neg_hi:[1,0,0]
	v_pk_fma_f32 v[8:9], v[46:47], v[22:23], v[90:91] op_sel:[1,0,0] op_sel_hi:[1,1,1] neg_lo:[1,0,0] neg_hi:[1,0,0]
	v_pk_mul_f32 v[24:25], v[2:3], v[52:53] op_sel:[0,0] op_sel_hi:[1,0]
	v_pk_mul_f32 v[84:85], v[4:5], v[52:53] op_sel:[0,1] op_sel_hi:[1,1]
	v_pk_fma_f32 v[24:25], v[6:7], v[54:55], v[24:25] op_sel:[0,0,0] op_sel_hi:[1,0,1]
	v_pk_fma_f32 v[84:85], v[8:9], v[54:55], v[84:85] op_sel:[0,1,0] op_sel_hi:[1,1,1]
	v_pk_add_f32 v[24:25], v[24:25], v[84:85]
	s_waitcnt lgkmcnt(0)
	v_pk_mul_f32 v[22:23], v[2:3], v[60:61] op_sel:[0,0] op_sel_hi:[1,0]
	ds_read_b128 v[36:39], v20 offset:6656
	v_pk_fma_f32 v[22:23], v[4:5], v[60:61], v[22:23] op_sel:[0,1,0] op_sel_hi:[1,1,1]
	ds_read_b128 v[40:43], v20 offset:14848
	v_pk_fma_f32 v[22:23], v[6:7], v[62:63], v[22:23] op_sel:[0,0,0] op_sel_hi:[1,0,1]
	ds_read_b64 v[56:57], v21 offset:47616
	v_pk_fma_f32 v[22:23], v[8:9], v[62:63], v[22:23] op_sel:[0,1,0] op_sel_hi:[1,1,1]
	ds_read_b128 v[48:51], v20 offset:31232
	v_add_f32_dpp v24, v24, v24 row_ror:12 row_mask:0xf bank_mask:0x5
	ds_read_b128 v[44:47], v20 offset:23040
	v_add_f32_dpp v25, v25, v25 row_ror:4 row_mask:0xf bank_mask:0xa
	ds_read_b128 v[52:55], v20 offset:39424
	v_add_f32_dpp v22, v22, v22 quad_perm:[1,0,3,2] row_mask:0xf bank_mask:0xf
	v_add_f32_dpp v23, v23, v23 quad_perm:[1,0,3,2] row_mask:0xf bank_mask:0xf
	v_pk_mul_f32 v[84:85], v[2:3], v[64:65] op_sel:[0,0] op_sel_hi:[1,0]
	v_pk_mul_f32 v[86:87], v[4:5], v[64:65] op_sel:[0,1] op_sel_hi:[1,1]
	v_mov_b32_dpp v24, v25 quad_perm:[0,1,2,3] row_mask:0xf bank_mask:0xa
	v_add_f32_dpp v22, v22, v22 quad_perm:[2,3,0,1] row_mask:0xf bank_mask:0xf
	v_add_f32_dpp v23, v23, v23 quad_perm:[2,3,0,1] row_mask:0xf bank_mask:0xf
	v_pk_mul_f32 v[88:89], v[6:7], v[66:67] op_sel:[0,0] op_sel_hi:[1,0]
	v_pk_mul_f32 v[90:91], v[8:9], v[66:67] op_sel:[0,1] op_sel_hi:[1,1]
	v_add_f32_dpp v24, v24, v24 row_ror:8 row_mask:0xf bank_mask:0xf
	v_add_f32_dpp v22, v22, v22 row_half_mirror row_mask:0xf bank_mask:0xf
	v_add_f32_dpp v23, v23, v23 row_half_mirror row_mask:0xf bank_mask:0xf
	v_pk_fma_f32 v[84:85], v[72:73], v[80:81], v[84:85] op_sel:[0,0,0] op_sel_hi:[0,1,1]
	v_pk_fma_f32 v[86:87], v[72:73], v[80:81], v[86:87] op_sel:[1,0,0] op_sel_hi:[1,1,1]
	v_add_f32_dpp v24, v24, v24 quad_perm:[1,0,3,2] row_mask:0xf bank_mask:0xf
	v_add_f32_dpp v22, v22, v22 row_mirror row_mask:0xf bank_mask:0xf
	v_add_f32_dpp v23, v23, v23 row_mirror row_mask:0xf bank_mask:0xf
	v_pk_fma_f32 v[88:89], v[74:75], v[80:81], v[88:89] op_sel:[0,0,0] op_sel_hi:[0,1,1]
	v_pk_fma_f32 v[90:91], v[74:75], v[80:81], v[90:91] op_sel:[1,0,0] op_sel_hi:[1,1,1]
	v_add_f32_dpp v24, v24, v24 quad_perm:[2,3,0,1] row_mask:0xf bank_mask:0xf
	v_cndmask_b32_e64 v33, 0, v24, s[0:1]
	v_pk_fma_f32 v[2:3], v[68:69], v[22:23], v[84:85] op_sel:[0,0,0] op_sel_hi:[0,1,1] neg_lo:[1,0,0] neg_hi:[1,0,0]
	v_pk_fma_f32 v[4:5], v[68:69], v[22:23], v[86:87] op_sel:[1,0,0] op_sel_hi:[1,1,1] neg_lo:[1,0,0] neg_hi:[1,0,0]
	v_pk_fma_f32 v[6:7], v[70:71], v[22:23], v[88:89] op_sel:[0,0,0] op_sel_hi:[0,1,1] neg_lo:[1,0,0] neg_hi:[1,0,0]
	v_pk_fma_f32 v[8:9], v[70:71], v[22:23], v[90:91] op_sel:[1,0,0] op_sel_hi:[1,1,1] neg_lo:[1,0,0] neg_hi:[1,0,0]
	v_pk_mul_f32 v[26:27], v[2:3], v[76:77] op_sel:[0,0] op_sel_hi:[1,0]
	v_pk_mul_f32 v[84:85], v[4:5], v[76:77] op_sel:[0,1] op_sel_hi:[1,1]
	v_pk_fma_f32 v[26:27], v[6:7], v[78:79], v[26:27] op_sel:[0,0,0] op_sel_hi:[1,0,1]
	v_pk_fma_f32 v[84:85], v[8:9], v[78:79], v[84:85] op_sel:[0,1,0] op_sel_hi:[1,1,1]
	v_pk_add_f32 v[26:27], v[26:27], v[84:85]
	s_waitcnt lgkmcnt(0)
	v_pk_mul_f32 v[22:23], v[2:3], v[36:37] op_sel:[0,0] op_sel_hi:[1,0]
	ds_read_b128 v[60:63], v20 offset:6912
	v_pk_fma_f32 v[22:23], v[4:5], v[36:37], v[22:23] op_sel:[0,1,0] op_sel_hi:[1,1,1]
	ds_read_b128 v[64:67], v20 offset:15104
	v_pk_fma_f32 v[22:23], v[6:7], v[38:39], v[22:23] op_sel:[0,0,0] op_sel_hi:[1,0,1]
	ds_read_b64 v[80:81], v21 offset:47872
	v_pk_fma_f32 v[22:23], v[8:9], v[38:39], v[22:23] op_sel:[0,1,0] op_sel_hi:[1,1,1]
	ds_read_b128 v[72:75], v20 offset:31488
	v_add_f32_dpp v26, v26, v26 row_ror:12 row_mask:0xf bank_mask:0x5
	ds_read_b128 v[68:71], v20 offset:23296
	v_add_f32_dpp v27, v27, v27 row_ror:4 row_mask:0xf bank_mask:0xa
	ds_read_b128 v[76:79], v20 offset:39680
	v_add_f32_dpp v22, v22, v22 quad_perm:[1,0,3,2] row_mask:0xf bank_mask:0xf
	v_add_f32_dpp v23, v23, v23 quad_perm:[1,0,3,2] row_mask:0xf bank_mask:0xf
	v_pk_mul_f32 v[84:85], v[2:3], v[40:41] op_sel:[0,0] op_sel_hi:[1,0]
	v_pk_mul_f32 v[86:87], v[4:5], v[40:41] op_sel:[0,1] op_sel_hi:[1,1]
	v_mov_b32_dpp v26, v27 quad_perm:[0,1,2,3] row_mask:0xf bank_mask:0xa
	v_add_f32_dpp v22, v22, v22 quad_perm:[2,3,0,1] row_mask:0xf bank_mask:0xf
	v_add_f32_dpp v23, v23, v23 quad_perm:[2,3,0,1] row_mask:0xf bank_mask:0xf
	v_pk_mul_f32 v[88:89], v[6:7], v[42:43] op_sel:[0,0] op_sel_hi:[1,0]
	v_pk_mul_f32 v[90:91], v[8:9], v[42:43] op_sel:[0,1] op_sel_hi:[1,1]
	v_add_f32_dpp v26, v26, v26 row_ror:8 row_mask:0xf bank_mask:0xf
	v_add_f32_dpp v22, v22, v22 row_half_mirror row_mask:0xf bank_mask:0xf
	v_add_f32_dpp v23, v23, v23 row_half_mirror row_mask:0xf bank_mask:0xf
	v_pk_fma_f32 v[84:85], v[48:49], v[56:57], v[84:85] op_sel:[0,0,0] op_sel_hi:[0,1,1]
	v_pk_fma_f32 v[86:87], v[48:49], v[56:57], v[86:87] op_sel:[1,0,0] op_sel_hi:[1,1,1]
	v_add_f32_dpp v26, v26, v26 quad_perm:[1,0,3,2] row_mask:0xf bank_mask:0xf
	v_add_f32_dpp v22, v22, v22 row_mirror row_mask:0xf bank_mask:0xf
	v_add_f32_dpp v23, v23, v23 row_mirror row_mask:0xf bank_mask:0xf
	v_pk_fma_f32 v[88:89], v[50:51], v[56:57], v[88:89] op_sel:[0,0,0] op_sel_hi:[0,1,1]
	v_pk_fma_f32 v[90:91], v[50:51], v[56:57], v[90:91] op_sel:[1,0,0] op_sel_hi:[1,1,1]
	v_add_f32_dpp v26, v26, v26 quad_perm:[2,3,0,1] row_mask:0xf bank_mask:0xf
	v_cndmask_b32_e64 v33, v33, v26, s[6:7]
	v_pk_fma_f32 v[2:3], v[44:45], v[22:23], v[84:85] op_sel:[0,0,0] op_sel_hi:[0,1,1] neg_lo:[1,0,0] neg_hi:[1,0,0]
	v_pk_fma_f32 v[4:5], v[44:45], v[22:23], v[86:87] op_sel:[1,0,0] op_sel_hi:[1,1,1] neg_lo:[1,0,0] neg_hi:[1,0,0]
	v_pk_fma_f32 v[6:7], v[46:47], v[22:23], v[88:89] op_sel:[0,0,0] op_sel_hi:[0,1,1] neg_lo:[1,0,0] neg_hi:[1,0,0]
	v_pk_fma_f32 v[8:9], v[46:47], v[22:23], v[90:91] op_sel:[1,0,0] op_sel_hi:[1,1,1] neg_lo:[1,0,0] neg_hi:[1,0,0]
	v_pk_mul_f32 v[24:25], v[2:3], v[52:53] op_sel:[0,0] op_sel_hi:[1,0]
	v_pk_mul_f32 v[84:85], v[4:5], v[52:53] op_sel:[0,1] op_sel_hi:[1,1]
	v_pk_fma_f32 v[24:25], v[6:7], v[54:55], v[24:25] op_sel:[0,0,0] op_sel_hi:[1,0,1]
	v_pk_fma_f32 v[84:85], v[8:9], v[54:55], v[84:85] op_sel:[0,1,0] op_sel_hi:[1,1,1]
	v_pk_add_f32 v[24:25], v[24:25], v[84:85]
	s_waitcnt lgkmcnt(0)
	v_pk_mul_f32 v[22:23], v[2:3], v[60:61] op_sel:[0,0] op_sel_hi:[1,0]
	ds_read_b128 v[36:39], v20 offset:7168
	v_pk_fma_f32 v[22:23], v[4:5], v[60:61], v[22:23] op_sel:[0,1,0] op_sel_hi:[1,1,1]
	ds_read_b128 v[40:43], v20 offset:15360
	v_pk_fma_f32 v[22:23], v[6:7], v[62:63], v[22:23] op_sel:[0,0,0] op_sel_hi:[1,0,1]
	ds_read_b64 v[56:57], v21 offset:48128
	v_pk_fma_f32 v[22:23], v[8:9], v[62:63], v[22:23] op_sel:[0,1,0] op_sel_hi:[1,1,1]
	ds_read_b128 v[48:51], v20 offset:31744
	v_add_f32_dpp v24, v24, v24 row_ror:12 row_mask:0xf bank_mask:0x5
	ds_read_b128 v[44:47], v20 offset:23552
	v_add_f32_dpp v25, v25, v25 row_ror:4 row_mask:0xf bank_mask:0xa
	ds_read_b128 v[52:55], v20 offset:39936
	v_add_f32_dpp v22, v22, v22 quad_perm:[1,0,3,2] row_mask:0xf bank_mask:0xf
	v_add_f32_dpp v23, v23, v23 quad_perm:[1,0,3,2] row_mask:0xf bank_mask:0xf
	v_pk_mul_f32 v[84:85], v[2:3], v[64:65] op_sel:[0,0] op_sel_hi:[1,0]
	v_pk_mul_f32 v[86:87], v[4:5], v[64:65] op_sel:[0,1] op_sel_hi:[1,1]
	v_mov_b32_dpp v24, v25 quad_perm:[0,1,2,3] row_mask:0xf bank_mask:0xa
	v_add_f32_dpp v22, v22, v22 quad_perm:[2,3,0,1] row_mask:0xf bank_mask:0xf
	v_add_f32_dpp v23, v23, v23 quad_perm:[2,3,0,1] row_mask:0xf bank_mask:0xf
	v_pk_mul_f32 v[88:89], v[6:7], v[66:67] op_sel:[0,0] op_sel_hi:[1,0]
	v_pk_mul_f32 v[90:91], v[8:9], v[66:67] op_sel:[0,1] op_sel_hi:[1,1]
	v_add_f32_dpp v24, v24, v24 row_ror:8 row_mask:0xf bank_mask:0xf
	v_add_f32_dpp v22, v22, v22 row_half_mirror row_mask:0xf bank_mask:0xf
	v_add_f32_dpp v23, v23, v23 row_half_mirror row_mask:0xf bank_mask:0xf
	v_pk_fma_f32 v[84:85], v[72:73], v[80:81], v[84:85] op_sel:[0,0,0] op_sel_hi:[0,1,1]
	v_pk_fma_f32 v[86:87], v[72:73], v[80:81], v[86:87] op_sel:[1,0,0] op_sel_hi:[1,1,1]
	v_add_f32_dpp v24, v24, v24 quad_perm:[1,0,3,2] row_mask:0xf bank_mask:0xf
	v_add_f32_dpp v22, v22, v22 row_mirror row_mask:0xf bank_mask:0xf
	v_add_f32_dpp v23, v23, v23 row_mirror row_mask:0xf bank_mask:0xf
	v_pk_fma_f32 v[88:89], v[74:75], v[80:81], v[88:89] op_sel:[0,0,0] op_sel_hi:[0,1,1]
	v_pk_fma_f32 v[90:91], v[74:75], v[80:81], v[90:91] op_sel:[1,0,0] op_sel_hi:[1,1,1]
	v_add_f32_dpp v24, v24, v24 quad_perm:[2,3,0,1] row_mask:0xf bank_mask:0xf
	v_cndmask_b32_e64 v33, v33, v24, s[8:9]
	v_pk_fma_f32 v[2:3], v[68:69], v[22:23], v[84:85] op_sel:[0,0,0] op_sel_hi:[0,1,1] neg_lo:[1,0,0] neg_hi:[1,0,0]
	v_pk_fma_f32 v[4:5], v[68:69], v[22:23], v[86:87] op_sel:[1,0,0] op_sel_hi:[1,1,1] neg_lo:[1,0,0] neg_hi:[1,0,0]
	v_pk_fma_f32 v[6:7], v[70:71], v[22:23], v[88:89] op_sel:[0,0,0] op_sel_hi:[0,1,1] neg_lo:[1,0,0] neg_hi:[1,0,0]
	v_pk_fma_f32 v[8:9], v[70:71], v[22:23], v[90:91] op_sel:[1,0,0] op_sel_hi:[1,1,1] neg_lo:[1,0,0] neg_hi:[1,0,0]
	v_pk_mul_f32 v[26:27], v[2:3], v[76:77] op_sel:[0,0] op_sel_hi:[1,0]
	v_pk_mul_f32 v[84:85], v[4:5], v[76:77] op_sel:[0,1] op_sel_hi:[1,1]
	v_pk_fma_f32 v[26:27], v[6:7], v[78:79], v[26:27] op_sel:[0,0,0] op_sel_hi:[1,0,1]
	v_pk_fma_f32 v[84:85], v[8:9], v[78:79], v[84:85] op_sel:[0,1,0] op_sel_hi:[1,1,1]
	v_pk_add_f32 v[26:27], v[26:27], v[84:85]
	s_waitcnt lgkmcnt(0)
	v_pk_mul_f32 v[22:23], v[2:3], v[36:37] op_sel:[0,0] op_sel_hi:[1,0]
	ds_read_b128 v[60:63], v20 offset:7424
	v_pk_fma_f32 v[22:23], v[4:5], v[36:37], v[22:23] op_sel:[0,1,0] op_sel_hi:[1,1,1]
	ds_read_b128 v[64:67], v20 offset:15616
	v_pk_fma_f32 v[22:23], v[6:7], v[38:39], v[22:23] op_sel:[0,0,0] op_sel_hi:[1,0,1]
	ds_read_b64 v[80:81], v21 offset:48384
	v_pk_fma_f32 v[22:23], v[8:9], v[38:39], v[22:23] op_sel:[0,1,0] op_sel_hi:[1,1,1]
	ds_read_b128 v[72:75], v20 offset:32000
	v_add_f32_dpp v26, v26, v26 row_ror:12 row_mask:0xf bank_mask:0x5
	ds_read_b128 v[68:71], v20 offset:23808
	v_add_f32_dpp v27, v27, v27 row_ror:4 row_mask:0xf bank_mask:0xa
	ds_read_b128 v[76:79], v20 offset:40192
	v_add_f32_dpp v22, v22, v22 quad_perm:[1,0,3,2] row_mask:0xf bank_mask:0xf
	v_add_f32_dpp v23, v23, v23 quad_perm:[1,0,3,2] row_mask:0xf bank_mask:0xf
	v_pk_mul_f32 v[84:85], v[2:3], v[40:41] op_sel:[0,0] op_sel_hi:[1,0]
	v_pk_mul_f32 v[86:87], v[4:5], v[40:41] op_sel:[0,1] op_sel_hi:[1,1]
	v_mov_b32_dpp v26, v27 quad_perm:[0,1,2,3] row_mask:0xf bank_mask:0xa
	v_add_f32_dpp v22, v22, v22 quad_perm:[2,3,0,1] row_mask:0xf bank_mask:0xf
	v_add_f32_dpp v23, v23, v23 quad_perm:[2,3,0,1] row_mask:0xf bank_mask:0xf
	v_pk_mul_f32 v[88:89], v[6:7], v[42:43] op_sel:[0,0] op_sel_hi:[1,0]
	v_pk_mul_f32 v[90:91], v[8:9], v[42:43] op_sel:[0,1] op_sel_hi:[1,1]
	v_add_f32_dpp v26, v26, v26 row_ror:8 row_mask:0xf bank_mask:0xf
	v_add_f32_dpp v22, v22, v22 row_half_mirror row_mask:0xf bank_mask:0xf
	v_add_f32_dpp v23, v23, v23 row_half_mirror row_mask:0xf bank_mask:0xf
	v_pk_fma_f32 v[84:85], v[48:49], v[56:57], v[84:85] op_sel:[0,0,0] op_sel_hi:[0,1,1]
	v_pk_fma_f32 v[86:87], v[48:49], v[56:57], v[86:87] op_sel:[1,0,0] op_sel_hi:[1,1,1]
	v_add_f32_dpp v26, v26, v26 quad_perm:[1,0,3,2] row_mask:0xf bank_mask:0xf
	v_add_f32_dpp v22, v22, v22 row_mirror row_mask:0xf bank_mask:0xf
	v_add_f32_dpp v23, v23, v23 row_mirror row_mask:0xf bank_mask:0xf
	v_pk_fma_f32 v[88:89], v[50:51], v[56:57], v[88:89] op_sel:[0,0,0] op_sel_hi:[0,1,1]
	v_pk_fma_f32 v[90:91], v[50:51], v[56:57], v[90:91] op_sel:[1,0,0] op_sel_hi:[1,1,1]
	v_add_f32_dpp v26, v26, v26 quad_perm:[2,3,0,1] row_mask:0xf bank_mask:0xf
	v_cndmask_b32_e64 v33, v33, v26, s[10:11]
	v_pk_fma_f32 v[2:3], v[44:45], v[22:23], v[84:85] op_sel:[0,0,0] op_sel_hi:[0,1,1] neg_lo:[1,0,0] neg_hi:[1,0,0]
	v_pk_fma_f32 v[4:5], v[44:45], v[22:23], v[86:87] op_sel:[1,0,0] op_sel_hi:[1,1,1] neg_lo:[1,0,0] neg_hi:[1,0,0]
	v_pk_fma_f32 v[6:7], v[46:47], v[22:23], v[88:89] op_sel:[0,0,0] op_sel_hi:[0,1,1] neg_lo:[1,0,0] neg_hi:[1,0,0]
	v_pk_fma_f32 v[8:9], v[46:47], v[22:23], v[90:91] op_sel:[1,0,0] op_sel_hi:[1,1,1] neg_lo:[1,0,0] neg_hi:[1,0,0]
	v_pk_mul_f32 v[24:25], v[2:3], v[52:53] op_sel:[0,0] op_sel_hi:[1,0]
	v_pk_mul_f32 v[84:85], v[4:5], v[52:53] op_sel:[0,1] op_sel_hi:[1,1]
	v_pk_fma_f32 v[24:25], v[6:7], v[54:55], v[24:25] op_sel:[0,0,0] op_sel_hi:[1,0,1]
	v_pk_fma_f32 v[84:85], v[8:9], v[54:55], v[84:85] op_sel:[0,1,0] op_sel_hi:[1,1,1]
	v_pk_add_f32 v[24:25], v[24:25], v[84:85]
	s_waitcnt lgkmcnt(0)
	v_pk_mul_f32 v[22:23], v[2:3], v[60:61] op_sel:[0,0] op_sel_hi:[1,0]
	ds_read_b128 v[36:39], v20 offset:7680
	v_pk_fma_f32 v[22:23], v[4:5], v[60:61], v[22:23] op_sel:[0,1,0] op_sel_hi:[1,1,1]
	ds_read_b128 v[40:43], v20 offset:15872
	v_pk_fma_f32 v[22:23], v[6:7], v[62:63], v[22:23] op_sel:[0,0,0] op_sel_hi:[1,0,1]
	ds_read_b64 v[56:57], v21 offset:48640
	v_pk_fma_f32 v[22:23], v[8:9], v[62:63], v[22:23] op_sel:[0,1,0] op_sel_hi:[1,1,1]
	ds_read_b128 v[48:51], v20 offset:32256
	v_add_f32_dpp v24, v24, v24 row_ror:12 row_mask:0xf bank_mask:0x5
	ds_read_b128 v[44:47], v20 offset:24064
	v_add_f32_dpp v25, v25, v25 row_ror:4 row_mask:0xf bank_mask:0xa
	ds_read_b128 v[52:55], v20 offset:40448
	v_add_f32_dpp v22, v22, v22 quad_perm:[1,0,3,2] row_mask:0xf bank_mask:0xf
	v_add_f32_dpp v23, v23, v23 quad_perm:[1,0,3,2] row_mask:0xf bank_mask:0xf
	v_pk_mul_f32 v[84:85], v[2:3], v[64:65] op_sel:[0,0] op_sel_hi:[1,0]
	v_pk_mul_f32 v[86:87], v[4:5], v[64:65] op_sel:[0,1] op_sel_hi:[1,1]
	v_mov_b32_dpp v24, v25 quad_perm:[0,1,2,3] row_mask:0xf bank_mask:0xa
	v_add_f32_dpp v22, v22, v22 quad_perm:[2,3,0,1] row_mask:0xf bank_mask:0xf
	v_add_f32_dpp v23, v23, v23 quad_perm:[2,3,0,1] row_mask:0xf bank_mask:0xf
	v_pk_mul_f32 v[88:89], v[6:7], v[66:67] op_sel:[0,0] op_sel_hi:[1,0]
	v_pk_mul_f32 v[90:91], v[8:9], v[66:67] op_sel:[0,1] op_sel_hi:[1,1]
	v_add_f32_dpp v24, v24, v24 row_ror:8 row_mask:0xf bank_mask:0xf
	v_add_f32_dpp v22, v22, v22 row_half_mirror row_mask:0xf bank_mask:0xf
	v_add_f32_dpp v23, v23, v23 row_half_mirror row_mask:0xf bank_mask:0xf
	v_pk_fma_f32 v[84:85], v[72:73], v[80:81], v[84:85] op_sel:[0,0,0] op_sel_hi:[0,1,1]
	v_pk_fma_f32 v[86:87], v[72:73], v[80:81], v[86:87] op_sel:[1,0,0] op_sel_hi:[1,1,1]
	v_add_f32_dpp v24, v24, v24 quad_perm:[1,0,3,2] row_mask:0xf bank_mask:0xf
	v_add_f32_dpp v22, v22, v22 row_mirror row_mask:0xf bank_mask:0xf
	v_add_f32_dpp v23, v23, v23 row_mirror row_mask:0xf bank_mask:0xf
	v_pk_fma_f32 v[88:89], v[74:75], v[80:81], v[88:89] op_sel:[0,0,0] op_sel_hi:[0,1,1]
	v_pk_fma_f32 v[90:91], v[74:75], v[80:81], v[90:91] op_sel:[1,0,0] op_sel_hi:[1,1,1]
	v_add_f32_dpp v24, v24, v24 quad_perm:[2,3,0,1] row_mask:0xf bank_mask:0xf
	v_cndmask_b32_e64 v33, v33, v24, s[12:13]
	v_pk_fma_f32 v[2:3], v[68:69], v[22:23], v[84:85] op_sel:[0,0,0] op_sel_hi:[0,1,1] neg_lo:[1,0,0] neg_hi:[1,0,0]
	v_pk_fma_f32 v[4:5], v[68:69], v[22:23], v[86:87] op_sel:[1,0,0] op_sel_hi:[1,1,1] neg_lo:[1,0,0] neg_hi:[1,0,0]
	v_pk_fma_f32 v[6:7], v[70:71], v[22:23], v[88:89] op_sel:[0,0,0] op_sel_hi:[0,1,1] neg_lo:[1,0,0] neg_hi:[1,0,0]
	v_pk_fma_f32 v[8:9], v[70:71], v[22:23], v[90:91] op_sel:[1,0,0] op_sel_hi:[1,1,1] neg_lo:[1,0,0] neg_hi:[1,0,0]
	v_pk_mul_f32 v[26:27], v[2:3], v[76:77] op_sel:[0,0] op_sel_hi:[1,0]
	v_pk_mul_f32 v[84:85], v[4:5], v[76:77] op_sel:[0,1] op_sel_hi:[1,1]
	v_pk_fma_f32 v[26:27], v[6:7], v[78:79], v[26:27] op_sel:[0,0,0] op_sel_hi:[1,0,1]
	v_pk_fma_f32 v[84:85], v[8:9], v[78:79], v[84:85] op_sel:[0,1,0] op_sel_hi:[1,1,1]
	v_pk_add_f32 v[26:27], v[26:27], v[84:85]
	s_waitcnt lgkmcnt(0)
	v_pk_mul_f32 v[22:23], v[2:3], v[36:37] op_sel:[0,0] op_sel_hi:[1,0]
	ds_read_b128 v[60:63], v20 offset:7936
	v_pk_fma_f32 v[22:23], v[4:5], v[36:37], v[22:23] op_sel:[0,1,0] op_sel_hi:[1,1,1]
	ds_read_b128 v[64:67], v20 offset:16128
	v_pk_fma_f32 v[22:23], v[6:7], v[38:39], v[22:23] op_sel:[0,0,0] op_sel_hi:[1,0,1]
	ds_read_b64 v[80:81], v21 offset:48896
	v_pk_fma_f32 v[22:23], v[8:9], v[38:39], v[22:23] op_sel:[0,1,0] op_sel_hi:[1,1,1]
	ds_read_b128 v[72:75], v20 offset:32512
	v_add_f32_dpp v26, v26, v26 row_ror:12 row_mask:0xf bank_mask:0x5
	ds_read_b128 v[68:71], v20 offset:24320
	v_add_f32_dpp v27, v27, v27 row_ror:4 row_mask:0xf bank_mask:0xa
	ds_read_b128 v[76:79], v20 offset:40704
	v_add_f32_dpp v22, v22, v22 quad_perm:[1,0,3,2] row_mask:0xf bank_mask:0xf
	v_add_f32_dpp v23, v23, v23 quad_perm:[1,0,3,2] row_mask:0xf bank_mask:0xf
	v_pk_mul_f32 v[84:85], v[2:3], v[40:41] op_sel:[0,0] op_sel_hi:[1,0]
	v_pk_mul_f32 v[86:87], v[4:5], v[40:41] op_sel:[0,1] op_sel_hi:[1,1]
	v_mov_b32_dpp v26, v27 quad_perm:[0,1,2,3] row_mask:0xf bank_mask:0xa
	v_add_f32_dpp v22, v22, v22 quad_perm:[2,3,0,1] row_mask:0xf bank_mask:0xf
	v_add_f32_dpp v23, v23, v23 quad_perm:[2,3,0,1] row_mask:0xf bank_mask:0xf
	v_pk_mul_f32 v[88:89], v[6:7], v[42:43] op_sel:[0,0] op_sel_hi:[1,0]
	v_pk_mul_f32 v[90:91], v[8:9], v[42:43] op_sel:[0,1] op_sel_hi:[1,1]
	v_add_f32_dpp v26, v26, v26 row_ror:8 row_mask:0xf bank_mask:0xf
	v_add_f32_dpp v22, v22, v22 row_half_mirror row_mask:0xf bank_mask:0xf
	v_add_f32_dpp v23, v23, v23 row_half_mirror row_mask:0xf bank_mask:0xf
	v_pk_fma_f32 v[84:85], v[48:49], v[56:57], v[84:85] op_sel:[0,0,0] op_sel_hi:[0,1,1]
	v_pk_fma_f32 v[86:87], v[48:49], v[56:57], v[86:87] op_sel:[1,0,0] op_sel_hi:[1,1,1]
	v_add_f32_dpp v26, v26, v26 quad_perm:[1,0,3,2] row_mask:0xf bank_mask:0xf
	v_add_f32_dpp v22, v22, v22 row_mirror row_mask:0xf bank_mask:0xf
	v_add_f32_dpp v23, v23, v23 row_mirror row_mask:0xf bank_mask:0xf
	v_pk_fma_f32 v[88:89], v[50:51], v[56:57], v[88:89] op_sel:[0,0,0] op_sel_hi:[0,1,1]
	v_pk_fma_f32 v[90:91], v[50:51], v[56:57], v[90:91] op_sel:[1,0,0] op_sel_hi:[1,1,1]
	v_add_f32_dpp v26, v26, v26 quad_perm:[2,3,0,1] row_mask:0xf bank_mask:0xf
	v_cndmask_b32_e64 v33, v33, v26, s[14:15]
	v_pk_fma_f32 v[2:3], v[44:45], v[22:23], v[84:85] op_sel:[0,0,0] op_sel_hi:[0,1,1] neg_lo:[1,0,0] neg_hi:[1,0,0]
	v_pk_fma_f32 v[4:5], v[44:45], v[22:23], v[86:87] op_sel:[1,0,0] op_sel_hi:[1,1,1] neg_lo:[1,0,0] neg_hi:[1,0,0]
	v_pk_fma_f32 v[6:7], v[46:47], v[22:23], v[88:89] op_sel:[0,0,0] op_sel_hi:[0,1,1] neg_lo:[1,0,0] neg_hi:[1,0,0]
	v_pk_fma_f32 v[8:9], v[46:47], v[22:23], v[90:91] op_sel:[1,0,0] op_sel_hi:[1,1,1] neg_lo:[1,0,0] neg_hi:[1,0,0]
	v_pk_mul_f32 v[24:25], v[2:3], v[52:53] op_sel:[0,0] op_sel_hi:[1,0]
	v_pk_mul_f32 v[84:85], v[4:5], v[52:53] op_sel:[0,1] op_sel_hi:[1,1]
	v_pk_fma_f32 v[24:25], v[6:7], v[54:55], v[24:25] op_sel:[0,0,0] op_sel_hi:[1,0,1]
	v_pk_fma_f32 v[84:85], v[8:9], v[54:55], v[84:85] op_sel:[0,1,0] op_sel_hi:[1,1,1]
	v_pk_add_f32 v[24:25], v[24:25], v[84:85]
	s_waitcnt lgkmcnt(0)
	v_pk_mul_f32 v[22:23], v[2:3], v[60:61] op_sel:[0,0] op_sel_hi:[1,0]
	v_pk_fma_f32 v[22:23], v[4:5], v[60:61], v[22:23] op_sel:[0,1,0] op_sel_hi:[1,1,1]
	v_pk_fma_f32 v[22:23], v[6:7], v[62:63], v[22:23] op_sel:[0,0,0] op_sel_hi:[1,0,1]
	v_pk_fma_f32 v[22:23], v[8:9], v[62:63], v[22:23] op_sel:[0,1,0] op_sel_hi:[1,1,1]
	v_add_f32_dpp v24, v24, v24 row_ror:12 row_mask:0xf bank_mask:0x5
	v_add_f32_dpp v25, v25, v25 row_ror:4 row_mask:0xf bank_mask:0xa
	v_add_f32_dpp v22, v22, v22 quad_perm:[1,0,3,2] row_mask:0xf bank_mask:0xf
	v_add_f32_dpp v23, v23, v23 quad_perm:[1,0,3,2] row_mask:0xf bank_mask:0xf
	v_pk_mul_f32 v[84:85], v[2:3], v[64:65] op_sel:[0,0] op_sel_hi:[1,0]
	v_pk_mul_f32 v[86:87], v[4:5], v[64:65] op_sel:[0,1] op_sel_hi:[1,1]
	v_mov_b32_dpp v24, v25 quad_perm:[0,1,2,3] row_mask:0xf bank_mask:0xa
	v_add_f32_dpp v22, v22, v22 quad_perm:[2,3,0,1] row_mask:0xf bank_mask:0xf
	v_add_f32_dpp v23, v23, v23 quad_perm:[2,3,0,1] row_mask:0xf bank_mask:0xf
	v_pk_mul_f32 v[88:89], v[6:7], v[66:67] op_sel:[0,0] op_sel_hi:[1,0]
	v_pk_mul_f32 v[90:91], v[8:9], v[66:67] op_sel:[0,1] op_sel_hi:[1,1]
	v_add_f32_dpp v24, v24, v24 row_ror:8 row_mask:0xf bank_mask:0xf
	v_add_f32_dpp v22, v22, v22 row_half_mirror row_mask:0xf bank_mask:0xf
	v_add_f32_dpp v23, v23, v23 row_half_mirror row_mask:0xf bank_mask:0xf
	v_pk_fma_f32 v[84:85], v[72:73], v[80:81], v[84:85] op_sel:[0,0,0] op_sel_hi:[0,1,1]
	v_pk_fma_f32 v[86:87], v[72:73], v[80:81], v[86:87] op_sel:[1,0,0] op_sel_hi:[1,1,1]
	v_add_f32_dpp v24, v24, v24 quad_perm:[1,0,3,2] row_mask:0xf bank_mask:0xf
	v_add_f32_dpp v22, v22, v22 row_mirror row_mask:0xf bank_mask:0xf
	v_add_f32_dpp v23, v23, v23 row_mirror row_mask:0xf bank_mask:0xf
	v_pk_fma_f32 v[88:89], v[74:75], v[80:81], v[88:89] op_sel:[0,0,0] op_sel_hi:[0,1,1]
	v_pk_fma_f32 v[90:91], v[74:75], v[80:81], v[90:91] op_sel:[1,0,0] op_sel_hi:[1,1,1]
	v_add_f32_dpp v24, v24, v24 quad_perm:[2,3,0,1] row_mask:0xf bank_mask:0xf
	v_cndmask_b32_e64 v33, v33, v24, s[16:17]
	v_pk_fma_f32 v[2:3], v[68:69], v[22:23], v[84:85] op_sel:[0,0,0] op_sel_hi:[0,1,1] neg_lo:[1,0,0] neg_hi:[1,0,0]
	v_pk_fma_f32 v[4:5], v[68:69], v[22:23], v[86:87] op_sel:[1,0,0] op_sel_hi:[1,1,1] neg_lo:[1,0,0] neg_hi:[1,0,0]
	v_pk_fma_f32 v[6:7], v[70:71], v[22:23], v[88:89] op_sel:[0,0,0] op_sel_hi:[0,1,1] neg_lo:[1,0,0] neg_hi:[1,0,0]
	v_pk_fma_f32 v[8:9], v[70:71], v[22:23], v[90:91] op_sel:[1,0,0] op_sel_hi:[1,1,1] neg_lo:[1,0,0] neg_hi:[1,0,0]
	v_pk_mul_f32 v[26:27], v[2:3], v[76:77] op_sel:[0,0] op_sel_hi:[1,0]
	v_pk_mul_f32 v[84:85], v[4:5], v[76:77] op_sel:[0,1] op_sel_hi:[1,1]
	v_pk_fma_f32 v[26:27], v[6:7], v[78:79], v[26:27] op_sel:[0,0,0] op_sel_hi:[1,0,1]
	v_pk_fma_f32 v[84:85], v[8:9], v[78:79], v[84:85] op_sel:[0,1,0] op_sel_hi:[1,1,1]
	v_pk_add_f32 v[26:27], v[26:27], v[84:85]
	s_nop 1
	v_add_f32_dpp v26, v26, v26 row_ror:12 row_mask:0xf bank_mask:0x5
	v_add_f32_dpp v27, v27, v27 row_ror:4 row_mask:0xf bank_mask:0xa
	s_nop 1
	v_mov_b32_dpp v26, v27 quad_perm:[0,1,2,3] row_mask:0xf bank_mask:0xa
	s_nop 1
	v_add_f32_dpp v26, v26, v26 row_ror:8 row_mask:0xf bank_mask:0xf
	s_nop 1
	v_add_f32_dpp v26, v26, v26 quad_perm:[1,0,3,2] row_mask:0xf bank_mask:0xf
	s_nop 1
	v_add_f32_dpp v26, v26, v26 quad_perm:[2,3,0,1] row_mask:0xf bank_mask:0xf
	v_cndmask_b32_e32 v33, v33, v26, vcc
	v_lshl_add_u32 v35, s23, 12, v11
	s_add_i32 s22, s22, 1
	ds_write2st64_b32 v35, v30, v31 offset1:4
	ds_write2st64_b32 v35, v32, v33 offset0:8 offset1:12
	s_cmp_eq_u32 s22, 64
	s_waitcnt lgkmcnt(0)
	s_barrier
	s_cbranch_scc0 .LBB0_1750
	s_lshl_b32 s0, s18, 4
	s_or_b32 s0, s0, s26
	s_ashr_i32 s1, s0, 31
	s_lshl_b64 s[0:1], s[0:1], 6
	s_lshl_b32 s2, s27, 5
	s_or_b32 s0, s0, s2
	v_or_b32_e32 v12, s0, v1
	v_mov_b32_e32 v13, s1
	v_lshlrev_b64 v[12:13], 8, v[12:13]
	v_lshl_add_u64 v[12:13], s[82:83], 0, v[12:13]
	v_mov_b32_e32 v11, 0
	v_lshl_add_u64 v[10:11], v[12:13], 0, v[10:11]
	s_mov_b64 s[0:1], 0x4100000
	v_lshl_add_u64 v[12:13], v[10:11], 0, s[0:1]
	v_add_co_u32_e32 v10, vcc, 0x4100000, v10
	s_nop 1
	v_addc_co_u32_e32 v11, vcc, 0, v11, vcc
	v_mov_b32_e32 v14, v2
	v_mov_b32_e32 v15, v4
	v_mov_b32_e32 v16, v6
	v_mov_b32_e32 v17, v8
	v_mov_b32_e32 v18, v3
	v_mov_b32_e32 v19, v5
	v_mov_b32_e32 v20, v7
	v_mov_b32_e32 v21, v9
	global_store_dwordx4 v[10:11], v[14:17], off
	global_store_dwordx4 v[12:13], v[18:21], off offset:256

.LBB0_1773:
	s_add_i32 s30, s5, 1
	s_cmp_eq_u32 s5, 63
	s_mov_b64 s[6:7], -1
	s_cbranch_scc1 .LBB0_1793
	s_cmp_eq_u32 s5, 0
	s_cbranch_scc0 .Lprod_cge1
	s_waitcnt vmcnt(0)
	s_branch .Lprod_noconv
.Lprod_cge1:
	s_cmp_eq_u64 s[0:1], 0
	s_cbranch_scc1 .Lprod_nb
	s_cmp_lt_u32 s5, 2
	s_cbranch_scc1 .Lprod_w8
	s_waitcnt vmcnt(12)
	s_branch .Lprod_conv
.Lprod_w8:
	s_waitcnt vmcnt(8)
	s_branch .Lprod_conv
.Lprod_nb:
	s_cmp_lt_u32 s5, 2
	s_cbranch_scc1 .Lprod_w0
	s_waitcnt vmcnt(4)
	s_branch .Lprod_conv

.Lprod_conv:
	v_lshlrev_b32_e32 v2, 16, v100
	v_lshlrev_b32_e32 v4, 16, v101
	v_lshlrev_b32_e32 v6, 16, v102
	v_lshlrev_b32_e32 v1, 16, v103
	v_lshlrev_b32_e32 v3, 16, v104
	v_lshlrev_b32_e32 v5, 16, v105
	v_lshlrev_b32_e32 v8, 16, v106
	v_lshlrev_b32_e32 v10, 16, v107
	v_lshlrev_b32_e32 v12, 16, v108
	v_lshlrev_b32_e32 v7, 16, v109
	v_lshlrev_b32_e32 v9, 16, v110
	v_lshlrev_b32_e32 v11, 16, v111
	v_lshlrev_b32_e32 v14, 16, v112
	v_lshlrev_b32_e32 v16, 16, v113
	v_lshlrev_b32_e32 v18, 16, v114
	v_lshlrev_b32_e32 v13, 16, v115
	v_lshlrev_b32_e32 v15, 16, v116
	v_lshlrev_b32_e32 v17, 16, v117
	v_lshlrev_b32_e32 v20, 16, v118
	v_lshlrev_b32_e32 v22, 16, v119
	v_lshlrev_b32_e32 v24, 16, v120
	v_lshlrev_b32_e32 v19, 16, v121
	v_lshlrev_b32_e32 v21, 16, v122
	v_lshlrev_b32_e32 v23, 16, v123
	v_lshlrev_b32_e32 v26, 16, v124
	v_lshlrev_b32_e32 v28, 16, v125
	v_lshlrev_b32_e32 v30, 16, v126
	v_mov_b32_e32 v65, v130
	v_mov_b32_e32 v66, v131
	v_mov_b32_e32 v67, v132
	v_mov_b32_e32 v68, v133
	v_mov_b32_e32 v69, v134
	v_mov_b32_e32 v70, v135
	v_mov_b32_e32 v71, v136
	v_mov_b32_e32 v72, v137
	v_mov_b32_e32 v73, v138
	v_mov_b32_e32 v74, v139
	v_mov_b32_e32 v75, v140
	v_mov_b32_e32 v76, v141
	v_mov_b32_e32 v77, v142
	v_mov_b32_e32 v78, v143
	v_mov_b32_e32 v79, v144
	v_mov_b32_e32 v80, v145
.Lprod_noconv:
	s_cmp_gt_u32 s5, 61
	s_cbranch_scc1 .Lprod_noload
	v_lshl_add_u64 v[150:151], s[34:35], 0, v[44:45]
	v_add_co_u32_e32 v152, vcc, 0xd3d4000, v150
	s_nop 1
	v_addc_co_u32_e32 v153, vcc, 0, v151, vcc
	v_add_co_u32_e32 v154, vcc, 0xd3d5000, v150
	s_nop 1
	v_addc_co_u32_e32 v155, vcc, 0, v151, vcc
	v_add_co_u32_e32 v156, vcc, 0xd3da000, v150
	s_nop 1
	v_addc_co_u32_e32 v157, vcc, 0, v151, vcc
	v_add_co_u32_e32 v158, vcc, 0xd3db000, v150
	s_nop 1
	v_addc_co_u32_e32 v159, vcc, 0, v151, vcc
	v_add_co_u32_e32 v160, vcc, 0xd3df000, v150
	s_nop 1
	v_addc_co_u32_e32 v161, vcc, 0, v151, vcc
	v_add_co_u32_e32 v162, vcc, 0xd3e0000, v150
	s_nop 1
	v_addc_co_u32_e32 v163, vcc, 0, v151, vcc
	global_load_ushort v100, v[152:153], off offset:1536
	global_load_ushort v101, v[152:153], off offset:3584
	global_load_ushort v102, v[154:155], off offset:1536
	global_load_ushort v103, v[156:157], off offset:512
	global_load_ushort v104, v[156:157], off offset:2560
	global_load_ushort v105, v[158:159], off offset:512
	global_load_ushort v106, v[160:161], off offset:3584
	global_load_ushort v107, v[162:163], off offset:1536
	v_add_co_u32_e32 v152, vcc, 0xd3e5000, v150
	s_nop 1
	v_addc_co_u32_e32 v153, vcc, 0, v151, vcc
	v_add_co_u32_e32 v154, vcc, 0xd3e6000, v150
	s_nop 1
	v_addc_co_u32_e32 v155, vcc, 0, v151, vcc
	v_add_co_u32_e32 v156, vcc, 0xd3eb000, v150
	s_nop 1
	v_addc_co_u32_e32 v157, vcc, 0, v151, vcc
	v_add_co_u32_e32 v158, vcc, 0xd3ec000, v150
	s_nop 1
	v_addc_co_u32_e32 v159, vcc, 0, v151, vcc
	v_add_co_u32_e32 v160, vcc, 0xd3f1000, v150
	s_nop 1
	v_addc_co_u32_e32 v161, vcc, 0, v151, vcc
	global_load_ushort v108, v[162:163], off offset:3584
	global_load_ushort v109, v[152:153], off offset:2560
	global_load_ushort v110, v[154:155], off offset:512
	global_load_ushort v111, v[154:155], off offset:2560
	global_load_ushort v112, v[156:157], off offset:1536
	global_load_ushort v113, v[156:157], off offset:3584
	global_load_ushort v114, v[158:159], off offset:1536
	global_load_ushort v115, v[160:161], off offset:512
	v_add_co_u32_e32 v152, vcc, 0xd3f2000, v150
	s_nop 1
	v_addc_co_u32_e32 v153, vcc, 0, v151, vcc
	v_add_co_u32_e32 v154, vcc, 0xd3f6000, v150
	s_nop 1
	v_addc_co_u32_e32 v155, vcc, 0, v151, vcc
	v_add_co_u32_e32 v156, vcc, 0xd3f7000, v150
	s_nop 1
	v_addc_co_u32_e32 v157, vcc, 0, v151, vcc
	v_add_co_u32_e32 v158, vcc, 0xd3fc000, v150
	s_nop 1
	v_addc_co_u32_e32 v159, vcc, 0, v151, vcc
	v_add_co_u32_e32 v162, vcc, 0xd3fd000, v150
	s_nop 1
	v_addc_co_u32_e32 v163, vcc, 0, v151, vcc
	global_load_ushort v116, v[160:161], off offset:2560
	global_load_ushort v117, v[152:153], off offset:512
	global_load_ushort v118, v[154:155], off offset:3584
	global_load_ushort v119, v[156:157], off offset:1536
	global_load_ushort v120, v[156:157], off offset:3584
	global_load_ushort v121, v[158:159], off offset:2560
	global_load_ushort v122, v[162:163], off offset:512
	global_load_ushort v123, v[162:163], off offset:2560
	v_add_co_u32_e32 v152, vcc, 0xd403000, v150
	v_lshl_add_u64 v[154:155], s[34:35], 0, v[46:47]
	s_nop 0
	v_addc_co_u32_e32 v153, vcc, 0, v151, vcc
	v_add_co_u32_e32 v150, vcc, 0xd402000, v150
	v_lshlrev_b64 v[158:159], 2, v[48:49]
	s_nop 0
	v_addc_co_u32_e32 v151, vcc, 0, v151, vcc
	v_add_co_u32_e32 v156, vcc, 0x1b202000, v154
	v_or_b32_e32 v160, 0x1000, v158
	s_nop 0
	v_addc_co_u32_e32 v157, vcc, 0, v155, vcc
	v_mov_b32_e32 v161, v159
	v_or_b32_e32 v164, 0x2000, v158
	v_mov_b32_e32 v165, v159
	v_add_co_u32_e32 v154, vcc, 0x19102000, v154
	v_lshl_add_u64 v[162:163], s[14:15], 0, v[160:161]
	v_lshl_add_u64 v[166:167], s[14:15], 0, v[164:165]
	v_addc_co_u32_e32 v155, vcc, 0, v155, vcc
	v_lshl_add_u64 v[160:161], s[12:13], 0, v[160:161]
	global_load_ushort v124, v[152:153], off offset:1536
	global_load_ushort v125, v[150:151], off offset:3584
	global_load_dword v130, v[156:157], off offset:512
	global_load_dword v131, v[154:155], off offset:512
	global_load_dword v132, v[162:163], off
	global_load_dword v133, v[160:161], off
	global_load_dword v134, v[166:167], off
	global_load_ushort v126, v[150:151], off offset:1536
	v_lshl_add_u64 v[150:151], s[12:13], 0, v[164:165]
	v_or_b32_e32 v152, 0x3000, v158
	v_mov_b32_e32 v153, v159
	v_or_b32_e32 v156, 0x4000, v158
	v_mov_b32_e32 v157, v159
	v_or_b32_e32 v162, 0x5000, v158
	v_mov_b32_e32 v163, v159
	v_or_b32_e32 v166, 0x6000, v158
	v_mov_b32_e32 v167, v159
	v_lshl_add_u64 v[154:155], s[14:15], 0, v[152:153]
	v_lshl_add_u64 v[152:153], s[12:13], 0, v[152:153]
	v_lshl_add_u64 v[160:161], s[14:15], 0, v[156:157]
	v_lshl_add_u64 v[156:157], s[12:13], 0, v[156:157]
	v_lshl_add_u64 v[164:165], s[14:15], 0, v[162:163]
	v_lshl_add_u64 v[162:163], s[12:13], 0, v[162:163]
	v_lshl_add_u64 v[168:169], s[14:15], 0, v[166:167]
	global_load_dword v135, v[150:151], off
	global_load_dword v136, v[154:155], off
	global_load_dword v137, v[152:153], off
	global_load_dword v138, v[160:161], off
	global_load_dword v139, v[156:157], off
	global_load_dword v140, v[164:165], off
	global_load_dword v141, v[162:163], off
	global_load_dword v142, v[168:169], off
	v_lshl_add_u64 v[150:151], s[12:13], 0, v[166:167]
	v_or_b32_e32 v158, 0x7000, v158
	v_lshl_add_u64 v[152:153], s[14:15], 0, v[158:159]
	v_lshl_add_u64 v[154:155], s[12:13], 0, v[158:159]
	global_load_dword v143, v[150:151], off
	global_load_dword v144, v[152:153], off
	global_load_dword v145, v[154:155], off
.Lprod_noload:
	s_bitcmp1_b32 s30, 0
	s_cselect_b32 s2, 0xc000, 0
	s_add_i32 s2, s2, 0
	v_add_u32_e32 v81, s2, v54
	v_sub_f32_e32 v82, v4, v3
	v_sub_f32_e32 v93, v3, v10
	v_fma_f32 v82, v27, v82, v3
	v_fma_f32 v93, v27, v93, v10
	v_mul_f32_e32 v85, v29, v82
	v_mul_f32_e32 v96, v29, v93
	v_mul_f32_e32 v86, v85, v85
	v_mul_f32_e32 v97, v96, v96
	s_nop 0
	v_add_f32_dpp v86, v86, v86 quad_perm:[1,0,3,2] row_mask:0xf bank_mask:0xf bound_ctrl:1
	v_add_f32_dpp v97, v97, v97 quad_perm:[1,0,3,2] row_mask:0xf bank_mask:0xf bound_ctrl:1
	s_nop 0
	v_add_f32_dpp v86, v86, v86 quad_perm:[2,3,0,1] row_mask:0xf bank_mask:0xf bound_ctrl:1
	v_add_f32_dpp v97, v97, v97 quad_perm:[2,3,0,1] row_mask:0xf bank_mask:0xf bound_ctrl:1
	s_nop 0
	v_add_f32_dpp v86, v86, v86 row_half_mirror row_mask:0xf bank_mask:0xf bound_ctrl:1
	v_add_f32_dpp v97, v97, v97 row_half_mirror row_mask:0xf bank_mask:0xf bound_ctrl:1
	s_nop 0
	v_add_f32_dpp v86, v86, v86 row_mirror row_mask:0xf bank_mask:0xf bound_ctrl:1
	v_add_f32_dpp v97, v97, v97 row_mirror row_mask:0xf bank_mask:0xf bound_ctrl:1
	s_nop 0
	v_add_f32_dpp v86, v86, v86 row_bcast:15 row_mask:0xa bank_mask:0xf
	v_add_f32_dpp v97, v97, v97 row_bcast:15 row_mask:0xa bank_mask:0xf
	s_nop 0
	v_add_f32_dpp v86, v86, v86 row_bcast:31 row_mask:0xc bank_mask:0xf
	v_add_f32_dpp v97, v97, v97 row_bcast:31 row_mask:0xc bank_mask:0xf
	v_readlane_b32 s24, v86, 63
	v_readlane_b32 s25, v97, 63
	v_sub_f32_e32 v83, v2, v1
	v_sub_f32_e32 v94, v1, v8
	v_fma_f32 v83, v25, v83, v1
	v_fma_f32 v94, v25, v94, v8
	v_sub_f32_e32 v84, v6, v5
	v_sub_f32_e32 v95, v5, v12
	v_fma_f32 v84, v43, v84, v5
	v_fma_f32 v95, v43, v95, v12
	v_add_f32_e32 v88, -1.0, v65
	v_add_f32_e32 v170, -1.0, v67
	v_fma_f32 v88, v31, v88, 1.0
	v_fma_f32 v170, v31, v170, 1.0
	v_mul_f32_e32 v89, v88, v82
	v_mul_f32_e32 v171, v170, v93
	v_mul_f32_e32 v90, v83, v89
	v_mul_f32_e32 v172, v94, v171
	v_mul_f32_e32 v90, v35, v90
	v_mul_f32_e32 v172, v35, v172
	s_nop 0
	v_add_f32_dpp v90, v90, v90 quad_perm:[1,0,3,2] row_mask:0xf bank_mask:0xf bound_ctrl:1
	v_add_f32_dpp v172, v172, v172 quad_perm:[1,0,3,2] row_mask:0xf bank_mask:0xf bound_ctrl:1
	s_nop 0
	v_add_f32_dpp v90, v90, v90 quad_perm:[2,3,0,1] row_mask:0xf bank_mask:0xf bound_ctrl:1
	v_add_f32_dpp v172, v172, v172 quad_perm:[2,3,0,1] row_mask:0xf bank_mask:0xf bound_ctrl:1
	s_nop 0
	v_add_f32_dpp v90, v90, v90 row_half_mirror row_mask:0xf bank_mask:0xf bound_ctrl:1
	v_add_f32_dpp v172, v172, v172 row_half_mirror row_mask:0xf bank_mask:0xf bound_ctrl:1
	s_nop 0
	v_add_f32_dpp v90, v90, v90 row_mirror row_mask:0xf bank_mask:0xf bound_ctrl:1
	v_add_f32_dpp v172, v172, v172 row_mirror row_mask:0xf bank_mask:0xf bound_ctrl:1
	s_nop 0
	v_add_f32_dpp v90, v90, v90 row_bcast:15 row_mask:0xa bank_mask:0xf
	v_add_f32_dpp v172, v172, v172 row_bcast:15 row_mask:0xa bank_mask:0xf
	s_nop 0
	v_add_f32_dpp v90, v90, v90 row_bcast:31 row_mask:0xc bank_mask:0xf
	v_add_f32_dpp v172, v172, v172 row_bcast:31 row_mask:0xc bank_mask:0xf
	v_readlane_b32 s6, v90, 63
	v_readlane_b32 s7, v172, 63
	v_mov_b32_e32 v87, s24
	v_mov_b32_e32 v98, s25
	v_max_f32_e32 v87, 0x179abe15, v87
	v_max_f32_e32 v98, 0x179abe15, v98
	v_rsq_f32_e32 v87, v87
	v_rsq_f32_e32 v98, v98
	v_mul_f32_e32 v85, v85, v87
	v_mul_f32_e32 v96, v96, v98
	v_mul_f32_e32 v91, v65, v85
	v_mul_f32_e32 v173, v67, v96
	v_add_u32_e32 v92, v81, v57
	v_add_u32_e32 v174, v81, v58
	ds_write_b32 v92, v85
	ds_write_b32 v174, v96
	ds_write2st64_b32 v92, v66, v91 offset0:32 offset1:64
	ds_write2st64_b32 v174, v68, v173 offset0:32 offset1:64
	ds_write2st64_b32 v92, v89, v83 offset0:96 offset1:128
	ds_write2st64_b32 v174, v171, v94 offset0:96 offset1:128
	ds_write_b32 v92, v84 offset:40960
	ds_write_b32 v174, v95 offset:40960
	v_sub_f32_e32 v82, v10, v9
	v_sub_f32_e32 v93, v9, v16
	v_fma_f32 v82, v27, v82, v9
	v_fma_f32 v93, v27, v93, v16
	v_mul_f32_e32 v85, v29, v82
	v_mul_f32_e32 v96, v29, v93
	v_mul_f32_e32 v86, v85, v85
	v_mul_f32_e32 v97, v96, v96
	s_nop 0
	v_add_f32_dpp v86, v86, v86 quad_perm:[1,0,3,2] row_mask:0xf bank_mask:0xf bound_ctrl:1
	v_add_f32_dpp v97, v97, v97 quad_perm:[1,0,3,2] row_mask:0xf bank_mask:0xf bound_ctrl:1
	s_nop 0
	v_add_f32_dpp v86, v86, v86 quad_perm:[2,3,0,1] row_mask:0xf bank_mask:0xf bound_ctrl:1
	v_add_f32_dpp v97, v97, v97 quad_perm:[2,3,0,1] row_mask:0xf bank_mask:0xf bound_ctrl:1
	s_nop 0
	v_add_f32_dpp v86, v86, v86 row_half_mirror row_mask:0xf bank_mask:0xf bound_ctrl:1
	v_add_f32_dpp v97, v97, v97 row_half_mirror row_mask:0xf bank_mask:0xf bound_ctrl:1
	s_nop 0
	v_add_f32_dpp v86, v86, v86 row_mirror row_mask:0xf bank_mask:0xf bound_ctrl:1
	v_add_f32_dpp v97, v97, v97 row_mirror row_mask:0xf bank_mask:0xf bound_ctrl:1
	s_nop 0
	v_add_f32_dpp v86, v86, v86 row_bcast:15 row_mask:0xa bank_mask:0xf
	v_add_f32_dpp v97, v97, v97 row_bcast:15 row_mask:0xa bank_mask:0xf
	s_nop 0
	v_add_f32_dpp v86, v86, v86 row_bcast:31 row_mask:0xc bank_mask:0xf
	v_add_f32_dpp v97, v97, v97 row_bcast:31 row_mask:0xc bank_mask:0xf
	v_readlane_b32 s24, v86, 63
	v_readlane_b32 s25, v97, 63
	v_sub_f32_e32 v83, v8, v7
	v_sub_f32_e32 v94, v7, v14
	v_fma_f32 v83, v25, v83, v7
	v_fma_f32 v94, v25, v94, v14
	v_sub_f32_e32 v84, v12, v11
	v_sub_f32_e32 v95, v11, v18
	v_fma_f32 v84, v43, v84, v11
	v_fma_f32 v95, v43, v95, v18
	v_add_f32_e32 v88, -1.0, v69
	v_add_f32_e32 v170, -1.0, v71
	v_fma_f32 v88, v31, v88, 1.0
	v_fma_f32 v170, v31, v170, 1.0
	v_mul_f32_e32 v89, v88, v82
	v_mul_f32_e32 v171, v170, v93
	v_mul_f32_e32 v90, v83, v89
	v_mul_f32_e32 v172, v94, v171
	v_mul_f32_e32 v90, v35, v90
	v_mul_f32_e32 v172, v35, v172
	s_nop 0
	v_add_f32_dpp v90, v90, v90 quad_perm:[1,0,3,2] row_mask:0xf bank_mask:0xf bound_ctrl:1
	v_add_f32_dpp v172, v172, v172 quad_perm:[1,0,3,2] row_mask:0xf bank_mask:0xf bound_ctrl:1
	s_nop 0
	v_add_f32_dpp v90, v90, v90 quad_perm:[2,3,0,1] row_mask:0xf bank_mask:0xf bound_ctrl:1
	v_add_f32_dpp v172, v172, v172 quad_perm:[2,3,0,1] row_mask:0xf bank_mask:0xf bound_ctrl:1
	s_nop 0
	v_add_f32_dpp v90, v90, v90 row_half_mirror row_mask:0xf bank_mask:0xf bound_ctrl:1
	v_add_f32_dpp v172, v172, v172 row_half_mirror row_mask:0xf bank_mask:0xf bound_ctrl:1
	s_nop 0
	v_add_f32_dpp v90, v90, v90 row_mirror row_mask:0xf bank_mask:0xf bound_ctrl:1
	v_add_f32_dpp v172, v172, v172 row_mirror row_mask:0xf bank_mask:0xf bound_ctrl:1
	s_nop 0
	v_add_f32_dpp v90, v90, v90 row_bcast:15 row_mask:0xa bank_mask:0xf
	v_add_f32_dpp v172, v172, v172 row_bcast:15 row_mask:0xa bank_mask:0xf
	s_nop 0
	v_add_f32_dpp v90, v90, v90 row_bcast:31 row_mask:0xc bank_mask:0xf
	v_add_f32_dpp v172, v172, v172 row_bcast:31 row_mask:0xc bank_mask:0xf
	v_readlane_b32 s29, v90, 63
	v_readlane_b32 s31, v172, 63
	v_mov_b32_e32 v87, s24
	v_mov_b32_e32 v98, s25
	v_max_f32_e32 v87, 0x179abe15, v87
	v_max_f32_e32 v98, 0x179abe15, v98
	v_rsq_f32_e32 v87, v87
	v_rsq_f32_e32 v98, v98
	v_mul_f32_e32 v85, v85, v87
	v_mul_f32_e32 v96, v96, v98
	v_mul_f32_e32 v91, v69, v85
	v_mul_f32_e32 v173, v71, v96
	v_add_u32_e32 v92, v81, v59
	v_add_u32_e32 v174, v81, v60
	ds_write_b32 v92, v85
	ds_write_b32 v174, v96
	ds_write2st64_b32 v92, v70, v91 offset0:32 offset1:64
	ds_write2st64_b32 v174, v72, v173 offset0:32 offset1:64
	ds_write2st64_b32 v92, v89, v83 offset0:96 offset1:128
	ds_write2st64_b32 v174, v171, v94 offset0:96 offset1:128
	ds_write_b32 v92, v84 offset:40960
	ds_write_b32 v174, v95 offset:40960
	v_sub_f32_e32 v82, v16, v15
	v_sub_f32_e32 v93, v15, v22
	v_fma_f32 v82, v27, v82, v15
	v_fma_f32 v93, v27, v93, v22
	v_mul_f32_e32 v85, v29, v82
	v_mul_f32_e32 v96, v29, v93
	v_mul_f32_e32 v86, v85, v85
	v_mul_f32_e32 v97, v96, v96
	s_nop 0
	v_add_f32_dpp v86, v86, v86 quad_perm:[1,0,3,2] row_mask:0xf bank_mask:0xf bound_ctrl:1
	v_add_f32_dpp v97, v97, v97 quad_perm:[1,0,3,2] row_mask:0xf bank_mask:0xf bound_ctrl:1
	s_nop 0
	v_add_f32_dpp v86, v86, v86 quad_perm:[2,3,0,1] row_mask:0xf bank_mask:0xf bound_ctrl:1
	v_add_f32_dpp v97, v97, v97 quad_perm:[2,3,0,1] row_mask:0xf bank_mask:0xf bound_ctrl:1
	s_nop 0
	v_add_f32_dpp v86, v86, v86 row_half_mirror row_mask:0xf bank_mask:0xf bound_ctrl:1
	v_add_f32_dpp v97, v97, v97 row_half_mirror row_mask:0xf bank_mask:0xf bound_ctrl:1
	s_nop 0
	v_add_f32_dpp v86, v86, v86 row_mirror row_mask:0xf bank_mask:0xf bound_ctrl:1
	v_add_f32_dpp v97, v97, v97 row_mirror row_mask:0xf bank_mask:0xf bound_ctrl:1
	s_nop 0
	v_add_f32_dpp v86, v86, v86 row_bcast:15 row_mask:0xa bank_mask:0xf
	v_add_f32_dpp v97, v97, v97 row_bcast:15 row_mask:0xa bank_mask:0xf
	s_nop 0
	v_add_f32_dpp v86, v86, v86 row_bcast:31 row_mask:0xc bank_mask:0xf
	v_add_f32_dpp v97, v97, v97 row_bcast:31 row_mask:0xc bank_mask:0xf
	v_readlane_b32 s24, v86, 63
	v_readlane_b32 s25, v97, 63
	v_sub_f32_e32 v83, v14, v13
	v_sub_f32_e32 v94, v13, v20
	v_fma_f32 v83, v25, v83, v13
	v_fma_f32 v94, v25, v94, v20
	v_sub_f32_e32 v84, v18, v17
	v_sub_f32_e32 v95, v17, v24
	v_fma_f32 v84, v43, v84, v17
	v_fma_f32 v95, v43, v95, v24
	v_add_f32_e32 v88, -1.0, v73
	v_add_f32_e32 v170, -1.0, v75
	v_fma_f32 v88, v31, v88, 1.0
	v_fma_f32 v170, v31, v170, 1.0
	v_mul_f32_e32 v89, v88, v82
	v_mul_f32_e32 v171, v170, v93
	v_mul_f32_e32 v90, v83, v89
	v_mul_f32_e32 v172, v94, v171
	v_mul_f32_e32 v90, v35, v90
	v_mul_f32_e32 v172, v35, v172
	s_nop 0
	v_add_f32_dpp v90, v90, v90 quad_perm:[1,0,3,2] row_mask:0xf bank_mask:0xf bound_ctrl:1
	v_add_f32_dpp v172, v172, v172 quad_perm:[1,0,3,2] row_mask:0xf bank_mask:0xf bound_ctrl:1
	s_nop 0
	v_add_f32_dpp v90, v90, v90 quad_perm:[2,3,0,1] row_mask:0xf bank_mask:0xf bound_ctrl:1
	v_add_f32_dpp v172, v172, v172 quad_perm:[2,3,0,1] row_mask:0xf bank_mask:0xf bound_ctrl:1
	s_nop 0
	v_add_f32_dpp v90, v90, v90 row_half_mirror row_mask:0xf bank_mask:0xf bound_ctrl:1
	v_add_f32_dpp v172, v172, v172 row_half_mirror row_mask:0xf bank_mask:0xf bound_ctrl:1
	s_nop 0
	v_add_f32_dpp v90, v90, v90 row_mirror row_mask:0xf bank_mask:0xf bound_ctrl:1
	v_add_f32_dpp v172, v172, v172 row_mirror row_mask:0xf bank_mask:0xf bound_ctrl:1
	s_nop 0
	v_add_f32_dpp v90, v90, v90 row_bcast:15 row_mask:0xa bank_mask:0xf
	v_add_f32_dpp v172, v172, v172 row_bcast:15 row_mask:0xa bank_mask:0xf
	s_nop 0
	v_add_f32_dpp v90, v90, v90 row_bcast:31 row_mask:0xc bank_mask:0xf
	v_add_f32_dpp v172, v172, v172 row_bcast:31 row_mask:0xc bank_mask:0xf
	v_readlane_b32 s98, v90, 63
	v_readlane_b32 s99, v172, 63
	v_mov_b32_e32 v87, s24
	v_mov_b32_e32 v98, s25
	v_max_f32_e32 v87, 0x179abe15, v87
	v_max_f32_e32 v98, 0x179abe15, v98
	v_rsq_f32_e32 v87, v87
	v_rsq_f32_e32 v98, v98
	v_mul_f32_e32 v85, v85, v87
	v_mul_f32_e32 v96, v96, v98
	v_mul_f32_e32 v91, v73, v85
	v_mul_f32_e32 v173, v75, v96
	v_add_u32_e32 v92, v81, v61
	v_add_u32_e32 v174, v81, v62
	ds_write_b32 v92, v85
	ds_write_b32 v174, v96
	ds_write2st64_b32 v92, v74, v91 offset0:32 offset1:64
	ds_write2st64_b32 v174, v76, v173 offset0:32 offset1:64
	ds_write2st64_b32 v92, v89, v83 offset0:96 offset1:128
	ds_write2st64_b32 v174, v171, v94 offset0:96 offset1:128
	ds_write_b32 v92, v84 offset:40960
	ds_write_b32 v174, v95 offset:40960
	v_sub_f32_e32 v82, v22, v21
	v_sub_f32_e32 v93, v21, v28
	v_fma_f32 v82, v27, v82, v21
	v_fma_f32 v93, v27, v93, v28
	v_mul_f32_e32 v85, v29, v82
	v_mul_f32_e32 v96, v29, v93
	v_mul_f32_e32 v86, v85, v85
	v_mul_f32_e32 v97, v96, v96
	s_nop 0
	v_add_f32_dpp v86, v86, v86 quad_perm:[1,0,3,2] row_mask:0xf bank_mask:0xf bound_ctrl:1
	v_add_f32_dpp v97, v97, v97 quad_perm:[1,0,3,2] row_mask:0xf bank_mask:0xf bound_ctrl:1
	s_nop 0
	v_add_f32_dpp v86, v86, v86 quad_perm:[2,3,0,1] row_mask:0xf bank_mask:0xf bound_ctrl:1
	v_add_f32_dpp v97, v97, v97 quad_perm:[2,3,0,1] row_mask:0xf bank_mask:0xf bound_ctrl:1
	s_nop 0
	v_add_f32_dpp v86, v86, v86 row_half_mirror row_mask:0xf bank_mask:0xf bound_ctrl:1
	v_add_f32_dpp v97, v97, v97 row_half_mirror row_mask:0xf bank_mask:0xf bound_ctrl:1
	s_nop 0
	v_add_f32_dpp v86, v86, v86 row_mirror row_mask:0xf bank_mask:0xf bound_ctrl:1
	v_add_f32_dpp v97, v97, v97 row_mirror row_mask:0xf bank_mask:0xf bound_ctrl:1
	s_nop 0
	v_add_f32_dpp v86, v86, v86 row_bcast:15 row_mask:0xa bank_mask:0xf
	v_add_f32_dpp v97, v97, v97 row_bcast:15 row_mask:0xa bank_mask:0xf
	s_nop 0
	v_add_f32_dpp v86, v86, v86 row_bcast:31 row_mask:0xc bank_mask:0xf
	v_add_f32_dpp v97, v97, v97 row_bcast:31 row_mask:0xc bank_mask:0xf
	v_readlane_b32 s24, v86, 63
	v_readlane_b32 s25, v97, 63
	v_sub_f32_e32 v83, v20, v19
	v_sub_f32_e32 v94, v19, v30
	v_fma_f32 v83, v25, v83, v19
	v_fma_f32 v94, v25, v94, v30
	v_sub_f32_e32 v84, v24, v23
	v_sub_f32_e32 v95, v23, v26
	v_fma_f32 v84, v43, v84, v23
	v_fma_f32 v95, v43, v95, v26
	v_add_f32_e32 v88, -1.0, v77
	v_add_f32_e32 v170, -1.0, v79
	v_fma_f32 v88, v31, v88, 1.0
	v_fma_f32 v170, v31, v170, 1.0
	v_mul_f32_e32 v89, v88, v82
	v_mul_f32_e32 v171, v170, v93
	v_mul_f32_e32 v90, v83, v89
	v_mul_f32_e32 v172, v94, v171
	v_mul_f32_e32 v90, v35, v90
	v_mul_f32_e32 v172, v35, v172
	s_nop 0
	v_add_f32_dpp v90, v90, v90 quad_perm:[1,0,3,2] row_mask:0xf bank_mask:0xf bound_ctrl:1
	v_add_f32_dpp v172, v172, v172 quad_perm:[1,0,3,2] row_mask:0xf bank_mask:0xf bound_ctrl:1
	s_nop 0
	v_add_f32_dpp v90, v90, v90 quad_perm:[2,3,0,1] row_mask:0xf bank_mask:0xf bound_ctrl:1
	v_add_f32_dpp v172, v172, v172 quad_perm:[2,3,0,1] row_mask:0xf bank_mask:0xf bound_ctrl:1
	s_nop 0
	v_add_f32_dpp v90, v90, v90 row_half_mirror row_mask:0xf bank_mask:0xf bound_ctrl:1
	v_add_f32_dpp v172, v172, v172 row_half_mirror row_mask:0xf bank_mask:0xf bound_ctrl:1
	s_nop 0
	v_add_f32_dpp v90, v90, v90 row_mirror row_mask:0xf bank_mask:0xf bound_ctrl:1
	v_add_f32_dpp v172, v172, v172 row_mirror row_mask:0xf bank_mask:0xf bound_ctrl:1
	s_nop 0
	v_add_f32_dpp v90, v90, v90 row_bcast:15 row_mask:0xa bank_mask:0xf
	v_add_f32_dpp v172, v172, v172 row_bcast:15 row_mask:0xa bank_mask:0xf
	s_nop 0
	v_add_f32_dpp v90, v90, v90 row_bcast:31 row_mask:0xc bank_mask:0xf
	v_add_f32_dpp v172, v172, v172 row_bcast:31 row_mask:0xc bank_mask:0xf
	v_readlane_b32 s100, v90, 63
	v_readlane_b32 s101, v172, 63
	v_mov_b32_e32 v87, s24
	v_mov_b32_e32 v98, s25
	v_max_f32_e32 v87, 0x179abe15, v87
	v_max_f32_e32 v98, 0x179abe15, v98
	v_rsq_f32_e32 v87, v87
	v_rsq_f32_e32 v98, v98
	v_mul_f32_e32 v85, v85, v87
	v_mul_f32_e32 v96, v96, v98
	v_mul_f32_e32 v91, v77, v85
	v_mul_f32_e32 v173, v79, v96
	v_add_u32_e32 v92, v81, v63
	v_add_u32_e32 v174, v81, v64
	ds_write_b32 v92, v85
	ds_write_b32 v174, v96
	ds_write2st64_b32 v92, v78, v91 offset0:32 offset1:64
	ds_write2st64_b32 v174, v80, v173 offset0:32 offset1:64
	ds_write2st64_b32 v92, v89, v83 offset0:96 offset1:128
	ds_write2st64_b32 v174, v171, v94 offset0:96 offset1:128
	ds_write_b32 v92, v84 offset:40960
	ds_write_b32 v174, v95 offset:40960
	v_lshl_add_u64 v[52:53], s[34:35], 0, v[50:51]
	s_and_saveexec_b64 s[24:25], s[0:1]
	s_cbranch_execz .Lprod_nobonus
	v_mov_b32_e32 v82, s6
	global_store_dword v[52:53], v82, off offset:-256
	v_mov_b32_e32 v83, s7
	global_store_dword v[52:53], v83, off offset:-192
	v_mov_b32_e32 v84, s29
	global_store_dword v[52:53], v84, off offset:-128
	v_mov_b32_e32 v85, s31
	global_store_dword v[52:53], v85, off offset:-64
	v_mov_b32_e32 v86, s98
	global_store_dword v[52:53], v86, off
	v_mov_b32_e32 v87, s99
	global_store_dword v[52:53], v87, off offset:64
	v_mov_b32_e32 v88, s100
	global_store_dword v[52:53], v88, off offset:128
	v_mov_b32_e32 v89, s101
	global_store_dword v[52:53], v89, off offset:192
.Lprod_nobonus:
	s_or_b64 exec, exec, s[24:25]
.LBB0_1790:
	s_or_b64 exec, exec, s[24:25]
.LBB0_1792:
	s_cmp_lg_u32 s5, 0
	s_cselect_b64 s[6:7], -1, 0
